# removed leftover v_div_scale / vcc moves of the replaced epilogue divisions (dead results)
# speedup vs baseline: 1.0008x; 1.0008x over previous
; DI unsigned cvtpk(float lo, float hi) { f32x2_t v = {lo, hi}; bf16x2_t b = __builtin_convertvector(v, bf16x2_t); return __builtin_bit_cast(unsigned, b); }
;   DI void operator()(const f32x4 (&acc)[2][2][4][2], const pg8::Unit& u, int wr, int wc, int fr, int fq) const {
;     ...
;       for (int m = 0; m < 4; ++m) {
;         const int row = u.pm * 256 + ai * 128 + wr * 64 + m * 16 + fr; float rs = 0.f;
;         const float rstd = rsqrtf(ssx[row] * (1.f / DM) + EPS);
; #pragma unroll
;         for (int bj = 0; bj < 2; ++bj)
; #pragma unroll
;           for (int n = 0; n < 2; ++n) {
;             const int col = u.pn * 256 + bj * 128 + wc * 32 + n * 16 + fq * 4; const size_t off = (size_t)row * DM + col;
;             f32x4 g;
; #pragma unroll
;             for (int j = 0; j < 4; ++j) g[j] = 1.f / (1.f + __expf(-rstd * acc[ai][bj][m][n][j]));
;             const u32x2 pw = *(const u32x2*)(PT + off); f32x4 pp; pp.x = __uint_as_float(pw.x << 16); pp.y = __uint_as_float(pw.x & 0xffff0000u); pp.z = __uint_as_float(pw.y << 16); pp.w = __uint_as_float(pw.y & 0xffff0000u);
;             const u32x2 xw = *(const u32x2*)(X1B + off); f32x4 x1; x1.x = __uint_as_float(xw.x << 16); x1.y = __uint_as_float(xw.x & 0xffff0000u); x1.z = __uint_as_float(xw.y << 16); x1.w = __uint_as_float(xw.y & 0xffff0000u);
;             const f32x4 xn = x1 + pp * g;
;             if (layer != 0) *(f32x4*)(out + off) = xn;
;             if (layer == 0) {
;               rs += xn.x * xn.x + xn.y * xn.y + xn.z * xn.z + xn.w * xn.w;
;               u32x2 w; w.x = cvtpk(xn.x, xn.y); w.y = cvtpk(xn.z, xn.w); *(u32x2*)(H + off) = w;
;             }
;           }
;         if (layer == 0) { rs += __shfl_xor(rs, 16); rs += __shfl_xor(rs, 32); if (fq == 0) atomicAdd(ss1 + row, rs); }
.LBB0_2372:
	v_lshl_add_u32 v146, s0, 8, v152
	v_ashrrev_i32_e32 v147, 31, v146
	v_lshl_add_u64 v[142:143], v[146:147], 2, s[24:25]
	global_load_dword v159, v[142:143], off
	v_lshl_or_b32 v140, s2, 8, v154
	v_lshlrev_b64 v[148:149], 10, v[146:147]
	v_ashrrev_i32_e32 v141, 31, v140
	v_lshl_add_u64 v[142:143], v[148:149], 0, v[140:141]
	v_lshlrev_b64 v[160:161], 1, v[142:143]
	v_lshl_add_u64 v[150:151], s[16:17], 0, v[160:161]
	v_lshl_add_u64 v[142:143], s[18:19], 0, v[160:161]
	global_load_dwordx2 v[162:163], v[150:151], off
	global_load_dwordx2 v[170:171], v[150:151], off offset:32
	global_load_dwordx2 v[164:165], v[142:143], off
	v_or_b32_e32 v142, 16, v140
	v_ashrrev_i32_e32 v143, 31, v142
	v_lshl_add_u64 v[166:167], v[148:149], 0, v[142:143]
	v_lshlrev_b64 v[166:167], 1, v[166:167]
	v_lshl_add_u64 v[160:161], s[28:29], 0, v[160:161]
	v_lshl_add_u64 v[168:169], s[18:19], 0, v[166:167]
	v_or_b32_e32 v144, 0x80, v140
	v_ashrrev_i32_e32 v145, 31, v144
	v_lshl_add_u64 v[166:167], s[28:29], 0, v[166:167]
	s_waitcnt vmcnt(0)
	v_fmamk_f32 v159, v159, 0x3a800000, v158
	v_mul_f32_e32 v172, 0x4b800000, v159
	v_cmp_gt_f32_e32 vcc, s54, v159
	v_and_b32_e32 v173, 0xffff0000, v162
	s_nop 0
	v_cndmask_b32_e32 v159, v159, v172, vcc
	v_rsq_f32_e32 v159, v159
	v_lshlrev_b32_e32 v174, 16, v164
	v_and_b32_e32 v175, 0xffff0000, v164
	v_lshlrev_b32_e32 v172, 16, v162
	v_mul_f32_e32 v164, 0x45800000, v159
	v_cndmask_b32_e32 v159, v159, v164, vcc
	v_mul_f32_e64 v124, v124, -v159
	v_mul_f32_e64 v125, v125, -v159
	v_mul_f32_e32 v124, 0x3fb8aa3b, v124
	v_mul_f32_e32 v125, 0x3fb8aa3b, v125
	v_mul_f32_e64 v126, v126, -v159
	v_mul_f32_e64 v127, v127, -v159
	v_exp_f32_e32 v124, v124
	v_exp_f32_e32 v125, v125
	v_mul_f32_e32 v126, 0x3fb8aa3b, v126
	v_mul_f32_e32 v127, 0x3fb8aa3b, v127
	v_exp_f32_e32 v126, v126
	v_exp_f32_e32 v127, v127
	v_pk_add_f32 v[124:125], v[124:125], 1.0 op_sel_hi:[1,0]
	v_lshlrev_b32_e32 v162, 16, v163
	v_pk_add_f32 v[126:127], v[126:127], 1.0 op_sel_hi:[1,0]
	v_rcp_f32_e32 v125, v125
	v_rcp_f32_e32 v124, v124
	v_rcp_f32_e32 v127, v127
	v_and_b32_e32 v163, 0xffff0000, v163
	v_lshlrev_b32_e32 v164, 16, v165
	v_and_b32_e32 v165, 0xffff0000, v165
	v_rcp_f32_e32 v126, v126
	v_pk_fma_f32 v[124:125], v[124:125], v[172:173], v[174:175]
	v_pk_fma_f32 v[126:127], v[126:127], v[162:163], v[164:165]
	v_cvt_pk_bf16_f32 v172, v124, v125
	v_cvt_pk_bf16_f32 v173, v126, v127
	global_store_dwordx2 v[160:161], v[172:173], off
	global_load_dwordx2 v[160:161], v[168:169], off
	v_mul_f32_e64 v120, v120, -v159
	v_mul_f32_e64 v121, v121, -v159
	v_mul_f32_e64 v122, v122, -v159
	v_mul_f32_e64 v116, v116, -v159
	v_mul_f32_e64 v168, v117, -v159
	v_mul_f32_e32 v117, 0x3fb8aa3b, v120
	v_mul_f32_e32 v169, 0x3fb8aa3b, v121
	v_mul_f32_e64 v123, v123, -v159
	v_mul_f32_e32 v120, 0x3fb8aa3b, v122
	v_mul_f32_e32 v122, 0x3fb8aa3b, v116
	v_exp_f32_e32 v116, v117
	v_exp_f32_e32 v117, v169
	v_mul_f32_e32 v121, 0x3fb8aa3b, v123
	v_exp_f32_e32 v120, v120
	v_exp_f32_e32 v121, v121
	v_pk_add_f32 v[116:117], v[116:117], 1.0 op_sel_hi:[1,0]
	v_mul_f32_e32 v123, 0x3fb8aa3b, v168
	v_lshlrev_b32_e32 v162, 16, v170
	v_and_b32_e32 v163, 0xffff0000, v170
	v_pk_add_f32 v[120:121], v[120:121], 1.0 op_sel_hi:[1,0]
	v_lshlrev_b32_e32 v164, 16, v171
	v_and_b32_e32 v165, 0xffff0000, v171
	v_rcp_f32_e32 v117, v117
	v_rcp_f32_e32 v116, v116
	v_rcp_f32_e32 v121, v121
	v_rcp_f32_e32 v120, v120
	v_exp_f32_e32 v122, v122
	v_mul_f32_e64 v118, v118, -v159
	s_waitcnt vmcnt(0)
	v_lshlrev_b32_e32 v168, 16, v160
	v_and_b32_e32 v169, 0xffff0000, v160
	v_lshlrev_b32_e32 v160, 16, v161
	v_and_b32_e32 v161, 0xffff0000, v161
	v_pk_fma_f32 v[120:121], v[120:121], v[164:165], v[160:161]
	v_pk_fma_f32 v[116:117], v[116:117], v[162:163], v[168:169]
	v_lshl_add_u64 v[162:163], v[148:149], 0, v[144:145]
	v_cvt_pk_bf16_f32 v160, v116, v117
	v_cvt_pk_bf16_f32 v161, v120, v121
	v_lshlrev_b64 v[162:163], 1, v[162:163]
	global_store_dwordx2 v[166:167], v[160:161], off
	v_lshl_add_u64 v[164:165], s[18:19], 0, v[162:163]
	global_load_dwordx2 v[160:161], v[150:151], off offset:256
	v_mul_f32_e64 v119, v119, -v159
	global_load_dwordx2 v[164:165], v[164:165], off
	v_exp_f32_e32 v123, v123
	v_mul_f32_e32 v118, 0x3fb8aa3b, v118
	v_mul_f32_e32 v119, 0x3fb8aa3b, v119
	v_exp_f32_e32 v118, v118
	v_exp_f32_e32 v119, v119
	v_pk_add_f32 v[122:123], v[122:123], 1.0 op_sel_hi:[1,0]
	v_mul_f32_e32 v125, v125, v125
	v_pk_add_f32 v[118:119], v[118:119], 1.0 op_sel_hi:[1,0]
	v_fmac_f32_e32 v125, v124, v124
	v_mul_f32_e32 v117, v117, v117
	v_rcp_f32_e32 v123, v123
	v_fmac_f32_e32 v117, v116, v116
	v_fmac_f32_e32 v125, v126, v126
	v_rcp_f32_e32 v122, v122
	v_fmac_f32_e32 v117, v120, v120
	v_fmac_f32_e32 v125, v127, v127
	v_rcp_f32_e32 v119, v119
	v_fmac_f32_e32 v117, v121, v121
	v_rcp_f32_e32 v118, v118
	v_add_f32_e32 v166, v125, v117
	v_mul_f32_e64 v112, v112, -v159
	v_mul_f32_e64 v113, v113, -v159
	v_mul_f32_e32 v112, 0x3fb8aa3b, v112
	v_mul_f32_e32 v113, 0x3fb8aa3b, v113
	v_exp_f32_e32 v112, v112
	v_exp_f32_e32 v113, v113
	s_waitcnt vmcnt(1)
	v_lshlrev_b32_e32 v116, 16, v160
	v_and_b32_e32 v117, 0xffff0000, v160
	v_lshlrev_b32_e32 v120, 16, v161
	v_and_b32_e32 v121, 0xffff0000, v161
	s_waitcnt vmcnt(0)
; DI unsigned cvtpk(float lo, float hi) { f32x2_t v = {lo, hi}; bf16x2_t b = __builtin_convertvector(v, bf16x2_t); return __builtin_bit_cast(unsigned, b); }
;   DI void operator()(const f32x4 (&acc)[2][2][4][2], const pg8::Unit& u, int wr, int wc, int fr, int fq) const {
;     ...
;       for (int m = 0; m < 4; ++m) {
;         const int row = u.pm * 256 + ai * 128 + wr * 64 + m * 16 + fr; float rs = 0.f;
;         const float rstd = rsqrtf(ssx[row] * (1.f / DM) + EPS);
; #pragma unroll
;         for (int bj = 0; bj < 2; ++bj)
; #pragma unroll
;           for (int n = 0; n < 2; ++n) {
;             const int col = u.pn * 256 + bj * 128 + wc * 32 + n * 16 + fq * 4; const size_t off = (size_t)row * DM + col;
;             f32x4 g;
; #pragma unroll
;             for (int j = 0; j < 4; ++j) g[j] = 1.f / (1.f + __expf(-rstd * acc[ai][bj][m][n][j]));
;             const u32x2 pw = *(const u32x2*)(PT + off); f32x4 pp; pp.x = __uint_as_float(pw.x << 16); pp.y = __uint_as_float(pw.x & 0xffff0000u); pp.z = __uint_as_float(pw.y << 16); pp.w = __uint_as_float(pw.y & 0xffff0000u);
;             const u32x2 xw = *(const u32x2*)(X1B + off); f32x4 x1; x1.x = __uint_as_float(xw.x << 16); x1.y = __uint_as_float(xw.x & 0xffff0000u); x1.z = __uint_as_float(xw.y << 16); x1.w = __uint_as_float(xw.y & 0xffff0000u);
;             const f32x4 xn = x1 + pp * g;
;             if (layer != 0) *(f32x4*)(out + off) = xn;
;             if (layer == 0) {
;               rs += xn.x * xn.x + xn.y * xn.y + xn.z * xn.z + xn.w * xn.w;
;               u32x2 w; w.x = cvtpk(xn.x, xn.y); w.y = cvtpk(xn.z, xn.w); *(u32x2*)(H + off) = w;
;             }
;           }
;         if (layer == 0) { rs += __shfl_xor(rs, 16); rs += __shfl_xor(rs, 32); if (fq == 0) atomicAdd(ss1 + row, rs); }
	v_lshlrev_b32_e32 v124, 16, v164
	v_and_b32_e32 v125, 0xffff0000, v164
	v_lshlrev_b32_e32 v126, 16, v165
	v_and_b32_e32 v127, 0xffff0000, v165
	v_pk_fma_f32 v[118:119], v[118:119], v[120:121], v[126:127]
	v_pk_fma_f32 v[120:121], v[122:123], v[116:117], v[124:125]
	v_cvt_pk_bf16_f32 v117, v118, v119
	v_cvt_pk_bf16_f32 v116, v120, v121
	v_lshl_add_u64 v[122:123], s[28:29], 0, v[162:163]
	global_store_dwordx2 v[122:123], v[116:117], off
	v_or_b32_e32 v116, 0x90, v140
	v_ashrrev_i32_e32 v117, 31, v116
	v_lshl_add_u64 v[124:125], v[148:149], 0, v[116:117]
	v_lshlrev_b64 v[126:127], 1, v[124:125]
	v_lshl_add_u64 v[124:125], s[18:19], 0, v[126:127]
	global_load_dwordx2 v[122:123], v[150:151], off offset:288
	v_mul_f32_e32 v121, v121, v121
	global_load_dwordx2 v[124:125], v[124:125], off
	v_fmac_f32_e32 v121, v120, v120
	v_pk_add_f32 v[112:113], v[112:113], 1.0 op_sel_hi:[1,0]
	v_fmac_f32_e32 v121, v118, v118
	v_fmac_f32_e32 v121, v119, v119
	v_add_f32_e32 v148, v121, v166
	v_mul_f32_e64 v114, v114, -v159
	v_mul_f32_e64 v115, v115, -v159
	v_mul_f32_e32 v114, 0x3fb8aa3b, v114
	v_mul_f32_e32 v115, 0x3fb8aa3b, v115
	v_exp_f32_e32 v114, v114
	v_exp_f32_e32 v115, v115
	v_rcp_f32_e32 v113, v113
	v_pk_add_f32 v[114:115], v[114:115], 1.0 op_sel_hi:[1,0]
	v_rcp_f32_e32 v112, v112
	v_rcp_f32_e32 v115, v115
	v_rcp_f32_e32 v114, v114
	s_waitcnt vmcnt(1)
	v_lshlrev_b32_e32 v118, 16, v122
	v_and_b32_e32 v119, 0xffff0000, v122
	v_lshlrev_b32_e32 v120, 16, v123
	v_and_b32_e32 v121, 0xffff0000, v123
	s_waitcnt vmcnt(0)
	v_lshlrev_b32_e32 v122, 16, v124
	v_and_b32_e32 v123, 0xffff0000, v124
	v_lshlrev_b32_e32 v124, 16, v125
	v_and_b32_e32 v125, 0xffff0000, v125
	v_pk_fma_f32 v[118:119], v[112:113], v[118:119], v[122:123]
	v_pk_fma_f32 v[114:115], v[114:115], v[120:121], v[124:125]
	v_mul_f32_e32 v112, v119, v119
	v_and_b32_e32 v120, 64, v183
	v_fmac_f32_e32 v112, v118, v118
	v_xor_b32_e32 v113, 16, v183
	v_add_u32_e32 v120, 64, v120
	v_fmac_f32_e32 v112, v114, v114
	v_cmp_lt_i32_e32 vcc, v113, v120
	v_fmac_f32_e32 v112, v115, v115
	v_add_f32_e32 v112, v148, v112
	v_cndmask_b32_e32 v113, v183, v113, vcc
	v_lshlrev_b32_e32 v124, 2, v113
	ds_bpermute_b32 v113, v124, v112
	v_cvt_pk_bf16_f32 v118, v118, v119
	v_cvt_pk_bf16_f32 v119, v114, v115
	v_lshl_add_u64 v[114:115], s[28:29], 0, v[126:127]
	global_store_dwordx2 v[114:115], v[118:119], off
	s_waitcnt lgkmcnt(0)
	v_add_f32_e32 v112, v112, v113
	v_xor_b32_e32 v113, 32, v183
	v_cmp_lt_i32_e32 vcc, v113, v120
	s_nop 1
	v_cndmask_b32_e32 v113, v183, v113, vcc
	v_lshlrev_b32_e32 v125, 2, v113
	ds_bpermute_b32 v113, v125, v112
	s_and_saveexec_b64 s[0:1], s[6:7]
	s_cbranch_execz .LBB0_2374
	s_waitcnt lgkmcnt(0)
	v_add_f32_e32 v114, v112, v113
	v_lshl_add_u64 v[112:113], v[146:147], 2, s[22:23]
	global_atomic_add_f32 v[112:113], v114, off
.LBB0_2374:
	s_or_b64 exec, exec, s[0:1]
	v_or_b32_e32 v112, 16, v146
	s_waitcnt lgkmcnt(0)
	v_ashrrev_i32_e32 v113, 31, v112
	v_lshl_add_u64 v[114:115], v[112:113], 2, s[24:25]
	global_load_dword v147, v[114:115], off
	v_lshlrev_b64 v[114:115], 10, v[112:113]
	v_lshl_add_u64 v[118:119], v[114:115], 0, v[140:141]
	v_lshlrev_b64 v[126:127], 1, v[118:119]
	v_lshl_add_u64 v[120:121], s[18:19], 0, v[126:127]
	global_load_dwordx2 v[122:123], v[120:121], off
	v_lshl_add_u64 v[118:119], s[16:17], 0, v[126:127]
	global_load_dwordx2 v[148:149], v[118:119], off
	global_load_dwordx2 v[162:163], v[118:119], off offset:32
	v_lshl_add_u64 v[120:121], v[114:115], 0, v[142:143]
	v_lshl_add_u64 v[150:151], v[114:115], 0, v[144:145]
	v_lshlrev_b64 v[160:161], 1, v[120:121]
	v_lshl_add_u64 v[126:127], s[28:29], 0, v[126:127]
	v_lshlrev_b64 v[120:121], 1, v[150:151]
	v_lshl_add_u64 v[150:151], s[18:19], 0, v[160:161]
	s_waitcnt vmcnt(3)
	v_fmamk_f32 v147, v147, 0x3a800000, v158
	v_mul_f32_e32 v159, 0x4b800000, v147
	v_cmp_gt_f32_e32 vcc, s54, v147
	s_waitcnt vmcnt(2)
	v_lshlrev_b32_e32 v166, 16, v122
	v_cndmask_b32_e32 v147, v147, v159, vcc
	v_rsq_f32_e32 v147, v147
	v_and_b32_e32 v167, 0xffff0000, v122
	s_waitcnt vmcnt(1)
	v_lshlrev_b32_e32 v164, 16, v148
	v_and_b32_e32 v165, 0xffff0000, v148
	v_mul_f32_e32 v122, 0x45800000, v147
	v_cndmask_b32_e32 v147, v147, v122, vcc
	v_mul_f32_e64 v108, v108, -v147
	v_mul_f32_e64 v109, v109, -v147
	v_mul_f32_e32 v108, 0x3fb8aa3b, v108
	v_mul_f32_e32 v109, 0x3fb8aa3b, v109
	v_mul_f32_e64 v110, v110, -v147
	v_mul_f32_e64 v111, v111, -v147
	v_exp_f32_e32 v108, v108
	v_exp_f32_e32 v109, v109
	v_mul_f32_e32 v110, 0x3fb8aa3b, v110
	v_mul_f32_e32 v111, 0x3fb8aa3b, v111
	v_exp_f32_e32 v110, v110
	v_exp_f32_e32 v111, v111
	v_pk_add_f32 v[108:109], v[108:109], 1.0 op_sel_hi:[1,0]
	v_lshlrev_b32_e32 v148, 16, v149
	v_pk_add_f32 v[110:111], v[110:111], 1.0 op_sel_hi:[1,0]
	v_rcp_f32_e32 v109, v109
	v_rcp_f32_e32 v108, v108
	v_rcp_f32_e32 v111, v111
	v_and_b32_e32 v149, 0xffff0000, v149
	v_lshlrev_b32_e32 v122, 16, v123
	v_and_b32_e32 v123, 0xffff0000, v123
	v_rcp_f32_e32 v110, v110
	v_pk_fma_f32 v[108:109], v[108:109], v[164:165], v[166:167]
	v_pk_fma_f32 v[110:111], v[110:111], v[148:149], v[122:123]
	v_cvt_pk_bf16_f32 v164, v108, v109
	v_cvt_pk_bf16_f32 v165, v110, v111
	global_store_dwordx2 v[126:127], v[164:165], off
	global_load_dwordx2 v[122:123], v[150:151], off
	v_mul_f32_e64 v104, v104, -v147
	v_mul_f32_e64 v105, v105, -v147
	v_mul_f32_e64 v159, v100, -v147
	v_mul_f32_e32 v100, 0x3fb8aa3b, v104
	v_mul_f32_e32 v105, 0x3fb8aa3b, v105
	v_mul_f32_e64 v106, v106, -v147
	v_mul_f32_e64 v107, v107, -v147
	v_exp_f32_e32 v104, v100
	v_exp_f32_e32 v105, v105
	v_mul_f32_e32 v106, 0x3fb8aa3b, v106
	v_mul_f32_e32 v107, 0x3fb8aa3b, v107
	v_exp_f32_e32 v106, v106
	v_exp_f32_e32 v107, v107
	v_pk_add_f32 v[104:105], v[104:105], 1.0 op_sel_hi:[1,0]
	v_lshl_add_u64 v[126:127], s[28:29], 0, v[160:161]
	s_waitcnt vmcnt(2)
; DI unsigned cvtpk(float lo, float hi) { f32x2_t v = {lo, hi}; bf16x2_t b = __builtin_convertvector(v, bf16x2_t); return __builtin_bit_cast(unsigned, b); }
;   DI void operator()(const f32x4 (&acc)[2][2][4][2], const pg8::Unit& u, int wr, int wc, int fr, int fq) const {
;     ...
;       for (int m = 0; m < 4; ++m) {
;         const int row = u.pm * 256 + ai * 128 + wr * 64 + m * 16 + fr; float rs = 0.f;
;         const float rstd = rsqrtf(ssx[row] * (1.f / DM) + EPS);
; #pragma unroll
;         for (int bj = 0; bj < 2; ++bj)
; #pragma unroll
;           for (int n = 0; n < 2; ++n) {
;             const int col = u.pn * 256 + bj * 128 + wc * 32 + n * 16 + fq * 4; const size_t off = (size_t)row * DM + col;
;             f32x4 g;
; #pragma unroll
;             for (int j = 0; j < 4; ++j) g[j] = 1.f / (1.f + __expf(-rstd * acc[ai][bj][m][n][j]));
;             const u32x2 pw = *(const u32x2*)(PT + off); f32x4 pp; pp.x = __uint_as_float(pw.x << 16); pp.y = __uint_as_float(pw.x & 0xffff0000u); pp.z = __uint_as_float(pw.y << 16); pp.w = __uint_as_float(pw.y & 0xffff0000u);
;             const u32x2 xw = *(const u32x2*)(X1B + off); f32x4 x1; x1.x = __uint_as_float(xw.x << 16); x1.y = __uint_as_float(xw.x & 0xffff0000u); x1.z = __uint_as_float(xw.y << 16); x1.w = __uint_as_float(xw.y & 0xffff0000u);
;             const f32x4 xn = x1 + pp * g;
;             if (layer != 0) *(f32x4*)(out + off) = xn;
;             if (layer == 0) {
;               rs += xn.x * xn.x + xn.y * xn.y + xn.z * xn.z + xn.w * xn.w;
;               u32x2 w; w.x = cvtpk(xn.x, xn.y); w.y = cvtpk(xn.z, xn.w); *(u32x2*)(H + off) = w;
;             }
;           }
;         if (layer == 0) { rs += __shfl_xor(rs, 16); rs += __shfl_xor(rs, 32); if (fq == 0) atomicAdd(ss1 + row, rs); }
	v_lshlrev_b32_e32 v160, 16, v163
	v_and_b32_e32 v161, 0xffff0000, v163
	v_mul_f32_e64 v163, v102, -v147
	v_lshlrev_b32_e32 v150, 16, v162
	v_and_b32_e32 v151, 0xffff0000, v162
	v_mul_f32_e64 v162, v101, -v147
	v_pk_add_f32 v[100:101], v[106:107], 1.0 op_sel_hi:[1,0]
	v_rcp_f32_e32 v105, v105
	v_rcp_f32_e32 v104, v104
	v_rcp_f32_e32 v101, v101
	v_rcp_f32_e32 v100, v100
	v_lshl_add_u64 v[148:149], s[18:19], 0, v[120:121]
	v_mul_f32_e64 v96, v96, -v147
	s_waitcnt vmcnt(0)
	v_lshlrev_b32_e32 v106, 16, v122
	v_and_b32_e32 v107, 0xffff0000, v122
	v_lshlrev_b32_e32 v122, 16, v123
	v_and_b32_e32 v123, 0xffff0000, v123
	v_pk_fma_f32 v[100:101], v[100:101], v[160:161], v[122:123]
	v_pk_fma_f32 v[104:105], v[104:105], v[150:151], v[106:107]
	v_cvt_pk_bf16_f32 v107, v100, v101
	v_cvt_pk_bf16_f32 v106, v104, v105
	global_store_dwordx2 v[126:127], v[106:107], off
	global_load_dwordx2 v[106:107], v[118:119], off offset:256
	v_mul_f32_e64 v122, v103, -v147
	global_load_dwordx2 v[102:103], v[148:149], off
	v_mul_f32_e32 v123, 0x3fb8aa3b, v159
	v_mul_f32_e32 v150, 0x3fb8aa3b, v162
	v_mul_f32_e32 v126, 0x3fb8aa3b, v163
	v_mul_f32_e32 v127, 0x3fb8aa3b, v122
	v_exp_f32_e32 v122, v123
	v_exp_f32_e32 v126, v126
	v_exp_f32_e32 v127, v127
	v_exp_f32_e32 v123, v150
	v_mul_f32_e32 v105, v105, v105
	v_fmac_f32_e32 v105, v104, v104
	v_pk_add_f32 v[126:127], v[126:127], 1.0 op_sel_hi:[1,0]
	v_pk_add_f32 v[122:123], v[122:123], 1.0 op_sel_hi:[1,0]
	v_mul_f32_e32 v159, v109, v109
	v_fmac_f32_e32 v159, v108, v108
	v_rcp_f32_e32 v109, v123
	v_fmac_f32_e32 v159, v110, v110
	v_fmac_f32_e32 v105, v100, v100
	v_fmac_f32_e32 v159, v111, v111
	v_rcp_f32_e32 v111, v127
	v_fmac_f32_e32 v105, v101, v101
	v_rcp_f32_e32 v108, v122
	v_rcp_f32_e32 v110, v126
	v_add_f32_e32 v122, v159, v105
	v_mul_f32_e64 v97, v97, -v147
	v_mul_f32_e32 v96, 0x3fb8aa3b, v96
	v_mul_f32_e32 v97, 0x3fb8aa3b, v97
	s_waitcnt vmcnt(1)
	v_lshlrev_b32_e32 v100, 16, v106
	v_and_b32_e32 v101, 0xffff0000, v106
	v_lshlrev_b32_e32 v104, 16, v107
	v_and_b32_e32 v105, 0xffff0000, v107
	s_waitcnt vmcnt(0)
	v_lshlrev_b32_e32 v106, 16, v102
	v_and_b32_e32 v107, 0xffff0000, v102
	v_lshlrev_b32_e32 v102, 16, v103
	v_and_b32_e32 v103, 0xffff0000, v103
	v_pk_fma_f32 v[102:103], v[110:111], v[104:105], v[102:103]
	v_pk_fma_f32 v[100:101], v[108:109], v[100:101], v[106:107]
	v_cvt_pk_bf16_f32 v105, v102, v103
	v_cvt_pk_bf16_f32 v104, v100, v101
	v_lshl_add_u64 v[106:107], s[28:29], 0, v[120:121]
	global_store_dwordx2 v[106:107], v[104:105], off
	v_lshl_add_u64 v[106:107], v[114:115], 0, v[116:117]
	v_lshlrev_b64 v[106:107], 1, v[106:107]
	v_lshl_add_u64 v[108:109], s[18:19], 0, v[106:107]
	global_load_dwordx2 v[104:105], v[118:119], off offset:288
	v_exp_f32_e32 v96, v96
	global_load_dwordx2 v[108:109], v[108:109], off
	v_exp_f32_e32 v97, v97
	v_mul_f32_e32 v101, v101, v101
	v_fmac_f32_e32 v101, v100, v100
	v_fmac_f32_e32 v101, v102, v102
	v_pk_add_f32 v[96:97], v[96:97], 1.0 op_sel_hi:[1,0]
	v_fmac_f32_e32 v101, v103, v103
	v_add_f32_e32 v110, v101, v122
	v_mul_f32_e64 v98, v98, -v147
	v_mul_f32_e64 v99, v99, -v147
	v_mul_f32_e32 v98, 0x3fb8aa3b, v98
	v_mul_f32_e32 v99, 0x3fb8aa3b, v99
	v_exp_f32_e32 v98, v98
	v_exp_f32_e32 v99, v99
	v_rcp_f32_e32 v97, v97
	v_pk_add_f32 v[98:99], v[98:99], 1.0 op_sel_hi:[1,0]
	v_rcp_f32_e32 v96, v96
	v_rcp_f32_e32 v99, v99
	v_rcp_f32_e32 v98, v98
	s_waitcnt vmcnt(1)
	v_lshlrev_b32_e32 v100, 16, v104
	v_and_b32_e32 v101, 0xffff0000, v104
	v_lshlrev_b32_e32 v102, 16, v105
	v_and_b32_e32 v103, 0xffff0000, v105
	s_waitcnt vmcnt(0)
	v_lshlrev_b32_e32 v104, 16, v108
	v_and_b32_e32 v105, 0xffff0000, v108
	v_pk_fma_f32 v[100:101], v[96:97], v[100:101], v[104:105]
	v_lshlrev_b32_e32 v108, 16, v109
	v_and_b32_e32 v109, 0xffff0000, v109
	v_mul_f32_e32 v96, v101, v101
	v_pk_fma_f32 v[98:99], v[98:99], v[102:103], v[108:109]
	v_fmac_f32_e32 v96, v100, v100
	v_fmac_f32_e32 v96, v98, v98
	v_fmac_f32_e32 v96, v99, v99
	v_add_f32_e32 v96, v110, v96
	ds_bpermute_b32 v97, v124, v96
	v_cvt_pk_bf16_f32 v100, v100, v101
	v_cvt_pk_bf16_f32 v101, v98, v99
	v_lshl_add_u64 v[98:99], s[28:29], 0, v[106:107]
	global_store_dwordx2 v[98:99], v[100:101], off
	s_waitcnt lgkmcnt(0)
	v_add_f32_e32 v96, v96, v97
	ds_bpermute_b32 v97, v125, v96
	s_and_saveexec_b64 s[0:1], s[6:7]
	s_cbranch_execz .LBB0_2376
	s_waitcnt lgkmcnt(0)
	v_add_f32_e32 v98, v96, v97
	v_lshl_add_u64 v[96:97], v[112:113], 2, s[22:23]
	global_atomic_add_f32 v[96:97], v98, off
; DI unsigned cvtpk(float lo, float hi) { f32x2_t v = {lo, hi}; bf16x2_t b = __builtin_convertvector(v, bf16x2_t); return __builtin_bit_cast(unsigned, b); }
;   DI void operator()(const f32x4 (&acc)[2][2][4][2], const pg8::Unit& u, int wr, int wc, int fr, int fq) const {
;     ...
;       for (int m = 0; m < 4; ++m) {
;         const int row = u.pm * 256 + ai * 128 + wr * 64 + m * 16 + fr; float rs = 0.f;
;         const float rstd = rsqrtf(ssx[row] * (1.f / DM) + EPS);
; #pragma unroll
;         for (int bj = 0; bj < 2; ++bj)
; #pragma unroll
;           for (int n = 0; n < 2; ++n) {
;             const int col = u.pn * 256 + bj * 128 + wc * 32 + n * 16 + fq * 4; const size_t off = (size_t)row * DM + col;
;             f32x4 g;
; #pragma unroll
;             for (int j = 0; j < 4; ++j) g[j] = 1.f / (1.f + __expf(-rstd * acc[ai][bj][m][n][j]));
;             const u32x2 pw = *(const u32x2*)(PT + off); f32x4 pp; pp.x = __uint_as_float(pw.x << 16); pp.y = __uint_as_float(pw.x & 0xffff0000u); pp.z = __uint_as_float(pw.y << 16); pp.w = __uint_as_float(pw.y & 0xffff0000u);
;             const u32x2 xw = *(const u32x2*)(X1B + off); f32x4 x1; x1.x = __uint_as_float(xw.x << 16); x1.y = __uint_as_float(xw.x & 0xffff0000u); x1.z = __uint_as_float(xw.y << 16); x1.w = __uint_as_float(xw.y & 0xffff0000u);
;             const f32x4 xn = x1 + pp * g;
;             if (layer != 0) *(f32x4*)(out + off) = xn;
;             if (layer == 0) {
;               rs += xn.x * xn.x + xn.y * xn.y + xn.z * xn.z + xn.w * xn.w;
;               u32x2 w; w.x = cvtpk(xn.x, xn.y); w.y = cvtpk(xn.z, xn.w); *(u32x2*)(H + off) = w;
;             }
;           }
;         if (layer == 0) { rs += __shfl_xor(rs, 16); rs += __shfl_xor(rs, 32); if (fq == 0) atomicAdd(ss1 + row, rs); }
.LBB0_2376:
	s_or_b64 exec, exec, s[0:1]
	v_or_b32_e32 v96, 32, v146
	s_waitcnt lgkmcnt(0)
	v_ashrrev_i32_e32 v97, 31, v96
	v_lshl_add_u64 v[98:99], v[96:97], 2, s[24:25]
	global_load_dword v118, v[98:99], off
	v_lshlrev_b64 v[98:99], 10, v[96:97]
	v_lshl_add_u64 v[100:101], v[98:99], 0, v[140:141]
	v_lshlrev_b64 v[106:107], 1, v[100:101]
	v_lshl_add_u64 v[102:103], s[18:19], 0, v[106:107]
	global_load_dwordx2 v[104:105], v[102:103], off
	v_lshl_add_u64 v[100:101], s[16:17], 0, v[106:107]
	global_load_dwordx2 v[108:109], v[100:101], off
	global_load_dwordx2 v[114:115], v[100:101], off offset:32
	v_lshl_add_u64 v[102:103], v[98:99], 0, v[142:143]
	v_lshl_add_u64 v[110:111], v[98:99], 0, v[144:145]
	v_lshlrev_b64 v[112:113], 1, v[102:103]
	v_lshl_add_u64 v[106:107], s[28:29], 0, v[106:107]
	v_lshlrev_b64 v[102:103], 1, v[110:111]
	v_lshl_add_u64 v[110:111], s[18:19], 0, v[112:113]
	s_waitcnt vmcnt(3)
	v_fmamk_f32 v118, v118, 0x3a800000, v158
	v_mul_f32_e32 v119, 0x4b800000, v118
	v_cmp_gt_f32_e32 vcc, s54, v118
	s_waitcnt vmcnt(2)
	v_lshlrev_b32_e32 v120, 16, v104
	v_cndmask_b32_e32 v118, v118, v119, vcc
	v_rsq_f32_e32 v122, v118
	v_and_b32_e32 v121, 0xffff0000, v104
	s_waitcnt vmcnt(1)
	v_lshlrev_b32_e32 v118, 16, v108
	v_and_b32_e32 v119, 0xffff0000, v108
	v_mul_f32_e32 v104, 0x45800000, v122
	v_cndmask_b32_e32 v122, v122, v104, vcc
	v_mul_f32_e64 v92, v92, -v122
	v_mul_f32_e64 v93, v93, -v122
	v_mul_f32_e32 v92, 0x3fb8aa3b, v92
	v_mul_f32_e32 v93, 0x3fb8aa3b, v93
	v_mul_f32_e64 v94, v94, -v122
	v_mul_f32_e64 v95, v95, -v122
	v_exp_f32_e32 v92, v92
	v_exp_f32_e32 v93, v93
	v_mul_f32_e32 v94, 0x3fb8aa3b, v94
	v_mul_f32_e32 v95, 0x3fb8aa3b, v95
	v_exp_f32_e32 v94, v94
	v_exp_f32_e32 v95, v95
	v_pk_add_f32 v[92:93], v[92:93], 1.0 op_sel_hi:[1,0]
	v_lshlrev_b32_e32 v108, 16, v109
	v_pk_add_f32 v[94:95], v[94:95], 1.0 op_sel_hi:[1,0]
	v_rcp_f32_e32 v93, v93
	v_rcp_f32_e32 v92, v92
	v_rcp_f32_e32 v95, v95
	v_and_b32_e32 v109, 0xffff0000, v109
	v_lshlrev_b32_e32 v104, 16, v105
	v_and_b32_e32 v105, 0xffff0000, v105
	v_rcp_f32_e32 v94, v94
	v_pk_fma_f32 v[92:93], v[92:93], v[118:119], v[120:121]
	v_pk_fma_f32 v[94:95], v[94:95], v[108:109], v[104:105]
	v_cvt_pk_bf16_f32 v118, v92, v93
	v_cvt_pk_bf16_f32 v119, v94, v95
	global_store_dwordx2 v[106:107], v[118:119], off
	global_load_dwordx2 v[104:105], v[110:111], off
	v_mul_f32_e64 v88, v88, -v122
	v_mul_f32_e64 v89, v89, -v122
	s_waitcnt vmcnt(2)
	v_lshlrev_b32_e32 v110, 16, v114
	v_and_b32_e32 v111, 0xffff0000, v114
	v_mul_f32_e64 v114, v84, -v122
	v_mul_f32_e32 v84, 0x3fb8aa3b, v88
	v_mul_f32_e32 v89, 0x3fb8aa3b, v89
	v_mul_f32_e64 v90, v90, -v122
	v_mul_f32_e64 v91, v91, -v122
	v_exp_f32_e32 v88, v84
	v_exp_f32_e32 v89, v89
	v_mul_f32_e32 v90, 0x3fb8aa3b, v90
	v_mul_f32_e32 v91, 0x3fb8aa3b, v91
	v_exp_f32_e32 v90, v90
	v_exp_f32_e32 v91, v91
	v_pk_add_f32 v[88:89], v[88:89], 1.0 op_sel_hi:[1,0]
	v_mul_f32_e64 v118, v86, -v122
	v_lshl_add_u64 v[106:107], s[28:29], 0, v[112:113]
	v_lshlrev_b32_e32 v112, 16, v115
	v_and_b32_e32 v113, 0xffff0000, v115
	v_mul_f32_e64 v115, v85, -v122
	v_pk_add_f32 v[84:85], v[90:91], 1.0 op_sel_hi:[1,0]
	v_rcp_f32_e32 v89, v89
	v_rcp_f32_e32 v88, v88
	v_rcp_f32_e32 v85, v85
	v_rcp_f32_e32 v84, v84
	v_lshl_add_u64 v[108:109], s[18:19], 0, v[102:103]
	v_mul_f32_e64 v80, v80, -v122
	s_waitcnt vmcnt(0)
	v_lshlrev_b32_e32 v90, 16, v104
	v_and_b32_e32 v91, 0xffff0000, v104
	v_lshlrev_b32_e32 v104, 16, v105
	v_and_b32_e32 v105, 0xffff0000, v105
	v_pk_fma_f32 v[84:85], v[84:85], v[112:113], v[104:105]
	v_pk_fma_f32 v[88:89], v[88:89], v[110:111], v[90:91]
	v_cvt_pk_bf16_f32 v91, v84, v85
	v_cvt_pk_bf16_f32 v90, v88, v89
	global_store_dwordx2 v[106:107], v[90:91], off
	global_load_dwordx2 v[90:91], v[100:101], off offset:256
	v_mul_f32_e64 v104, v87, -v122
	global_load_dwordx2 v[86:87], v[108:109], off
	v_mul_f32_e32 v105, 0x3fb8aa3b, v114
	v_mul_f32_e32 v110, 0x3fb8aa3b, v115
	v_mul_f32_e32 v106, 0x3fb8aa3b, v118
	v_mul_f32_e32 v107, 0x3fb8aa3b, v104
	v_exp_f32_e32 v104, v105
	v_exp_f32_e32 v106, v106
	v_exp_f32_e32 v107, v107
	v_exp_f32_e32 v105, v110
	v_mul_f32_e32 v89, v89, v89
	v_fmac_f32_e32 v89, v88, v88
	v_pk_add_f32 v[106:107], v[106:107], 1.0 op_sel_hi:[1,0]
	v_pk_add_f32 v[104:105], v[104:105], 1.0 op_sel_hi:[1,0]
	v_mul_f32_e32 v112, v93, v93
	v_fmac_f32_e32 v112, v92, v92
	v_rcp_f32_e32 v93, v105
	v_fmac_f32_e32 v112, v94, v94
	v_fmac_f32_e32 v89, v84, v84
	v_fmac_f32_e32 v112, v95, v95
	v_rcp_f32_e32 v95, v107
	v_fmac_f32_e32 v89, v85, v85
	v_rcp_f32_e32 v92, v104
	v_rcp_f32_e32 v94, v106
	v_add_f32_e32 v104, v112, v89
	v_mul_f32_e64 v81, v81, -v122
	v_mul_f32_e32 v80, 0x3fb8aa3b, v80
	v_mul_f32_e32 v81, 0x3fb8aa3b, v81
	s_waitcnt vmcnt(1)
	v_lshlrev_b32_e32 v84, 16, v90
	v_and_b32_e32 v85, 0xffff0000, v90
	v_lshlrev_b32_e32 v88, 16, v91
	v_and_b32_e32 v89, 0xffff0000, v91
	s_waitcnt vmcnt(0)
	v_lshlrev_b32_e32 v90, 16, v86
	v_and_b32_e32 v91, 0xffff0000, v86
	v_lshlrev_b32_e32 v86, 16, v87
	v_and_b32_e32 v87, 0xffff0000, v87
	v_pk_fma_f32 v[86:87], v[94:95], v[88:89], v[86:87]
	v_pk_fma_f32 v[84:85], v[92:93], v[84:85], v[90:91]
	v_cvt_pk_bf16_f32 v89, v86, v87
	v_cvt_pk_bf16_f32 v88, v84, v85
	v_lshl_add_u64 v[90:91], s[28:29], 0, v[102:103]
	global_store_dwordx2 v[90:91], v[88:89], off
	v_lshl_add_u64 v[90:91], v[98:99], 0, v[116:117]
	v_lshlrev_b64 v[90:91], 1, v[90:91]
	v_lshl_add_u64 v[92:93], s[18:19], 0, v[90:91]
	global_load_dwordx2 v[88:89], v[100:101], off offset:288
	v_exp_f32_e32 v80, v80
	global_load_dwordx2 v[92:93], v[92:93], off
	v_exp_f32_e32 v81, v81
	v_mul_f32_e32 v85, v85, v85
	v_fmac_f32_e32 v85, v84, v84
	v_fmac_f32_e32 v85, v86, v86
	v_pk_add_f32 v[80:81], v[80:81], 1.0 op_sel_hi:[1,0]
	v_fmac_f32_e32 v85, v87, v87
	v_add_f32_e32 v94, v85, v104
	v_mul_f32_e64 v82, v82, -v122
	v_mul_f32_e64 v83, v83, -v122
	v_mul_f32_e32 v82, 0x3fb8aa3b, v82
	v_mul_f32_e32 v83, 0x3fb8aa3b, v83
	v_exp_f32_e32 v82, v82
	v_exp_f32_e32 v83, v83
	v_rcp_f32_e32 v81, v81
	v_pk_add_f32 v[82:83], v[82:83], 1.0 op_sel_hi:[1,0]
	v_rcp_f32_e32 v80, v80
	v_rcp_f32_e32 v83, v83
	v_rcp_f32_e32 v82, v82
	s_waitcnt vmcnt(1)
	v_lshlrev_b32_e32 v84, 16, v88
	v_and_b32_e32 v85, 0xffff0000, v88
	v_lshlrev_b32_e32 v86, 16, v89
	v_and_b32_e32 v87, 0xffff0000, v89
	s_waitcnt vmcnt(0)
	v_lshlrev_b32_e32 v88, 16, v92
	v_and_b32_e32 v89, 0xffff0000, v92
	v_pk_fma_f32 v[84:85], v[80:81], v[84:85], v[88:89]
	v_lshlrev_b32_e32 v92, 16, v93
	v_and_b32_e32 v93, 0xffff0000, v93
	v_mul_f32_e32 v80, v85, v85
	v_pk_fma_f32 v[82:83], v[82:83], v[86:87], v[92:93]
	v_fmac_f32_e32 v80, v84, v84
	v_fmac_f32_e32 v80, v82, v82
	v_fmac_f32_e32 v80, v83, v83
	v_add_f32_e32 v80, v94, v80
	ds_bpermute_b32 v81, v124, v80
	v_cvt_pk_bf16_f32 v84, v84, v85
	v_cvt_pk_bf16_f32 v85, v82, v83
	v_lshl_add_u64 v[82:83], s[28:29], 0, v[90:91]
	global_store_dwordx2 v[82:83], v[84:85], off
	s_waitcnt lgkmcnt(0)
	v_add_f32_e32 v80, v80, v81
	ds_bpermute_b32 v81, v125, v80
	s_and_saveexec_b64 s[0:1], s[6:7]
	s_cbranch_execz .LBB0_2378
; DI unsigned cvtpk(float lo, float hi) { f32x2_t v = {lo, hi}; bf16x2_t b = __builtin_convertvector(v, bf16x2_t); return __builtin_bit_cast(unsigned, b); }
;   DI void operator()(const f32x4 (&acc)[2][2][4][2], const pg8::Unit& u, int wr, int wc, int fr, int fq) const {
;     ...
;       for (int m = 0; m < 4; ++m) {
;         const int row = u.pm * 256 + ai * 128 + wr * 64 + m * 16 + fr; float rs = 0.f;
;         const float rstd = rsqrtf(ssx[row] * (1.f / DM) + EPS);
; #pragma unroll
;         for (int bj = 0; bj < 2; ++bj)
; #pragma unroll
;           for (int n = 0; n < 2; ++n) {
;             const int col = u.pn * 256 + bj * 128 + wc * 32 + n * 16 + fq * 4; const size_t off = (size_t)row * DM + col;
;             f32x4 g;
; #pragma unroll
;             for (int j = 0; j < 4; ++j) g[j] = 1.f / (1.f + __expf(-rstd * acc[ai][bj][m][n][j]));
;             const u32x2 pw = *(const u32x2*)(PT + off); f32x4 pp; pp.x = __uint_as_float(pw.x << 16); pp.y = __uint_as_float(pw.x & 0xffff0000u); pp.z = __uint_as_float(pw.y << 16); pp.w = __uint_as_float(pw.y & 0xffff0000u);
;             const u32x2 xw = *(const u32x2*)(X1B + off); f32x4 x1; x1.x = __uint_as_float(xw.x << 16); x1.y = __uint_as_float(xw.x & 0xffff0000u); x1.z = __uint_as_float(xw.y << 16); x1.w = __uint_as_float(xw.y & 0xffff0000u);
;             const f32x4 xn = x1 + pp * g;
;             if (layer != 0) *(f32x4*)(out + off) = xn;
;             if (layer == 0) {
;               rs += xn.x * xn.x + xn.y * xn.y + xn.z * xn.z + xn.w * xn.w;
;               u32x2 w; w.x = cvtpk(xn.x, xn.y); w.y = cvtpk(xn.z, xn.w); *(u32x2*)(H + off) = w;
;             }
;           }
;         if (layer == 0) { rs += __shfl_xor(rs, 16); rs += __shfl_xor(rs, 32); if (fq == 0) atomicAdd(ss1 + row, rs); }
	s_waitcnt lgkmcnt(0)
	v_add_f32_e32 v82, v80, v81
	v_lshl_add_u64 v[80:81], v[96:97], 2, s[22:23]
	global_atomic_add_f32 v[80:81], v82, off
.LBB0_2378:
	s_or_b64 exec, exec, s[0:1]
	v_or_b32_e32 v80, 48, v146
	s_waitcnt lgkmcnt(0)
	v_ashrrev_i32_e32 v81, 31, v80
	v_lshl_add_u64 v[82:83], v[80:81], 2, s[24:25]
	global_load_dword v100, v[82:83], off
	v_lshlrev_b64 v[82:83], 10, v[80:81]
	v_lshl_add_u64 v[84:85], v[82:83], 0, v[140:141]
	v_lshlrev_b64 v[90:91], 1, v[84:85]
	v_lshl_add_u64 v[86:87], s[18:19], 0, v[90:91]
	global_load_dwordx2 v[88:89], v[86:87], off
	v_lshl_add_u64 v[84:85], s[16:17], 0, v[90:91]
	global_load_dwordx2 v[92:93], v[84:85], off
	global_load_dwordx2 v[98:99], v[84:85], off offset:32
	v_lshl_add_u64 v[86:87], v[82:83], 0, v[142:143]
	v_lshl_add_u64 v[94:95], v[82:83], 0, v[144:145]
	v_lshlrev_b64 v[96:97], 1, v[86:87]
	v_lshl_add_u64 v[90:91], s[28:29], 0, v[90:91]
	v_lshlrev_b64 v[86:87], 1, v[94:95]
	v_lshl_add_u64 v[94:95], s[18:19], 0, v[96:97]
	s_waitcnt vmcnt(3)
	v_fmamk_f32 v100, v100, 0x3a800000, v158
	v_mul_f32_e32 v101, 0x4b800000, v100
	v_cmp_gt_f32_e32 vcc, s54, v100
	s_waitcnt vmcnt(2)
	v_lshlrev_b32_e32 v102, 16, v88
	v_cndmask_b32_e32 v100, v100, v101, vcc
	v_rsq_f32_e32 v104, v100
	v_and_b32_e32 v103, 0xffff0000, v88
	s_waitcnt vmcnt(1)
	v_lshlrev_b32_e32 v100, 16, v92
	v_and_b32_e32 v101, 0xffff0000, v92
	v_mul_f32_e32 v88, 0x45800000, v104
	v_cndmask_b32_e32 v104, v104, v88, vcc
	v_mul_f32_e64 v76, v76, -v104
	v_mul_f32_e64 v77, v77, -v104
	v_mul_f32_e32 v76, 0x3fb8aa3b, v76
	v_mul_f32_e32 v77, 0x3fb8aa3b, v77
	v_mul_f32_e64 v78, v78, -v104
	v_mul_f32_e64 v79, v79, -v104
	v_exp_f32_e32 v76, v76
	v_exp_f32_e32 v77, v77
	v_mul_f32_e32 v78, 0x3fb8aa3b, v78
	v_mul_f32_e32 v79, 0x3fb8aa3b, v79
	v_exp_f32_e32 v78, v78
	v_exp_f32_e32 v79, v79
	v_pk_add_f32 v[76:77], v[76:77], 1.0 op_sel_hi:[1,0]
	v_lshlrev_b32_e32 v92, 16, v93
	v_pk_add_f32 v[78:79], v[78:79], 1.0 op_sel_hi:[1,0]
	v_rcp_f32_e32 v77, v77
	v_rcp_f32_e32 v76, v76
	v_rcp_f32_e32 v79, v79
	v_and_b32_e32 v93, 0xffff0000, v93
	v_lshlrev_b32_e32 v88, 16, v89
	v_and_b32_e32 v89, 0xffff0000, v89
	v_rcp_f32_e32 v78, v78
	v_pk_fma_f32 v[76:77], v[76:77], v[100:101], v[102:103]
	v_pk_fma_f32 v[78:79], v[78:79], v[92:93], v[88:89]
	v_cvt_pk_bf16_f32 v100, v76, v77
	v_cvt_pk_bf16_f32 v101, v78, v79
	global_store_dwordx2 v[90:91], v[100:101], off
	global_load_dwordx2 v[88:89], v[94:95], off
	v_mul_f32_e64 v72, v72, -v104
	v_mul_f32_e64 v73, v73, -v104
	s_waitcnt vmcnt(2)
	v_lshlrev_b32_e32 v94, 16, v98
	v_and_b32_e32 v95, 0xffff0000, v98
	v_mul_f32_e64 v98, v68, -v104
	v_mul_f32_e32 v68, 0x3fb8aa3b, v72
	v_mul_f32_e32 v73, 0x3fb8aa3b, v73
	v_mul_f32_e64 v74, v74, -v104
	v_mul_f32_e64 v75, v75, -v104
	v_exp_f32_e32 v72, v68
	v_exp_f32_e32 v73, v73
	v_mul_f32_e32 v74, 0x3fb8aa3b, v74
	v_mul_f32_e32 v75, 0x3fb8aa3b, v75
	v_exp_f32_e32 v74, v74
	v_exp_f32_e32 v75, v75
	v_pk_add_f32 v[72:73], v[72:73], 1.0 op_sel_hi:[1,0]
	v_mul_f32_e64 v100, v70, -v104
	v_lshl_add_u64 v[90:91], s[28:29], 0, v[96:97]
	v_lshlrev_b32_e32 v96, 16, v99
	v_and_b32_e32 v97, 0xffff0000, v99
	v_mul_f32_e64 v99, v69, -v104
	v_pk_add_f32 v[68:69], v[74:75], 1.0 op_sel_hi:[1,0]
	v_rcp_f32_e32 v73, v73
	v_rcp_f32_e32 v72, v72
	v_rcp_f32_e32 v69, v69
	v_rcp_f32_e32 v68, v68
	v_lshl_add_u64 v[92:93], s[18:19], 0, v[86:87]
	v_mul_f32_e64 v64, v64, -v104
	s_waitcnt vmcnt(0)
	v_lshlrev_b32_e32 v74, 16, v88
	v_and_b32_e32 v75, 0xffff0000, v88
	v_lshlrev_b32_e32 v88, 16, v89
	v_and_b32_e32 v89, 0xffff0000, v89
	v_pk_fma_f32 v[68:69], v[68:69], v[96:97], v[88:89]
	v_pk_fma_f32 v[72:73], v[72:73], v[94:95], v[74:75]
	v_cvt_pk_bf16_f32 v75, v68, v69
	v_cvt_pk_bf16_f32 v74, v72, v73
	global_store_dwordx2 v[90:91], v[74:75], off
	global_load_dwordx2 v[74:75], v[84:85], off offset:256
	v_mul_f32_e64 v88, v71, -v104
	global_load_dwordx2 v[70:71], v[92:93], off
	v_mul_f32_e32 v89, 0x3fb8aa3b, v98
	v_mul_f32_e32 v94, 0x3fb8aa3b, v99
	v_mul_f32_e32 v90, 0x3fb8aa3b, v100
	v_mul_f32_e32 v91, 0x3fb8aa3b, v88
	v_exp_f32_e32 v88, v89
	v_exp_f32_e32 v90, v90
	v_exp_f32_e32 v91, v91
	v_exp_f32_e32 v89, v94
	v_mul_f32_e32 v73, v73, v73
	v_fmac_f32_e32 v73, v72, v72
	v_pk_add_f32 v[90:91], v[90:91], 1.0 op_sel_hi:[1,0]
	v_pk_add_f32 v[88:89], v[88:89], 1.0 op_sel_hi:[1,0]
	v_mul_f32_e32 v96, v77, v77
	v_fmac_f32_e32 v96, v76, v76
	v_rcp_f32_e32 v77, v89
	v_fmac_f32_e32 v96, v78, v78
	v_fmac_f32_e32 v73, v68, v68
	v_fmac_f32_e32 v96, v79, v79
	v_rcp_f32_e32 v79, v91
	v_fmac_f32_e32 v73, v69, v69
	v_rcp_f32_e32 v76, v88
	v_rcp_f32_e32 v78, v90
	v_add_f32_e32 v88, v96, v73
	v_mul_f32_e64 v65, v65, -v104
	v_mul_f32_e32 v64, 0x3fb8aa3b, v64
	v_mul_f32_e32 v65, 0x3fb8aa3b, v65
	s_waitcnt vmcnt(1)
	v_lshlrev_b32_e32 v68, 16, v74
	v_and_b32_e32 v69, 0xffff0000, v74
	v_lshlrev_b32_e32 v72, 16, v75
	v_and_b32_e32 v73, 0xffff0000, v75
	s_waitcnt vmcnt(0)
	v_lshlrev_b32_e32 v74, 16, v70
	v_and_b32_e32 v75, 0xffff0000, v70
	v_lshlrev_b32_e32 v70, 16, v71
	v_and_b32_e32 v71, 0xffff0000, v71
	v_pk_fma_f32 v[70:71], v[78:79], v[72:73], v[70:71]
	v_pk_fma_f32 v[68:69], v[76:77], v[68:69], v[74:75]
	v_cvt_pk_bf16_f32 v73, v70, v71
	v_cvt_pk_bf16_f32 v72, v68, v69
	v_lshl_add_u64 v[74:75], s[28:29], 0, v[86:87]
	global_store_dwordx2 v[74:75], v[72:73], off
	v_lshl_add_u64 v[74:75], v[82:83], 0, v[116:117]
	v_lshlrev_b64 v[74:75], 1, v[74:75]
	v_lshl_add_u64 v[76:77], s[18:19], 0, v[74:75]
	global_load_dwordx2 v[72:73], v[84:85], off offset:288
	v_exp_f32_e32 v64, v64
	global_load_dwordx2 v[76:77], v[76:77], off
	v_exp_f32_e32 v65, v65
	v_mul_f32_e32 v69, v69, v69
	v_fmac_f32_e32 v69, v68, v68
	v_fmac_f32_e32 v69, v70, v70
	v_pk_add_f32 v[64:65], v[64:65], 1.0 op_sel_hi:[1,0]
	v_fmac_f32_e32 v69, v71, v71
	v_add_f32_e32 v78, v69, v88
	v_mul_f32_e64 v66, v66, -v104
	v_mul_f32_e64 v67, v67, -v104
	v_mul_f32_e32 v66, 0x3fb8aa3b, v66
	v_mul_f32_e32 v67, 0x3fb8aa3b, v67
	v_exp_f32_e32 v66, v66
	v_exp_f32_e32 v67, v67
	v_rcp_f32_e32 v65, v65
	v_pk_add_f32 v[66:67], v[66:67], 1.0 op_sel_hi:[1,0]
	v_rcp_f32_e32 v64, v64
	v_rcp_f32_e32 v67, v67
	v_rcp_f32_e32 v66, v66
	s_waitcnt vmcnt(1)
	v_lshlrev_b32_e32 v68, 16, v72
	v_and_b32_e32 v69, 0xffff0000, v72
	v_lshlrev_b32_e32 v70, 16, v73
	v_and_b32_e32 v71, 0xffff0000, v73
	s_waitcnt vmcnt(0)
	v_lshlrev_b32_e32 v72, 16, v76
	v_and_b32_e32 v73, 0xffff0000, v76
	v_pk_fma_f32 v[68:69], v[64:65], v[68:69], v[72:73]
	v_lshlrev_b32_e32 v76, 16, v77
	v_and_b32_e32 v77, 0xffff0000, v77
	v_mul_f32_e32 v64, v69, v69
	v_pk_fma_f32 v[66:67], v[66:67], v[70:71], v[76:77]
	v_fmac_f32_e32 v64, v68, v68
	v_fmac_f32_e32 v64, v66, v66
	v_fmac_f32_e32 v64, v67, v67
	v_add_f32_e32 v64, v78, v64
	ds_bpermute_b32 v65, v124, v64
	v_cvt_pk_bf16_f32 v68, v68, v69
	v_cvt_pk_bf16_f32 v69, v66, v67
	v_lshl_add_u64 v[66:67], s[28:29], 0, v[74:75]
	global_store_dwordx2 v[66:67], v[68:69], off
	s_waitcnt lgkmcnt(0)
	v_add_f32_e32 v64, v64, v65
	ds_bpermute_b32 v65, v125, v64
	s_and_saveexec_b64 s[0:1], s[6:7]
	s_cbranch_execz .LBB0_2380
; DI unsigned cvtpk(float lo, float hi) { f32x2_t v = {lo, hi}; bf16x2_t b = __builtin_convertvector(v, bf16x2_t); return __builtin_bit_cast(unsigned, b); }
;   DI void operator()(const f32x4 (&acc)[2][2][4][2], const pg8::Unit& u, int wr, int wc, int fr, int fq) const {
;     ...
;       for (int m = 0; m < 4; ++m) {
;         const int row = u.pm * 256 + ai * 128 + wr * 64 + m * 16 + fr; float rs = 0.f;
;         const float rstd = rsqrtf(ssx[row] * (1.f / DM) + EPS);
; #pragma unroll
;         for (int bj = 0; bj < 2; ++bj)
; #pragma unroll
;           for (int n = 0; n < 2; ++n) {
;             const int col = u.pn * 256 + bj * 128 + wc * 32 + n * 16 + fq * 4; const size_t off = (size_t)row * DM + col;
;             f32x4 g;
; #pragma unroll
;             for (int j = 0; j < 4; ++j) g[j] = 1.f / (1.f + __expf(-rstd * acc[ai][bj][m][n][j]));
;             const u32x2 pw = *(const u32x2*)(PT + off); f32x4 pp; pp.x = __uint_as_float(pw.x << 16); pp.y = __uint_as_float(pw.x & 0xffff0000u); pp.z = __uint_as_float(pw.y << 16); pp.w = __uint_as_float(pw.y & 0xffff0000u);
;             const u32x2 xw = *(const u32x2*)(X1B + off); f32x4 x1; x1.x = __uint_as_float(xw.x << 16); x1.y = __uint_as_float(xw.x & 0xffff0000u); x1.z = __uint_as_float(xw.y << 16); x1.w = __uint_as_float(xw.y & 0xffff0000u);
;             const f32x4 xn = x1 + pp * g;
;             if (layer != 0) *(f32x4*)(out + off) = xn;
;             if (layer == 0) {
;               rs += xn.x * xn.x + xn.y * xn.y + xn.z * xn.z + xn.w * xn.w;
;               u32x2 w; w.x = cvtpk(xn.x, xn.y); w.y = cvtpk(xn.z, xn.w); *(u32x2*)(H + off) = w;
;             }
;           }
;         if (layer == 0) { rs += __shfl_xor(rs, 16); rs += __shfl_xor(rs, 32); if (fq == 0) atomicAdd(ss1 + row, rs); }
	s_waitcnt lgkmcnt(0)
	v_add_f32_e32 v66, v64, v65
	v_lshl_add_u64 v[64:65], v[80:81], 2, s[22:23]
	global_atomic_add_f32 v[64:65], v66, off
.LBB0_2380:
	s_or_b64 exec, exec, s[0:1]
	v_add_u32_e32 v64, 0x80, v146
	s_waitcnt lgkmcnt(0)
	v_ashrrev_i32_e32 v65, 31, v64
	v_lshl_add_u64 v[66:67], v[64:65], 2, s[24:25]
	global_load_dword v84, v[66:67], off
	v_lshlrev_b64 v[66:67], 10, v[64:65]
	v_lshl_add_u64 v[68:69], v[66:67], 0, v[140:141]
	v_lshlrev_b64 v[74:75], 1, v[68:69]
	v_lshl_add_u64 v[70:71], s[18:19], 0, v[74:75]
	global_load_dwordx2 v[72:73], v[70:71], off
	v_lshl_add_u64 v[68:69], s[16:17], 0, v[74:75]
	global_load_dwordx2 v[76:77], v[68:69], off
	global_load_dwordx2 v[82:83], v[68:69], off offset:32
	v_lshl_add_u64 v[70:71], v[66:67], 0, v[142:143]
	v_lshl_add_u64 v[78:79], v[66:67], 0, v[144:145]
	v_lshlrev_b64 v[80:81], 1, v[70:71]
	v_lshl_add_u64 v[74:75], s[28:29], 0, v[74:75]
	v_lshlrev_b64 v[70:71], 1, v[78:79]
	v_lshl_add_u64 v[78:79], s[18:19], 0, v[80:81]
	s_waitcnt vmcnt(3)
	v_fmamk_f32 v84, v84, 0x3a800000, v158
	v_mul_f32_e32 v85, 0x4b800000, v84
	v_cmp_gt_f32_e32 vcc, s54, v84
	s_waitcnt vmcnt(2)
	v_lshlrev_b32_e32 v86, 16, v72
	v_cndmask_b32_e32 v84, v84, v85, vcc
	v_rsq_f32_e32 v88, v84
	v_and_b32_e32 v87, 0xffff0000, v72
	s_waitcnt vmcnt(1)
	v_lshlrev_b32_e32 v84, 16, v76
	v_and_b32_e32 v85, 0xffff0000, v76
	v_mul_f32_e32 v72, 0x45800000, v88
	v_cndmask_b32_e32 v88, v88, v72, vcc
	v_mul_f32_e64 v60, v60, -v88
	v_mul_f32_e64 v61, v61, -v88
	v_mul_f32_e32 v60, 0x3fb8aa3b, v60
	v_mul_f32_e32 v61, 0x3fb8aa3b, v61
	v_mul_f32_e64 v62, v62, -v88
	v_mul_f32_e64 v63, v63, -v88
	v_exp_f32_e32 v60, v60
	v_exp_f32_e32 v61, v61
	v_mul_f32_e32 v62, 0x3fb8aa3b, v62
	v_mul_f32_e32 v63, 0x3fb8aa3b, v63
	v_exp_f32_e32 v62, v62
	v_exp_f32_e32 v63, v63
	v_pk_add_f32 v[60:61], v[60:61], 1.0 op_sel_hi:[1,0]
	v_lshlrev_b32_e32 v76, 16, v77
	v_pk_add_f32 v[62:63], v[62:63], 1.0 op_sel_hi:[1,0]
	v_rcp_f32_e32 v61, v61
	v_rcp_f32_e32 v60, v60
	v_rcp_f32_e32 v63, v63
	v_and_b32_e32 v77, 0xffff0000, v77
	v_lshlrev_b32_e32 v72, 16, v73
	v_and_b32_e32 v73, 0xffff0000, v73
	v_rcp_f32_e32 v62, v62
	v_pk_fma_f32 v[60:61], v[60:61], v[84:85], v[86:87]
	v_pk_fma_f32 v[62:63], v[62:63], v[76:77], v[72:73]
	v_cvt_pk_bf16_f32 v84, v60, v61
	v_cvt_pk_bf16_f32 v85, v62, v63
	global_store_dwordx2 v[74:75], v[84:85], off
	global_load_dwordx2 v[72:73], v[78:79], off
	v_mul_f32_e64 v56, v56, -v88
	v_mul_f32_e64 v57, v57, -v88
	s_waitcnt vmcnt(2)
	v_lshlrev_b32_e32 v78, 16, v82
	v_and_b32_e32 v79, 0xffff0000, v82
	v_mul_f32_e64 v82, v52, -v88
	v_mul_f32_e32 v52, 0x3fb8aa3b, v56
	v_mul_f32_e32 v57, 0x3fb8aa3b, v57
	v_mul_f32_e64 v58, v58, -v88
	v_mul_f32_e64 v59, v59, -v88
	v_exp_f32_e32 v56, v52
	v_exp_f32_e32 v57, v57
	v_mul_f32_e32 v58, 0x3fb8aa3b, v58
	v_mul_f32_e32 v59, 0x3fb8aa3b, v59
	v_exp_f32_e32 v58, v58
	v_exp_f32_e32 v59, v59
	v_pk_add_f32 v[56:57], v[56:57], 1.0 op_sel_hi:[1,0]
	v_mul_f32_e64 v84, v54, -v88
	v_lshl_add_u64 v[74:75], s[28:29], 0, v[80:81]
	v_lshlrev_b32_e32 v80, 16, v83
	v_and_b32_e32 v81, 0xffff0000, v83
	v_mul_f32_e64 v83, v53, -v88
	v_pk_add_f32 v[52:53], v[58:59], 1.0 op_sel_hi:[1,0]
	v_rcp_f32_e32 v57, v57
	v_rcp_f32_e32 v56, v56
	v_rcp_f32_e32 v53, v53
	v_rcp_f32_e32 v52, v52
	v_lshl_add_u64 v[76:77], s[18:19], 0, v[70:71]
	v_mul_f32_e64 v48, v48, -v88
	s_waitcnt vmcnt(0)
	v_lshlrev_b32_e32 v58, 16, v72
	v_and_b32_e32 v59, 0xffff0000, v72
	v_lshlrev_b32_e32 v72, 16, v73
	v_and_b32_e32 v73, 0xffff0000, v73
	v_pk_fma_f32 v[52:53], v[52:53], v[80:81], v[72:73]
	v_pk_fma_f32 v[56:57], v[56:57], v[78:79], v[58:59]
	v_cvt_pk_bf16_f32 v59, v52, v53
	v_cvt_pk_bf16_f32 v58, v56, v57
	global_store_dwordx2 v[74:75], v[58:59], off
	global_load_dwordx2 v[58:59], v[68:69], off offset:256
	v_mul_f32_e64 v72, v55, -v88
	global_load_dwordx2 v[54:55], v[76:77], off
	v_mul_f32_e32 v73, 0x3fb8aa3b, v82
	v_mul_f32_e32 v78, 0x3fb8aa3b, v83
	v_mul_f32_e32 v74, 0x3fb8aa3b, v84
	v_mul_f32_e32 v75, 0x3fb8aa3b, v72
	v_exp_f32_e32 v72, v73
	v_exp_f32_e32 v74, v74
	v_exp_f32_e32 v75, v75
	v_exp_f32_e32 v73, v78
	v_mul_f32_e32 v57, v57, v57
	v_fmac_f32_e32 v57, v56, v56
	v_pk_add_f32 v[74:75], v[74:75], 1.0 op_sel_hi:[1,0]
	v_pk_add_f32 v[72:73], v[72:73], 1.0 op_sel_hi:[1,0]
	v_mul_f32_e32 v80, v61, v61
	v_fmac_f32_e32 v80, v60, v60
	v_rcp_f32_e32 v61, v73
	v_fmac_f32_e32 v80, v62, v62
	v_fmac_f32_e32 v57, v52, v52
	v_fmac_f32_e32 v80, v63, v63
	v_rcp_f32_e32 v63, v75
	v_fmac_f32_e32 v57, v53, v53
	v_rcp_f32_e32 v60, v72
	v_rcp_f32_e32 v62, v74
	v_add_f32_e32 v72, v80, v57
	v_mul_f32_e64 v49, v49, -v88
	v_mul_f32_e32 v48, 0x3fb8aa3b, v48
	v_mul_f32_e32 v49, 0x3fb8aa3b, v49
	s_waitcnt vmcnt(1)
	v_lshlrev_b32_e32 v52, 16, v58
	v_and_b32_e32 v53, 0xffff0000, v58
	v_lshlrev_b32_e32 v56, 16, v59
	v_and_b32_e32 v57, 0xffff0000, v59
	s_waitcnt vmcnt(0)
	v_lshlrev_b32_e32 v58, 16, v54
	v_and_b32_e32 v59, 0xffff0000, v54
	v_lshlrev_b32_e32 v54, 16, v55
	v_and_b32_e32 v55, 0xffff0000, v55
	v_pk_fma_f32 v[54:55], v[62:63], v[56:57], v[54:55]
	v_pk_fma_f32 v[52:53], v[60:61], v[52:53], v[58:59]
	v_cvt_pk_bf16_f32 v57, v54, v55
	v_cvt_pk_bf16_f32 v56, v52, v53
	v_lshl_add_u64 v[58:59], s[28:29], 0, v[70:71]
	global_store_dwordx2 v[58:59], v[56:57], off
	v_lshl_add_u64 v[58:59], v[66:67], 0, v[116:117]
	v_lshlrev_b64 v[58:59], 1, v[58:59]
	v_lshl_add_u64 v[60:61], s[18:19], 0, v[58:59]
	global_load_dwordx2 v[56:57], v[68:69], off offset:288
	v_exp_f32_e32 v48, v48
	global_load_dwordx2 v[60:61], v[60:61], off
	v_exp_f32_e32 v49, v49
	v_mul_f32_e32 v53, v53, v53
	v_fmac_f32_e32 v53, v52, v52
	v_fmac_f32_e32 v53, v54, v54
	v_pk_add_f32 v[48:49], v[48:49], 1.0 op_sel_hi:[1,0]
	v_fmac_f32_e32 v53, v55, v55
	v_add_f32_e32 v62, v53, v72
	v_mul_f32_e64 v50, v50, -v88
	v_mul_f32_e64 v51, v51, -v88
	v_mul_f32_e32 v50, 0x3fb8aa3b, v50
	v_mul_f32_e32 v51, 0x3fb8aa3b, v51
	v_exp_f32_e32 v50, v50
	v_exp_f32_e32 v51, v51
	v_rcp_f32_e32 v49, v49
	v_pk_add_f32 v[50:51], v[50:51], 1.0 op_sel_hi:[1,0]
	v_rcp_f32_e32 v48, v48
	v_rcp_f32_e32 v51, v51
	v_rcp_f32_e32 v50, v50
	s_waitcnt vmcnt(1)
	v_lshlrev_b32_e32 v52, 16, v56
	v_and_b32_e32 v53, 0xffff0000, v56
	v_lshlrev_b32_e32 v54, 16, v57
	v_and_b32_e32 v55, 0xffff0000, v57
	s_waitcnt vmcnt(0)
	v_lshlrev_b32_e32 v56, 16, v60
	v_and_b32_e32 v57, 0xffff0000, v60
	v_pk_fma_f32 v[52:53], v[48:49], v[52:53], v[56:57]
	v_lshlrev_b32_e32 v60, 16, v61
	v_and_b32_e32 v61, 0xffff0000, v61
	v_mul_f32_e32 v48, v53, v53
	v_pk_fma_f32 v[50:51], v[50:51], v[54:55], v[60:61]
	v_fmac_f32_e32 v48, v52, v52
	v_fmac_f32_e32 v48, v50, v50
	v_fmac_f32_e32 v48, v51, v51
	v_add_f32_e32 v48, v62, v48
	ds_bpermute_b32 v49, v124, v48
	v_cvt_pk_bf16_f32 v52, v52, v53
	v_cvt_pk_bf16_f32 v53, v50, v51
	v_lshl_add_u64 v[50:51], s[28:29], 0, v[58:59]
	global_store_dwordx2 v[50:51], v[52:53], off
	s_waitcnt lgkmcnt(0)
	v_add_f32_e32 v48, v48, v49
	ds_bpermute_b32 v49, v125, v48
	s_and_saveexec_b64 s[0:1], s[6:7]
	s_cbranch_execz .LBB0_2382
; DI unsigned cvtpk(float lo, float hi) { f32x2_t v = {lo, hi}; bf16x2_t b = __builtin_convertvector(v, bf16x2_t); return __builtin_bit_cast(unsigned, b); }
;   DI void operator()(const f32x4 (&acc)[2][2][4][2], const pg8::Unit& u, int wr, int wc, int fr, int fq) const {
;     ...
;       for (int m = 0; m < 4; ++m) {
;         const int row = u.pm * 256 + ai * 128 + wr * 64 + m * 16 + fr; float rs = 0.f;
;         const float rstd = rsqrtf(ssx[row] * (1.f / DM) + EPS);
; #pragma unroll
;         for (int bj = 0; bj < 2; ++bj)
; #pragma unroll
;           for (int n = 0; n < 2; ++n) {
;             const int col = u.pn * 256 + bj * 128 + wc * 32 + n * 16 + fq * 4; const size_t off = (size_t)row * DM + col;
;             f32x4 g;
; #pragma unroll
;             for (int j = 0; j < 4; ++j) g[j] = 1.f / (1.f + __expf(-rstd * acc[ai][bj][m][n][j]));
;             const u32x2 pw = *(const u32x2*)(PT + off); f32x4 pp; pp.x = __uint_as_float(pw.x << 16); pp.y = __uint_as_float(pw.x & 0xffff0000u); pp.z = __uint_as_float(pw.y << 16); pp.w = __uint_as_float(pw.y & 0xffff0000u);
;             const u32x2 xw = *(const u32x2*)(X1B + off); f32x4 x1; x1.x = __uint_as_float(xw.x << 16); x1.y = __uint_as_float(xw.x & 0xffff0000u); x1.z = __uint_as_float(xw.y << 16); x1.w = __uint_as_float(xw.y & 0xffff0000u);
;             const f32x4 xn = x1 + pp * g;
;             if (layer != 0) *(f32x4*)(out + off) = xn;
;             if (layer == 0) {
;               rs += xn.x * xn.x + xn.y * xn.y + xn.z * xn.z + xn.w * xn.w;
;               u32x2 w; w.x = cvtpk(xn.x, xn.y); w.y = cvtpk(xn.z, xn.w); *(u32x2*)(H + off) = w;
;             }
;           }
;         if (layer == 0) { rs += __shfl_xor(rs, 16); rs += __shfl_xor(rs, 32); if (fq == 0) atomicAdd(ss1 + row, rs); }
	s_waitcnt lgkmcnt(0)
	v_add_f32_e32 v50, v48, v49
	v_lshl_add_u64 v[48:49], v[64:65], 2, s[22:23]
	global_atomic_add_f32 v[48:49], v50, off
.LBB0_2382:
	s_or_b64 exec, exec, s[0:1]
	v_add_u32_e32 v48, 0x90, v146
	s_waitcnt lgkmcnt(0)
	v_ashrrev_i32_e32 v49, 31, v48
	v_lshl_add_u64 v[50:51], v[48:49], 2, s[24:25]
	global_load_dword v68, v[50:51], off
	v_lshlrev_b64 v[50:51], 10, v[48:49]
	v_lshl_add_u64 v[52:53], v[50:51], 0, v[140:141]
	v_lshlrev_b64 v[58:59], 1, v[52:53]
	v_lshl_add_u64 v[54:55], s[18:19], 0, v[58:59]
	global_load_dwordx2 v[56:57], v[54:55], off
	v_lshl_add_u64 v[52:53], s[16:17], 0, v[58:59]
	global_load_dwordx2 v[60:61], v[52:53], off
	global_load_dwordx2 v[66:67], v[52:53], off offset:32
	v_lshl_add_u64 v[54:55], v[50:51], 0, v[142:143]
	v_lshl_add_u64 v[62:63], v[50:51], 0, v[144:145]
	v_lshlrev_b64 v[64:65], 1, v[54:55]
	v_lshl_add_u64 v[58:59], s[28:29], 0, v[58:59]
	v_lshlrev_b64 v[54:55], 1, v[62:63]
	v_lshl_add_u64 v[62:63], s[18:19], 0, v[64:65]
	s_waitcnt vmcnt(3)
	v_fmamk_f32 v68, v68, 0x3a800000, v158
	v_mul_f32_e32 v69, 0x4b800000, v68
	v_cmp_gt_f32_e32 vcc, s54, v68
	s_waitcnt vmcnt(2)
	v_lshlrev_b32_e32 v70, 16, v56
	v_cndmask_b32_e32 v68, v68, v69, vcc
	v_rsq_f32_e32 v72, v68
	v_and_b32_e32 v71, 0xffff0000, v56
	s_waitcnt vmcnt(1)
	v_lshlrev_b32_e32 v68, 16, v60
	v_and_b32_e32 v69, 0xffff0000, v60
	v_mul_f32_e32 v56, 0x45800000, v72
	v_cndmask_b32_e32 v72, v72, v56, vcc
	v_mul_f32_e64 v44, v44, -v72
	v_mul_f32_e64 v45, v45, -v72
	v_mul_f32_e32 v44, 0x3fb8aa3b, v44
	v_mul_f32_e32 v45, 0x3fb8aa3b, v45
	v_mul_f32_e64 v46, v46, -v72
	v_mul_f32_e64 v47, v47, -v72
	v_exp_f32_e32 v44, v44
	v_exp_f32_e32 v45, v45
	v_mul_f32_e32 v46, 0x3fb8aa3b, v46
	v_mul_f32_e32 v47, 0x3fb8aa3b, v47
	v_exp_f32_e32 v46, v46
	v_exp_f32_e32 v47, v47
	v_pk_add_f32 v[44:45], v[44:45], 1.0 op_sel_hi:[1,0]
	v_lshlrev_b32_e32 v60, 16, v61
	v_pk_add_f32 v[46:47], v[46:47], 1.0 op_sel_hi:[1,0]
	v_rcp_f32_e32 v45, v45
	v_rcp_f32_e32 v44, v44
	v_rcp_f32_e32 v47, v47
	v_and_b32_e32 v61, 0xffff0000, v61
	v_lshlrev_b32_e32 v56, 16, v57
	v_and_b32_e32 v57, 0xffff0000, v57
	v_rcp_f32_e32 v46, v46
	v_pk_fma_f32 v[44:45], v[44:45], v[68:69], v[70:71]
	v_pk_fma_f32 v[46:47], v[46:47], v[60:61], v[56:57]
	v_cvt_pk_bf16_f32 v68, v44, v45
	v_cvt_pk_bf16_f32 v69, v46, v47
	global_store_dwordx2 v[58:59], v[68:69], off
	global_load_dwordx2 v[56:57], v[62:63], off
	v_mul_f32_e64 v40, v40, -v72
	v_mul_f32_e64 v41, v41, -v72
	s_waitcnt vmcnt(2)
	v_lshlrev_b32_e32 v62, 16, v66
	v_and_b32_e32 v63, 0xffff0000, v66
	v_mul_f32_e64 v66, v36, -v72
	v_mul_f32_e32 v36, 0x3fb8aa3b, v40
	v_mul_f32_e32 v41, 0x3fb8aa3b, v41
	v_mul_f32_e64 v42, v42, -v72
	v_mul_f32_e64 v43, v43, -v72
	v_exp_f32_e32 v40, v36
	v_exp_f32_e32 v41, v41
	v_mul_f32_e32 v42, 0x3fb8aa3b, v42
	v_mul_f32_e32 v43, 0x3fb8aa3b, v43
	v_exp_f32_e32 v42, v42
	v_exp_f32_e32 v43, v43
	v_pk_add_f32 v[40:41], v[40:41], 1.0 op_sel_hi:[1,0]
	v_mul_f32_e64 v68, v38, -v72
	v_lshl_add_u64 v[58:59], s[28:29], 0, v[64:65]
	v_lshlrev_b32_e32 v64, 16, v67
	v_and_b32_e32 v65, 0xffff0000, v67
	v_mul_f32_e64 v67, v37, -v72
	v_pk_add_f32 v[36:37], v[42:43], 1.0 op_sel_hi:[1,0]
	v_rcp_f32_e32 v41, v41
	v_rcp_f32_e32 v40, v40
	v_rcp_f32_e32 v37, v37
	v_rcp_f32_e32 v36, v36
	v_lshl_add_u64 v[60:61], s[18:19], 0, v[54:55]
	v_mul_f32_e64 v32, v32, -v72
	s_waitcnt vmcnt(0)
	v_lshlrev_b32_e32 v42, 16, v56
	v_and_b32_e32 v43, 0xffff0000, v56
	v_lshlrev_b32_e32 v56, 16, v57
	v_and_b32_e32 v57, 0xffff0000, v57
	v_pk_fma_f32 v[36:37], v[36:37], v[64:65], v[56:57]
	v_pk_fma_f32 v[40:41], v[40:41], v[62:63], v[42:43]
	v_cvt_pk_bf16_f32 v43, v36, v37
	v_cvt_pk_bf16_f32 v42, v40, v41
	global_store_dwordx2 v[58:59], v[42:43], off
	global_load_dwordx2 v[42:43], v[52:53], off offset:256
	v_mul_f32_e64 v56, v39, -v72
	global_load_dwordx2 v[38:39], v[60:61], off
	v_mul_f32_e32 v57, 0x3fb8aa3b, v66
	v_mul_f32_e32 v62, 0x3fb8aa3b, v67
	v_mul_f32_e32 v58, 0x3fb8aa3b, v68
	v_mul_f32_e32 v59, 0x3fb8aa3b, v56
	v_exp_f32_e32 v56, v57
	v_exp_f32_e32 v58, v58
	v_exp_f32_e32 v59, v59
	v_exp_f32_e32 v57, v62
	v_mul_f32_e32 v41, v41, v41
	v_fmac_f32_e32 v41, v40, v40
	v_pk_add_f32 v[58:59], v[58:59], 1.0 op_sel_hi:[1,0]
	v_pk_add_f32 v[56:57], v[56:57], 1.0 op_sel_hi:[1,0]
	v_mul_f32_e32 v64, v45, v45
	v_fmac_f32_e32 v64, v44, v44
	v_rcp_f32_e32 v45, v57
	v_fmac_f32_e32 v64, v46, v46
	v_fmac_f32_e32 v41, v36, v36
	v_fmac_f32_e32 v64, v47, v47
	v_rcp_f32_e32 v47, v59
	v_fmac_f32_e32 v41, v37, v37
	v_rcp_f32_e32 v44, v56
	v_rcp_f32_e32 v46, v58
	v_add_f32_e32 v56, v64, v41
	v_mul_f32_e64 v33, v33, -v72
	v_mul_f32_e32 v32, 0x3fb8aa3b, v32
	v_mul_f32_e32 v33, 0x3fb8aa3b, v33
	s_waitcnt vmcnt(1)
	v_lshlrev_b32_e32 v36, 16, v42
	v_and_b32_e32 v37, 0xffff0000, v42
	v_lshlrev_b32_e32 v40, 16, v43
	v_and_b32_e32 v41, 0xffff0000, v43
	s_waitcnt vmcnt(0)
	v_lshlrev_b32_e32 v42, 16, v38
	v_and_b32_e32 v43, 0xffff0000, v38
	v_lshlrev_b32_e32 v38, 16, v39
	v_and_b32_e32 v39, 0xffff0000, v39
	v_pk_fma_f32 v[38:39], v[46:47], v[40:41], v[38:39]
	v_pk_fma_f32 v[36:37], v[44:45], v[36:37], v[42:43]
	v_cvt_pk_bf16_f32 v41, v38, v39
	v_cvt_pk_bf16_f32 v40, v36, v37
	v_lshl_add_u64 v[42:43], s[28:29], 0, v[54:55]
	global_store_dwordx2 v[42:43], v[40:41], off
	v_lshl_add_u64 v[42:43], v[50:51], 0, v[116:117]
	v_lshlrev_b64 v[42:43], 1, v[42:43]
	v_lshl_add_u64 v[44:45], s[18:19], 0, v[42:43]
	global_load_dwordx2 v[40:41], v[52:53], off offset:288
	v_exp_f32_e32 v32, v32
	global_load_dwordx2 v[44:45], v[44:45], off
	v_exp_f32_e32 v33, v33
	v_mul_f32_e32 v37, v37, v37
	v_fmac_f32_e32 v37, v36, v36
	v_fmac_f32_e32 v37, v38, v38
	v_pk_add_f32 v[32:33], v[32:33], 1.0 op_sel_hi:[1,0]
	v_fmac_f32_e32 v37, v39, v39
	v_add_f32_e32 v46, v37, v56
	v_mul_f32_e64 v34, v34, -v72
	v_mul_f32_e64 v35, v35, -v72
	v_mul_f32_e32 v34, 0x3fb8aa3b, v34
	v_mul_f32_e32 v35, 0x3fb8aa3b, v35
	v_exp_f32_e32 v34, v34
	v_exp_f32_e32 v35, v35
	v_rcp_f32_e32 v33, v33
	v_pk_add_f32 v[34:35], v[34:35], 1.0 op_sel_hi:[1,0]
	v_rcp_f32_e32 v32, v32
	v_rcp_f32_e32 v35, v35
	v_rcp_f32_e32 v34, v34
	s_waitcnt vmcnt(1)
	v_lshlrev_b32_e32 v36, 16, v40
	v_and_b32_e32 v37, 0xffff0000, v40
	v_lshlrev_b32_e32 v38, 16, v41
	v_and_b32_e32 v39, 0xffff0000, v41
	s_waitcnt vmcnt(0)
	v_lshlrev_b32_e32 v40, 16, v44
	v_and_b32_e32 v41, 0xffff0000, v44
	v_pk_fma_f32 v[36:37], v[32:33], v[36:37], v[40:41]
	v_lshlrev_b32_e32 v44, 16, v45
	v_and_b32_e32 v45, 0xffff0000, v45
	v_mul_f32_e32 v32, v37, v37
	v_pk_fma_f32 v[34:35], v[34:35], v[38:39], v[44:45]
	v_fmac_f32_e32 v32, v36, v36
	v_fmac_f32_e32 v32, v34, v34
	v_fmac_f32_e32 v32, v35, v35
	v_add_f32_e32 v32, v46, v32
	ds_bpermute_b32 v33, v124, v32
	v_cvt_pk_bf16_f32 v36, v36, v37
	v_cvt_pk_bf16_f32 v37, v34, v35
	v_lshl_add_u64 v[34:35], s[28:29], 0, v[42:43]
	global_store_dwordx2 v[34:35], v[36:37], off
	s_waitcnt lgkmcnt(0)
	v_add_f32_e32 v32, v32, v33
	ds_bpermute_b32 v33, v125, v32
	s_and_saveexec_b64 s[0:1], s[6:7]
	s_cbranch_execz .LBB0_2384
; DI unsigned cvtpk(float lo, float hi) { f32x2_t v = {lo, hi}; bf16x2_t b = __builtin_convertvector(v, bf16x2_t); return __builtin_bit_cast(unsigned, b); }
;   DI void operator()(const f32x4 (&acc)[2][2][4][2], const pg8::Unit& u, int wr, int wc, int fr, int fq) const {
;     ...
;       for (int m = 0; m < 4; ++m) {
;         const int row = u.pm * 256 + ai * 128 + wr * 64 + m * 16 + fr; float rs = 0.f;
;         const float rstd = rsqrtf(ssx[row] * (1.f / DM) + EPS);
; #pragma unroll
;         for (int bj = 0; bj < 2; ++bj)
; #pragma unroll
;           for (int n = 0; n < 2; ++n) {
;             const int col = u.pn * 256 + bj * 128 + wc * 32 + n * 16 + fq * 4; const size_t off = (size_t)row * DM + col;
;             f32x4 g;
; #pragma unroll
;             for (int j = 0; j < 4; ++j) g[j] = 1.f / (1.f + __expf(-rstd * acc[ai][bj][m][n][j]));
;             const u32x2 pw = *(const u32x2*)(PT + off); f32x4 pp; pp.x = __uint_as_float(pw.x << 16); pp.y = __uint_as_float(pw.x & 0xffff0000u); pp.z = __uint_as_float(pw.y << 16); pp.w = __uint_as_float(pw.y & 0xffff0000u);
;             const u32x2 xw = *(const u32x2*)(X1B + off); f32x4 x1; x1.x = __uint_as_float(xw.x << 16); x1.y = __uint_as_float(xw.x & 0xffff0000u); x1.z = __uint_as_float(xw.y << 16); x1.w = __uint_as_float(xw.y & 0xffff0000u);
;             const f32x4 xn = x1 + pp * g;
;             if (layer != 0) *(f32x4*)(out + off) = xn;
;             if (layer == 0) {
;               rs += xn.x * xn.x + xn.y * xn.y + xn.z * xn.z + xn.w * xn.w;
;               u32x2 w; w.x = cvtpk(xn.x, xn.y); w.y = cvtpk(xn.z, xn.w); *(u32x2*)(H + off) = w;
;             }
;           }
;         if (layer == 0) { rs += __shfl_xor(rs, 16); rs += __shfl_xor(rs, 32); if (fq == 0) atomicAdd(ss1 + row, rs); }
	s_waitcnt lgkmcnt(0)
	v_add_f32_e32 v34, v32, v33
	v_lshl_add_u64 v[32:33], v[48:49], 2, s[22:23]
	global_atomic_add_f32 v[32:33], v34, off
.LBB0_2384:
	s_or_b64 exec, exec, s[0:1]
	v_add_u32_e32 v32, 0xa0, v146
	s_waitcnt lgkmcnt(0)
	v_ashrrev_i32_e32 v33, 31, v32
	v_lshl_add_u64 v[34:35], v[32:33], 2, s[24:25]
	global_load_dword v52, v[34:35], off
	v_lshlrev_b64 v[34:35], 10, v[32:33]
	v_lshl_add_u64 v[36:37], v[34:35], 0, v[140:141]
	v_lshlrev_b64 v[42:43], 1, v[36:37]
	v_lshl_add_u64 v[38:39], s[18:19], 0, v[42:43]
	global_load_dwordx2 v[40:41], v[38:39], off
	v_lshl_add_u64 v[36:37], s[16:17], 0, v[42:43]
	global_load_dwordx2 v[44:45], v[36:37], off
	global_load_dwordx2 v[50:51], v[36:37], off offset:32
	v_lshl_add_u64 v[38:39], v[34:35], 0, v[142:143]
	v_lshl_add_u64 v[46:47], v[34:35], 0, v[144:145]
	v_lshlrev_b64 v[48:49], 1, v[38:39]
	v_lshl_add_u64 v[42:43], s[28:29], 0, v[42:43]
	v_lshlrev_b64 v[38:39], 1, v[46:47]
	v_lshl_add_u64 v[46:47], s[18:19], 0, v[48:49]
	s_waitcnt vmcnt(3)
	v_fmamk_f32 v52, v52, 0x3a800000, v158
	v_mul_f32_e32 v53, 0x4b800000, v52
	v_cmp_gt_f32_e32 vcc, s54, v52
	s_waitcnt vmcnt(2)
	v_lshlrev_b32_e32 v54, 16, v40
	v_cndmask_b32_e32 v52, v52, v53, vcc
	v_rsq_f32_e32 v56, v52
	v_and_b32_e32 v55, 0xffff0000, v40
	s_waitcnt vmcnt(1)
	v_lshlrev_b32_e32 v52, 16, v44
	v_and_b32_e32 v53, 0xffff0000, v44
	v_mul_f32_e32 v40, 0x45800000, v56
	v_cndmask_b32_e32 v56, v56, v40, vcc
	v_mul_f32_e64 v28, v28, -v56
	v_mul_f32_e64 v29, v29, -v56
	v_mul_f32_e32 v28, 0x3fb8aa3b, v28
	v_mul_f32_e32 v29, 0x3fb8aa3b, v29
	v_mul_f32_e64 v30, v30, -v56
	v_mul_f32_e64 v31, v31, -v56
	v_exp_f32_e32 v28, v28
	v_exp_f32_e32 v29, v29
	v_mul_f32_e32 v30, 0x3fb8aa3b, v30
	v_mul_f32_e32 v31, 0x3fb8aa3b, v31
	v_exp_f32_e32 v30, v30
	v_exp_f32_e32 v31, v31
	v_pk_add_f32 v[28:29], v[28:29], 1.0 op_sel_hi:[1,0]
	v_lshlrev_b32_e32 v44, 16, v45
	v_pk_add_f32 v[30:31], v[30:31], 1.0 op_sel_hi:[1,0]
	v_rcp_f32_e32 v29, v29
	v_rcp_f32_e32 v28, v28
	v_rcp_f32_e32 v31, v31
	v_and_b32_e32 v45, 0xffff0000, v45
	v_lshlrev_b32_e32 v40, 16, v41
	v_and_b32_e32 v41, 0xffff0000, v41
	v_rcp_f32_e32 v30, v30
	v_pk_fma_f32 v[28:29], v[28:29], v[52:53], v[54:55]
	v_pk_fma_f32 v[30:31], v[30:31], v[44:45], v[40:41]
	v_cvt_pk_bf16_f32 v52, v28, v29
	v_cvt_pk_bf16_f32 v53, v30, v31
	global_store_dwordx2 v[42:43], v[52:53], off
	global_load_dwordx2 v[40:41], v[46:47], off
	v_mul_f32_e64 v24, v24, -v56
	v_mul_f32_e64 v25, v25, -v56
	s_waitcnt vmcnt(2)
	v_lshlrev_b32_e32 v46, 16, v50
	v_and_b32_e32 v47, 0xffff0000, v50
	v_mul_f32_e64 v50, v20, -v56
	v_mul_f32_e32 v20, 0x3fb8aa3b, v24
	v_mul_f32_e32 v25, 0x3fb8aa3b, v25
	v_mul_f32_e64 v26, v26, -v56
	v_mul_f32_e64 v27, v27, -v56
	v_exp_f32_e32 v24, v20
	v_exp_f32_e32 v25, v25
	v_mul_f32_e32 v26, 0x3fb8aa3b, v26
	v_mul_f32_e32 v27, 0x3fb8aa3b, v27
	v_exp_f32_e32 v26, v26
	v_exp_f32_e32 v27, v27
	v_pk_add_f32 v[24:25], v[24:25], 1.0 op_sel_hi:[1,0]
	v_mul_f32_e64 v52, v22, -v56
	v_lshl_add_u64 v[42:43], s[28:29], 0, v[48:49]
	v_lshlrev_b32_e32 v48, 16, v51
	v_and_b32_e32 v49, 0xffff0000, v51
	v_mul_f32_e64 v51, v21, -v56
	v_pk_add_f32 v[20:21], v[26:27], 1.0 op_sel_hi:[1,0]
	v_rcp_f32_e32 v25, v25
	v_rcp_f32_e32 v24, v24
	v_rcp_f32_e32 v21, v21
	v_rcp_f32_e32 v20, v20
	v_lshl_add_u64 v[44:45], s[18:19], 0, v[38:39]
	v_mul_f32_e64 v16, v16, -v56
	s_waitcnt vmcnt(0)
	v_lshlrev_b32_e32 v26, 16, v40
	v_and_b32_e32 v27, 0xffff0000, v40
	v_lshlrev_b32_e32 v40, 16, v41
	v_and_b32_e32 v41, 0xffff0000, v41
	v_pk_fma_f32 v[20:21], v[20:21], v[48:49], v[40:41]
	v_pk_fma_f32 v[24:25], v[24:25], v[46:47], v[26:27]
	v_cvt_pk_bf16_f32 v27, v20, v21
	v_cvt_pk_bf16_f32 v26, v24, v25
	global_store_dwordx2 v[42:43], v[26:27], off
	global_load_dwordx2 v[26:27], v[36:37], off offset:256
	v_mul_f32_e64 v40, v23, -v56
	global_load_dwordx2 v[22:23], v[44:45], off
	v_mul_f32_e32 v41, 0x3fb8aa3b, v50
	v_mul_f32_e32 v46, 0x3fb8aa3b, v51
	v_mul_f32_e32 v42, 0x3fb8aa3b, v52
	v_mul_f32_e32 v43, 0x3fb8aa3b, v40
	v_exp_f32_e32 v40, v41
	v_exp_f32_e32 v42, v42
	v_exp_f32_e32 v43, v43
	v_exp_f32_e32 v41, v46
	v_mul_f32_e32 v25, v25, v25
	v_fmac_f32_e32 v25, v24, v24
	v_pk_add_f32 v[42:43], v[42:43], 1.0 op_sel_hi:[1,0]
	v_pk_add_f32 v[40:41], v[40:41], 1.0 op_sel_hi:[1,0]
	v_mul_f32_e32 v48, v29, v29
	v_fmac_f32_e32 v48, v28, v28
	v_rcp_f32_e32 v29, v41
	v_fmac_f32_e32 v48, v30, v30
	v_fmac_f32_e32 v25, v20, v20
	v_fmac_f32_e32 v48, v31, v31
	v_rcp_f32_e32 v31, v43
	v_fmac_f32_e32 v25, v21, v21
	v_rcp_f32_e32 v28, v40
	v_rcp_f32_e32 v30, v42
	v_add_f32_e32 v40, v48, v25
	v_mul_f32_e64 v17, v17, -v56
	v_mul_f32_e32 v16, 0x3fb8aa3b, v16
	v_mul_f32_e32 v17, 0x3fb8aa3b, v17
	s_waitcnt vmcnt(1)
	v_lshlrev_b32_e32 v20, 16, v26
	v_and_b32_e32 v21, 0xffff0000, v26
	v_lshlrev_b32_e32 v24, 16, v27
	v_and_b32_e32 v25, 0xffff0000, v27
	s_waitcnt vmcnt(0)
	v_lshlrev_b32_e32 v26, 16, v22
	v_and_b32_e32 v27, 0xffff0000, v22
	v_lshlrev_b32_e32 v22, 16, v23
	v_and_b32_e32 v23, 0xffff0000, v23
	v_pk_fma_f32 v[22:23], v[30:31], v[24:25], v[22:23]
	v_pk_fma_f32 v[20:21], v[28:29], v[20:21], v[26:27]
	v_cvt_pk_bf16_f32 v25, v22, v23
	v_cvt_pk_bf16_f32 v24, v20, v21
	v_lshl_add_u64 v[26:27], s[28:29], 0, v[38:39]
	global_store_dwordx2 v[26:27], v[24:25], off
	v_lshl_add_u64 v[26:27], v[34:35], 0, v[116:117]
	v_lshlrev_b64 v[26:27], 1, v[26:27]
	v_lshl_add_u64 v[28:29], s[18:19], 0, v[26:27]
	global_load_dwordx2 v[24:25], v[36:37], off offset:288
	v_exp_f32_e32 v16, v16
	global_load_dwordx2 v[28:29], v[28:29], off
	v_exp_f32_e32 v17, v17
	v_mul_f32_e32 v21, v21, v21
	v_fmac_f32_e32 v21, v20, v20
	v_fmac_f32_e32 v21, v22, v22
	v_pk_add_f32 v[16:17], v[16:17], 1.0 op_sel_hi:[1,0]
	v_fmac_f32_e32 v21, v23, v23
	v_add_f32_e32 v30, v21, v40
	v_mul_f32_e64 v18, v18, -v56
	v_mul_f32_e64 v19, v19, -v56
	v_mul_f32_e32 v18, 0x3fb8aa3b, v18
	v_mul_f32_e32 v19, 0x3fb8aa3b, v19
	v_exp_f32_e32 v18, v18
	v_exp_f32_e32 v19, v19
	v_rcp_f32_e32 v17, v17
	v_pk_add_f32 v[18:19], v[18:19], 1.0 op_sel_hi:[1,0]
	v_rcp_f32_e32 v16, v16
	v_rcp_f32_e32 v19, v19
	v_rcp_f32_e32 v18, v18
	s_waitcnt vmcnt(1)
	v_lshlrev_b32_e32 v20, 16, v24
	v_and_b32_e32 v21, 0xffff0000, v24
	v_lshlrev_b32_e32 v22, 16, v25
	v_and_b32_e32 v23, 0xffff0000, v25
	s_waitcnt vmcnt(0)
	v_lshlrev_b32_e32 v24, 16, v28
	v_and_b32_e32 v25, 0xffff0000, v28
	v_pk_fma_f32 v[20:21], v[16:17], v[20:21], v[24:25]
	v_lshlrev_b32_e32 v28, 16, v29
	v_and_b32_e32 v29, 0xffff0000, v29
	v_mul_f32_e32 v16, v21, v21
	v_pk_fma_f32 v[18:19], v[18:19], v[22:23], v[28:29]
	v_fmac_f32_e32 v16, v20, v20
	v_fmac_f32_e32 v16, v18, v18
	v_fmac_f32_e32 v16, v19, v19
	v_add_f32_e32 v16, v30, v16
	ds_bpermute_b32 v17, v124, v16
	v_cvt_pk_bf16_f32 v20, v20, v21
	v_cvt_pk_bf16_f32 v21, v18, v19
	v_lshl_add_u64 v[18:19], s[28:29], 0, v[26:27]
	global_store_dwordx2 v[18:19], v[20:21], off
	s_waitcnt lgkmcnt(0)
	v_add_f32_e32 v16, v16, v17
	ds_bpermute_b32 v17, v125, v16
	s_and_saveexec_b64 s[0:1], s[6:7]
	s_cbranch_execz .LBB0_2386
; DI unsigned cvtpk(float lo, float hi) { f32x2_t v = {lo, hi}; bf16x2_t b = __builtin_convertvector(v, bf16x2_t); return __builtin_bit_cast(unsigned, b); }
;   DI void operator()(const f32x4 (&acc)[2][2][4][2], const pg8::Unit& u, int wr, int wc, int fr, int fq) const {
;     ...
;       for (int m = 0; m < 4; ++m) {
;         const int row = u.pm * 256 + ai * 128 + wr * 64 + m * 16 + fr; float rs = 0.f;
;         const float rstd = rsqrtf(ssx[row] * (1.f / DM) + EPS);
; #pragma unroll
;         for (int bj = 0; bj < 2; ++bj)
; #pragma unroll
;           for (int n = 0; n < 2; ++n) {
;             const int col = u.pn * 256 + bj * 128 + wc * 32 + n * 16 + fq * 4; const size_t off = (size_t)row * DM + col;
;             f32x4 g;
; #pragma unroll
;             for (int j = 0; j < 4; ++j) g[j] = 1.f / (1.f + __expf(-rstd * acc[ai][bj][m][n][j]));
;             const u32x2 pw = *(const u32x2*)(PT + off); f32x4 pp; pp.x = __uint_as_float(pw.x << 16); pp.y = __uint_as_float(pw.x & 0xffff0000u); pp.z = __uint_as_float(pw.y << 16); pp.w = __uint_as_float(pw.y & 0xffff0000u);
;             const u32x2 xw = *(const u32x2*)(X1B + off); f32x4 x1; x1.x = __uint_as_float(xw.x << 16); x1.y = __uint_as_float(xw.x & 0xffff0000u); x1.z = __uint_as_float(xw.y << 16); x1.w = __uint_as_float(xw.y & 0xffff0000u);
;             const f32x4 xn = x1 + pp * g;
;             if (layer != 0) *(f32x4*)(out + off) = xn;
;             if (layer == 0) {
;               rs += xn.x * xn.x + xn.y * xn.y + xn.z * xn.z + xn.w * xn.w;
;               u32x2 w; w.x = cvtpk(xn.x, xn.y); w.y = cvtpk(xn.z, xn.w); *(u32x2*)(H + off) = w;
;             }
;           }
;         if (layer == 0) { rs += __shfl_xor(rs, 16); rs += __shfl_xor(rs, 32); if (fq == 0) atomicAdd(ss1 + row, rs); }
	s_waitcnt lgkmcnt(0)
	v_add_f32_e32 v18, v16, v17
	v_lshl_add_u64 v[16:17], v[32:33], 2, s[22:23]
	global_atomic_add_f32 v[16:17], v18, off
.LBB0_2386:
	s_or_b64 exec, exec, s[0:1]
	v_add_u32_e32 v16, 0xb0, v146
	s_waitcnt lgkmcnt(0)
	v_ashrrev_i32_e32 v17, 31, v16
	v_lshl_add_u64 v[18:19], v[16:17], 2, s[24:25]
	global_load_dword v36, v[18:19], off
	v_lshlrev_b64 v[18:19], 10, v[16:17]
	v_lshl_add_u64 v[20:21], v[18:19], 0, v[140:141]
	v_lshlrev_b64 v[26:27], 1, v[20:21]
	v_lshl_add_u64 v[22:23], s[18:19], 0, v[26:27]
	global_load_dwordx2 v[24:25], v[22:23], off
	v_lshl_add_u64 v[20:21], s[16:17], 0, v[26:27]
	global_load_dwordx2 v[28:29], v[20:21], off
	global_load_dwordx2 v[34:35], v[20:21], off offset:32
	v_lshl_add_u64 v[22:23], v[18:19], 0, v[142:143]
	v_lshl_add_u64 v[30:31], v[18:19], 0, v[144:145]
	v_lshlrev_b64 v[32:33], 1, v[22:23]
	v_lshl_add_u64 v[26:27], s[28:29], 0, v[26:27]
	v_lshlrev_b64 v[22:23], 1, v[30:31]
	v_lshl_add_u64 v[30:31], s[18:19], 0, v[32:33]
	s_waitcnt vmcnt(3)
	v_fmamk_f32 v36, v36, 0x3a800000, v158
	v_mul_f32_e32 v37, 0x4b800000, v36
	v_cmp_gt_f32_e32 vcc, s54, v36
	s_waitcnt vmcnt(2)
	v_lshlrev_b32_e32 v38, 16, v24
	v_cndmask_b32_e32 v36, v36, v37, vcc
	v_rsq_f32_e32 v40, v36
	v_and_b32_e32 v39, 0xffff0000, v24
	s_waitcnt vmcnt(1)
	v_lshlrev_b32_e32 v36, 16, v28
	v_and_b32_e32 v37, 0xffff0000, v28
	v_mul_f32_e32 v24, 0x45800000, v40
	v_cndmask_b32_e32 v40, v40, v24, vcc
	v_mul_f32_e64 v12, v12, -v40
	v_mul_f32_e64 v13, v13, -v40
	v_mul_f32_e32 v12, 0x3fb8aa3b, v12
	v_mul_f32_e32 v13, 0x3fb8aa3b, v13
	v_mul_f32_e64 v14, v14, -v40
	v_mul_f32_e64 v15, v15, -v40
	v_exp_f32_e32 v12, v12
	v_exp_f32_e32 v13, v13
	v_mul_f32_e32 v14, 0x3fb8aa3b, v14
	v_mul_f32_e32 v15, 0x3fb8aa3b, v15
	v_exp_f32_e32 v14, v14
	v_exp_f32_e32 v15, v15
	v_pk_add_f32 v[12:13], v[12:13], 1.0 op_sel_hi:[1,0]
	v_lshlrev_b32_e32 v28, 16, v29
	v_pk_add_f32 v[14:15], v[14:15], 1.0 op_sel_hi:[1,0]
	v_rcp_f32_e32 v13, v13
	v_rcp_f32_e32 v12, v12
	v_rcp_f32_e32 v15, v15
	v_and_b32_e32 v29, 0xffff0000, v29
	v_lshlrev_b32_e32 v24, 16, v25
	v_and_b32_e32 v25, 0xffff0000, v25
	v_rcp_f32_e32 v14, v14
	v_pk_fma_f32 v[12:13], v[12:13], v[36:37], v[38:39]
	v_pk_fma_f32 v[14:15], v[14:15], v[28:29], v[24:25]
	v_cvt_pk_bf16_f32 v36, v12, v13
	v_cvt_pk_bf16_f32 v37, v14, v15
	global_store_dwordx2 v[26:27], v[36:37], off
	global_load_dwordx2 v[24:25], v[30:31], off
	v_mul_f32_e64 v8, v8, -v40
	v_mul_f32_e64 v9, v9, -v40
	s_waitcnt vmcnt(2)
	v_lshlrev_b32_e32 v30, 16, v34
	v_and_b32_e32 v31, 0xffff0000, v34
	v_mul_f32_e64 v34, v4, -v40
	v_mul_f32_e32 v4, 0x3fb8aa3b, v8
	v_mul_f32_e32 v9, 0x3fb8aa3b, v9
	v_mul_f32_e64 v10, v10, -v40
	v_mul_f32_e64 v11, v11, -v40
	v_exp_f32_e32 v8, v4
	v_exp_f32_e32 v9, v9
	v_mul_f32_e32 v10, 0x3fb8aa3b, v10
	v_mul_f32_e32 v11, 0x3fb8aa3b, v11
	v_exp_f32_e32 v10, v10
	v_exp_f32_e32 v11, v11
	v_pk_add_f32 v[8:9], v[8:9], 1.0 op_sel_hi:[1,0]
	v_mul_f32_e64 v36, v6, -v40
	v_lshl_add_u64 v[26:27], s[28:29], 0, v[32:33]
	v_lshlrev_b32_e32 v32, 16, v35
	v_and_b32_e32 v33, 0xffff0000, v35
	v_mul_f32_e64 v35, v5, -v40
	v_pk_add_f32 v[4:5], v[10:11], 1.0 op_sel_hi:[1,0]
	v_rcp_f32_e32 v9, v9
	v_rcp_f32_e32 v8, v8
	v_rcp_f32_e32 v5, v5
	v_rcp_f32_e32 v4, v4
	v_lshl_add_u64 v[28:29], s[18:19], 0, v[22:23]
	v_mul_f32_e64 v0, v0, -v40
	s_waitcnt vmcnt(0)
	v_lshlrev_b32_e32 v10, 16, v24
	v_and_b32_e32 v11, 0xffff0000, v24
	v_lshlrev_b32_e32 v24, 16, v25
	v_and_b32_e32 v25, 0xffff0000, v25
	v_pk_fma_f32 v[4:5], v[4:5], v[32:33], v[24:25]
	v_pk_fma_f32 v[8:9], v[8:9], v[30:31], v[10:11]
	v_cvt_pk_bf16_f32 v11, v4, v5
	v_cvt_pk_bf16_f32 v10, v8, v9
	global_store_dwordx2 v[26:27], v[10:11], off
	global_load_dwordx2 v[10:11], v[20:21], off offset:256
	v_mul_f32_e64 v24, v7, -v40
	global_load_dwordx2 v[6:7], v[28:29], off
	v_mul_f32_e32 v25, 0x3fb8aa3b, v34
	v_mul_f32_e32 v30, 0x3fb8aa3b, v35
	v_mul_f32_e32 v26, 0x3fb8aa3b, v36
	v_mul_f32_e32 v27, 0x3fb8aa3b, v24
	v_exp_f32_e32 v24, v25
	v_exp_f32_e32 v26, v26
	v_exp_f32_e32 v27, v27
	v_exp_f32_e32 v25, v30
	v_mul_f32_e32 v9, v9, v9
	v_fmac_f32_e32 v9, v8, v8
	v_pk_add_f32 v[26:27], v[26:27], 1.0 op_sel_hi:[1,0]
	v_pk_add_f32 v[24:25], v[24:25], 1.0 op_sel_hi:[1,0]
	v_mul_f32_e32 v32, v13, v13
	v_fmac_f32_e32 v32, v12, v12
	v_rcp_f32_e32 v13, v25
	v_fmac_f32_e32 v32, v14, v14
	v_fmac_f32_e32 v9, v4, v4
	v_fmac_f32_e32 v32, v15, v15
	v_rcp_f32_e32 v15, v27
	v_fmac_f32_e32 v9, v5, v5
	v_rcp_f32_e32 v12, v24
	v_rcp_f32_e32 v14, v26
	v_add_f32_e32 v24, v32, v9
	v_mul_f32_e64 v1, v1, -v40
	v_mul_f32_e32 v0, 0x3fb8aa3b, v0
	v_mul_f32_e32 v1, 0x3fb8aa3b, v1
	s_waitcnt vmcnt(1)
	v_lshlrev_b32_e32 v4, 16, v10
	v_and_b32_e32 v5, 0xffff0000, v10
	v_lshlrev_b32_e32 v8, 16, v11
	v_and_b32_e32 v9, 0xffff0000, v11
	s_waitcnt vmcnt(0)
	v_lshlrev_b32_e32 v10, 16, v6
	v_and_b32_e32 v11, 0xffff0000, v6
	v_lshlrev_b32_e32 v6, 16, v7
	v_and_b32_e32 v7, 0xffff0000, v7
	v_pk_fma_f32 v[6:7], v[14:15], v[8:9], v[6:7]
	v_pk_fma_f32 v[4:5], v[12:13], v[4:5], v[10:11]
	v_cvt_pk_bf16_f32 v9, v6, v7
	v_cvt_pk_bf16_f32 v8, v4, v5
	v_lshl_add_u64 v[10:11], s[28:29], 0, v[22:23]
	global_store_dwordx2 v[10:11], v[8:9], off
	v_lshl_add_u64 v[10:11], v[18:19], 0, v[116:117]
	v_lshlrev_b64 v[10:11], 1, v[10:11]
	v_lshl_add_u64 v[12:13], s[18:19], 0, v[10:11]
	global_load_dwordx2 v[8:9], v[20:21], off offset:288
	v_exp_f32_e32 v0, v0
	global_load_dwordx2 v[12:13], v[12:13], off
	v_exp_f32_e32 v1, v1
	v_mul_f32_e32 v5, v5, v5
	v_fmac_f32_e32 v5, v4, v4
	v_fmac_f32_e32 v5, v6, v6
	v_pk_add_f32 v[0:1], v[0:1], 1.0 op_sel_hi:[1,0]
	v_fmac_f32_e32 v5, v7, v7
	v_add_f32_e32 v14, v5, v24
	v_mul_f32_e64 v2, v2, -v40
	v_mul_f32_e64 v3, v3, -v40
	v_mul_f32_e32 v2, 0x3fb8aa3b, v2
	v_mul_f32_e32 v3, 0x3fb8aa3b, v3
	v_exp_f32_e32 v2, v2
	v_exp_f32_e32 v3, v3
	v_rcp_f32_e32 v1, v1
	v_pk_add_f32 v[2:3], v[2:3], 1.0 op_sel_hi:[1,0]
	v_rcp_f32_e32 v0, v0
	v_rcp_f32_e32 v3, v3
	v_rcp_f32_e32 v2, v2
	s_waitcnt vmcnt(1)
	v_lshlrev_b32_e32 v4, 16, v8
	v_and_b32_e32 v5, 0xffff0000, v8
	v_lshlrev_b32_e32 v6, 16, v9
	v_and_b32_e32 v7, 0xffff0000, v9
	s_waitcnt vmcnt(0)
	v_lshlrev_b32_e32 v8, 16, v12
	v_and_b32_e32 v9, 0xffff0000, v12
	v_pk_fma_f32 v[4:5], v[0:1], v[4:5], v[8:9]
	v_lshlrev_b32_e32 v12, 16, v13
	v_and_b32_e32 v13, 0xffff0000, v13
	v_mul_f32_e32 v0, v5, v5
	v_pk_fma_f32 v[2:3], v[2:3], v[6:7], v[12:13]
	v_fmac_f32_e32 v0, v4, v4
	v_fmac_f32_e32 v0, v2, v2
	v_fmac_f32_e32 v0, v3, v3
	v_add_f32_e32 v0, v14, v0
	ds_bpermute_b32 v1, v124, v0
	v_cvt_pk_bf16_f32 v4, v4, v5
	v_cvt_pk_bf16_f32 v5, v2, v3
	v_lshl_add_u64 v[2:3], s[28:29], 0, v[10:11]
	global_store_dwordx2 v[2:3], v[4:5], off
	s_waitcnt lgkmcnt(0)
	v_add_f32_e32 v0, v0, v1
	ds_bpermute_b32 v1, v125, v0
	s_and_saveexec_b64 s[0:1], s[6:7]
	s_cbranch_execz .LBB0_2388
	s_waitcnt lgkmcnt(0)
	v_add_f32_e32 v2, v0, v1
	v_lshl_add_u64 v[0:1], v[16:17], 2, s[22:23]
	global_atomic_add_f32 v[0:1], v2, off

; __device__ __forceinline__ unsigned xb_add(unsigned* p, unsigned v) { return __hip_atomic_fetch_add(p, v, __ATOMIC_RELAXED, __HIP_MEMORY_SCOPE_AGENT); }
; __device__ __forceinline__ void xcd_barrier(const XcdBarrier& b) {
;     ...
;             __builtin_amdgcn_fence(__ATOMIC_ACQUIRE, "agent");
;             xb_add(&bar[XB_XGEN(b.x)], 1u);
;             asm volatile("s_waitcnt vmcnt(0)" ::: "memory");
.LBB0_2573:
	s_or_b64 exec, exec, s[6:7]
	s_mov_b64 s[6:7], exec
	v_mbcnt_lo_u32_b32 v0, s6, 0
	v_mbcnt_hi_u32_b32 v0, s7, v0
	v_cmp_eq_u32_e32 vcc, 0, v0
	s_waitcnt vmcnt(0)
	buffer_inv sc1
	s_and_saveexec_b64 s[8:9], vcc
	s_cbranch_execz .LBB0_2575
	s_bcnt1_i32_b64 s6, s[6:7]
	v_mov_b32_e32 v0, 0x2000
	v_mov_b32_e32 v1, s6
	global_atomic_add v0, v1, s[2:3] offset:1024
	s_nop 0
	s_nop 0
	s_nop 0
	s_nop 0
	s_nop 0
	s_nop 0
	s_nop 0
	s_nop 0
	s_nop 0
	s_nop 0
	s_nop 0
	s_nop 0
	s_nop 0
	s_nop 0
	s_nop 0
	s_nop 0
	s_nop 0
	s_nop 0
	s_nop 0
	s_nop 0
	s_nop 0
	s_nop 0
	s_nop 0
	s_nop 0
	s_nop 0
	s_nop 0
	s_nop 0
	s_nop 0
	s_nop 0
	s_nop 0
	s_nop 0
	s_nop 0
	s_nop 0
	s_nop 0
	s_nop 0
	s_nop 0
	s_nop 0
	s_nop 0
	s_nop 0
	s_nop 0
	s_nop 0
	s_nop 0
	s_nop 0

;   DI void operator()(const f32x4 (&acc)[2][2][4][2], const pg8::Unit& u, int wr, int wc, int fr, int fq) const {
;     ...
;       for (int m = 0; m < 4; ++m) {
;         const int row = u.pm * 256 + ai * 128 + wr * 64 + m * 16 + fr; float rs = 0.f;
;         const float rstd = rsqrtf(ssx[row] * (1.f / DM) + EPS);
; #pragma unroll
;         for (int bj = 0; bj < 2; ++bj)
; #pragma unroll
;           for (int n = 0; n < 2; ++n) {
;             const int col = u.pn * 256 + bj * 128 + wc * 32 + n * 16 + fq * 4; const size_t off = (size_t)row * DM + col;
;             f32x4 g;
; #pragma unroll
;             for (int j = 0; j < 4; ++j) g[j] = 1.f / (1.f + __expf(-rstd * acc[ai][bj][m][n][j]));
;             const u32x2 pw = *(const u32x2*)(PT + off); f32x4 pp; pp.x = __uint_as_float(pw.x << 16); pp.y = __uint_as_float(pw.x & 0xffff0000u); pp.z = __uint_as_float(pw.y << 16); pp.w = __uint_as_float(pw.y & 0xffff0000u);
;             const u32x2 xw = *(const u32x2*)(X1B + off); f32x4 x1; x1.x = __uint_as_float(xw.x << 16); x1.y = __uint_as_float(xw.x & 0xffff0000u); x1.z = __uint_as_float(xw.y << 16); x1.w = __uint_as_float(xw.y & 0xffff0000u);
;             const f32x4 xn = x1 + pp * g;
;             if (layer != 0) *(f32x4*)(out + off) = xn;
.LBB0_2826:
	v_lshl_add_u32 v144, s2, 8, v152
	v_ashrrev_i32_e32 v145, 31, v144
	v_lshl_add_u64 v[140:141], v[144:145], 2, s[18:19]
	global_load_dword v159, v[140:141], off
	v_lshl_or_b32 v142, s45, 8, v154
	v_lshlrev_b64 v[146:147], 10, v[144:145]
	v_ashrrev_i32_e32 v143, 31, v142
	v_lshl_add_u64 v[148:149], v[146:147], 0, v[142:143]
	v_lshlrev_b64 v[140:141], 1, v[148:149]
	v_lshl_add_u64 v[150:151], s[10:11], 0, v[140:141]
	v_lshl_add_u64 v[140:141], s[12:13], 0, v[140:141]
	global_load_dwordx2 v[160:161], v[150:151], off
	global_load_dwordx2 v[162:163], v[140:141], off
	v_or_b32_e32 v140, 16, v142
	v_lshl_add_u64 v[148:149], v[148:149], 2, s[14:15]
	s_waitcnt vmcnt(0)
	v_fmamk_f32 v141, v159, 0x3a800000, v158
	v_mul_f32_e32 v145, 0x4b800000, v141
	v_cmp_gt_f32_e32 vcc, s44, v141
	v_lshlrev_b32_e32 v164, 16, v160
	s_nop 0
	v_cndmask_b32_e32 v141, v141, v145, vcc
	v_rsq_f32_e32 v141, v141
	v_and_b32_e32 v165, 0xffff0000, v160
	v_lshlrev_b32_e32 v160, 16, v161
	v_and_b32_e32 v161, 0xffff0000, v161
	v_mul_f32_e32 v145, 0x45800000, v141
	v_cndmask_b32_e32 v145, v141, v145, vcc
	v_mul_f32_e64 v124, v124, -v145
	v_mul_f32_e64 v125, v125, -v145
	v_mul_f32_e32 v124, 0x3fb8aa3b, v124
	v_mul_f32_e32 v125, 0x3fb8aa3b, v125
	v_mul_f32_e64 v126, v126, -v145
	v_mul_f32_e64 v127, v127, -v145
	v_exp_f32_e32 v124, v124
	v_exp_f32_e32 v125, v125
	v_mul_f32_e32 v126, 0x3fb8aa3b, v126
	v_mul_f32_e32 v127, 0x3fb8aa3b, v127
	v_exp_f32_e32 v126, v126
	v_exp_f32_e32 v127, v127
	v_pk_add_f32 v[124:125], v[124:125], 1.0 op_sel_hi:[1,0]
	v_lshlrev_b32_e32 v166, 16, v162
	v_pk_add_f32 v[126:127], v[126:127], 1.0 op_sel_hi:[1,0]
	v_rcp_f32_e32 v125, v125
	v_rcp_f32_e32 v124, v124
	v_rcp_f32_e32 v127, v127
	v_and_b32_e32 v167, 0xffff0000, v162
	v_lshlrev_b32_e32 v162, 16, v163
	v_and_b32_e32 v163, 0xffff0000, v163
	v_rcp_f32_e32 v126, v126
	v_pk_fma_f32 v[124:125], v[124:125], v[164:165], v[166:167]
	v_pk_fma_f32 v[126:127], v[126:127], v[160:161], v[162:163]
	v_ashrrev_i32_e32 v141, 31, v140
	global_store_dwordx4 v[148:149], v[124:127], off
	global_load_dwordx2 v[124:125], v[150:151], off offset:32
	v_mul_f32_e64 v120, v120, -v145
	v_lshl_add_u64 v[126:127], v[146:147], 0, v[140:141]
	v_lshl_add_u64 v[126:127], v[126:127], 1, s[12:13]
	global_load_dwordx2 v[126:127], v[126:127], off
	v_mul_f32_e64 v121, v121, -v145
	v_mul_f32_e64 v123, v123, -v145
	v_mul_f32_e64 v122, v122, -v145
	v_mul_f32_e32 v120, 0x3fb8aa3b, v120
	v_mul_f32_e32 v121, 0x3fb8aa3b, v121
	v_mul_f32_e32 v123, 0x3fb8aa3b, v123
	v_mul_f32_e32 v159, 0x3fb8aa3b, v122
	v_exp_f32_e32 v122, v120
	v_exp_f32_e32 v161, v123
	v_exp_f32_e32 v123, v121
	v_exp_f32_e32 v160, v159
	v_or_b32_e32 v120, 0x80, v142
	v_mul_f32_e64 v116, v116, -v145
	v_pk_add_f32 v[122:123], v[122:123], 1.0 op_sel_hi:[1,0]
	v_pk_add_f32 v[160:161], v[160:161], 1.0 op_sel_hi:[1,0]
	v_rcp_f32_e32 v123, v123
	v_rcp_f32_e32 v122, v122
	v_rcp_f32_e32 v161, v161
	v_rcp_f32_e32 v160, v160
	v_ashrrev_i32_e32 v121, 31, v120
	v_mul_f32_e64 v117, v117, -v145
	v_mul_f32_e64 v119, v119, -v145
	v_mul_f32_e64 v118, v118, -v145
	v_mul_f32_e32 v116, 0x3fb8aa3b, v116
	s_waitcnt vmcnt(1)
	v_lshlrev_b32_e32 v162, 16, v124
	v_and_b32_e32 v163, 0xffff0000, v124
	v_lshlrev_b32_e32 v124, 16, v125
	v_and_b32_e32 v125, 0xffff0000, v125
	s_waitcnt vmcnt(0)
	v_lshlrev_b32_e32 v164, 16, v126
	v_and_b32_e32 v165, 0xffff0000, v126
	v_lshlrev_b32_e32 v126, 16, v127
	v_and_b32_e32 v127, 0xffff0000, v127
	v_pk_fma_f32 v[124:125], v[160:161], v[124:125], v[126:127]
	v_pk_fma_f32 v[122:123], v[122:123], v[162:163], v[164:165]
	global_store_dwordx4 v[148:149], v[122:125], off offset:64
	global_load_dwordx2 v[122:123], v[150:151], off offset:256
	v_mul_f32_e32 v117, 0x3fb8aa3b, v117
	v_lshl_add_u64 v[124:125], v[146:147], 0, v[120:121]
	v_lshl_add_u64 v[124:125], v[124:125], 1, s[12:13]
	global_load_dwordx2 v[124:125], v[124:125], off
	v_mul_f32_e32 v119, 0x3fb8aa3b, v119
	v_mul_f32_e32 v126, 0x3fb8aa3b, v118
	v_exp_f32_e32 v118, v116
	v_exp_f32_e32 v127, v119
	v_exp_f32_e32 v119, v117
	v_exp_f32_e32 v126, v126
	v_or_b32_e32 v116, 0x90, v142
	v_mul_f32_e64 v112, v112, -v145
	v_pk_add_f32 v[118:119], v[118:119], 1.0 op_sel_hi:[1,0]
	v_pk_add_f32 v[126:127], v[126:127], 1.0 op_sel_hi:[1,0]
	v_rcp_f32_e32 v119, v119
	v_rcp_f32_e32 v118, v118
	v_rcp_f32_e32 v127, v127
	v_rcp_f32_e32 v126, v126
	v_ashrrev_i32_e32 v117, 31, v116
	v_mul_f32_e64 v113, v113, -v145
	v_mul_f32_e32 v112, 0x3fb8aa3b, v112
	v_mul_f32_e32 v113, 0x3fb8aa3b, v113
	v_mul_f32_e64 v114, v114, -v145
	v_mul_f32_e64 v115, v115, -v145
	v_exp_f32_e32 v112, v112
	v_exp_f32_e32 v113, v113
	v_mul_f32_e32 v114, 0x3fb8aa3b, v114
	v_mul_f32_e32 v115, 0x3fb8aa3b, v115
	s_waitcnt vmcnt(1)
	v_lshlrev_b32_e32 v160, 16, v122
	v_and_b32_e32 v161, 0xffff0000, v122
	v_lshlrev_b32_e32 v122, 16, v123
	v_and_b32_e32 v123, 0xffff0000, v123
	s_waitcnt vmcnt(0)
	v_lshlrev_b32_e32 v162, 16, v124
	v_and_b32_e32 v163, 0xffff0000, v124
	v_lshlrev_b32_e32 v124, 16, v125
	v_and_b32_e32 v125, 0xffff0000, v125
	v_pk_fma_f32 v[124:125], v[126:127], v[122:123], v[124:125]
	v_pk_fma_f32 v[122:123], v[118:119], v[160:161], v[162:163]
	global_store_dwordx4 v[148:149], v[122:125], off offset:512
	global_load_dwordx2 v[118:119], v[150:151], off offset:288
	v_exp_f32_e32 v114, v114
	v_lshl_add_u64 v[122:123], v[146:147], 0, v[116:117]
	v_lshl_add_u64 v[122:123], v[122:123], 1, s[12:13]
	global_load_dwordx2 v[122:123], v[122:123], off
	v_exp_f32_e32 v115, v115
	v_pk_add_f32 v[112:113], v[112:113], 1.0 op_sel_hi:[1,0]
	v_or_b32_e32 v124, 16, v144
	v_pk_add_f32 v[114:115], v[114:115], 1.0 op_sel_hi:[1,0]
	v_rcp_f32_e32 v113, v113
	v_rcp_f32_e32 v112, v112
	v_rcp_f32_e32 v115, v115
	v_rcp_f32_e32 v114, v114
	v_ashrrev_i32_e32 v125, 31, v124
	v_lshl_add_u64 v[126:127], v[124:125], 2, s[18:19]
	s_waitcnt vmcnt(1)
;   DI void operator()(const f32x4 (&acc)[2][2][4][2], const pg8::Unit& u, int wr, int wc, int fr, int fq) const {
;     ...
;       for (int m = 0; m < 4; ++m) {
;         const int row = u.pm * 256 + ai * 128 + wr * 64 + m * 16 + fr; float rs = 0.f;
;         const float rstd = rsqrtf(ssx[row] * (1.f / DM) + EPS);
; #pragma unroll
;         for (int bj = 0; bj < 2; ++bj)
; #pragma unroll
;           for (int n = 0; n < 2; ++n) {
;             const int col = u.pn * 256 + bj * 128 + wc * 32 + n * 16 + fq * 4; const size_t off = (size_t)row * DM + col;
;             f32x4 g;
; #pragma unroll
;             for (int j = 0; j < 4; ++j) g[j] = 1.f / (1.f + __expf(-rstd * acc[ai][bj][m][n][j]));
;             const u32x2 pw = *(const u32x2*)(PT + off); f32x4 pp; pp.x = __uint_as_float(pw.x << 16); pp.y = __uint_as_float(pw.x & 0xffff0000u); pp.z = __uint_as_float(pw.y << 16); pp.w = __uint_as_float(pw.y & 0xffff0000u);
;             const u32x2 xw = *(const u32x2*)(X1B + off); f32x4 x1; x1.x = __uint_as_float(xw.x << 16); x1.y = __uint_as_float(xw.x & 0xffff0000u); x1.z = __uint_as_float(xw.y << 16); x1.w = __uint_as_float(xw.y & 0xffff0000u);
;             const f32x4 xn = x1 + pp * g;
;             if (layer != 0) *(f32x4*)(out + off) = xn;
	v_lshlrev_b32_e32 v146, 16, v118
	v_and_b32_e32 v147, 0xffff0000, v118
	v_lshlrev_b32_e32 v118, 16, v119
	v_and_b32_e32 v119, 0xffff0000, v119
	s_waitcnt vmcnt(0)
	v_lshlrev_b32_e32 v150, 16, v122
	v_and_b32_e32 v151, 0xffff0000, v122
	v_lshlrev_b32_e32 v122, 16, v123
	v_and_b32_e32 v123, 0xffff0000, v123
	v_pk_fma_f32 v[114:115], v[114:115], v[118:119], v[122:123]
	v_pk_fma_f32 v[112:113], v[112:113], v[146:147], v[150:151]
	global_store_dwordx4 v[148:149], v[112:115], off offset:576
	s_nop 1
	v_lshlrev_b64 v[114:115], 10, v[124:125]
	v_lshl_add_u64 v[112:113], v[114:115], 0, v[142:143]
	v_lshlrev_b64 v[122:123], 1, v[112:113]
	v_lshl_add_u64 v[118:119], s[10:11], 0, v[122:123]
	global_load_dword v126, v[126:127], off
	s_nop 0
	global_load_dwordx2 v[124:125], v[118:119], off
	v_lshl_add_u64 v[122:123], s[12:13], 0, v[122:123]
	global_load_dwordx2 v[122:123], v[122:123], off
	v_lshl_add_u64 v[112:113], v[112:113], 2, s[14:15]
	s_waitcnt vmcnt(2)
	v_fmamk_f32 v145, v126, 0x3a800000, v158
	v_mul_f32_e32 v146, 0x4b800000, v145
	v_cmp_gt_f32_e32 vcc, s44, v145
	s_waitcnt vmcnt(0)
	v_and_b32_e32 v147, 0xffff0000, v122
	v_lshlrev_b32_e32 v148, 16, v123
	v_cndmask_b32_e32 v145, v145, v146, vcc
	v_rsq_f32_e32 v145, v145
	v_lshlrev_b32_e32 v146, 16, v122
	v_and_b32_e32 v149, 0xffff0000, v123
	v_lshlrev_b32_e32 v126, 16, v124
	v_mul_f32_e32 v122, 0x45800000, v145
	v_cndmask_b32_e32 v122, v145, v122, vcc
	v_mul_f32_e64 v108, v108, -v122
	v_mul_f32_e64 v109, v109, -v122
	v_mul_f32_e32 v108, 0x3fb8aa3b, v108
	v_mul_f32_e32 v109, 0x3fb8aa3b, v109
	v_mul_f32_e64 v110, v110, -v122
	v_mul_f32_e64 v111, v111, -v122
	v_exp_f32_e32 v108, v108
	v_exp_f32_e32 v109, v109
	v_mul_f32_e32 v110, 0x3fb8aa3b, v110
	v_mul_f32_e32 v111, 0x3fb8aa3b, v111
	v_exp_f32_e32 v110, v110
	v_exp_f32_e32 v111, v111
	v_pk_add_f32 v[108:109], v[108:109], 1.0 op_sel_hi:[1,0]
	v_and_b32_e32 v127, 0xffff0000, v124
	v_pk_add_f32 v[110:111], v[110:111], 1.0 op_sel_hi:[1,0]
	v_rcp_f32_e32 v109, v109
	v_rcp_f32_e32 v108, v108
	v_rcp_f32_e32 v111, v111
	v_lshlrev_b32_e32 v124, 16, v125
	v_and_b32_e32 v125, 0xffff0000, v125
	v_rcp_f32_e32 v110, v110
	v_pk_fma_f32 v[108:109], v[108:109], v[126:127], v[146:147]
	v_pk_fma_f32 v[110:111], v[110:111], v[124:125], v[148:149]
	global_store_dwordx4 v[112:113], v[108:111], off
	global_load_dwordx2 v[108:109], v[118:119], off offset:32
	v_mul_f32_e64 v104, v104, -v122
	v_lshl_add_u64 v[110:111], v[114:115], 0, v[140:141]
	v_lshl_add_u64 v[110:111], v[110:111], 1, s[12:13]
	global_load_dwordx2 v[110:111], v[110:111], off
	v_mul_f32_e64 v105, v105, -v122
	v_mul_f32_e32 v104, 0x3fb8aa3b, v104
	v_mul_f32_e32 v105, 0x3fb8aa3b, v105
	v_mul_f32_e64 v106, v106, -v122
	v_mul_f32_e64 v107, v107, -v122
	v_exp_f32_e32 v104, v104
	v_exp_f32_e32 v105, v105
	v_mul_f32_e32 v106, 0x3fb8aa3b, v106
	v_mul_f32_e32 v107, 0x3fb8aa3b, v107
	v_exp_f32_e32 v106, v106
	v_exp_f32_e32 v107, v107
	v_pk_add_f32 v[104:105], v[104:105], 1.0 op_sel_hi:[1,0]
	v_mul_f32_e64 v100, v100, -v122
	v_pk_add_f32 v[106:107], v[106:107], 1.0 op_sel_hi:[1,0]
	v_rcp_f32_e32 v105, v105
	v_rcp_f32_e32 v104, v104
	v_rcp_f32_e32 v107, v107
	v_rcp_f32_e32 v106, v106
	v_mul_f32_e64 v101, v101, -v122
	v_mul_f32_e32 v100, 0x3fb8aa3b, v100
	v_mul_f32_e32 v101, 0x3fb8aa3b, v101
	v_mul_f32_e64 v102, v102, -v122
	v_mul_f32_e64 v103, v103, -v122
	v_exp_f32_e32 v100, v100
	s_waitcnt vmcnt(1)
	v_lshlrev_b32_e32 v124, 16, v108
	v_and_b32_e32 v125, 0xffff0000, v108
	v_lshlrev_b32_e32 v108, 16, v109
	v_and_b32_e32 v109, 0xffff0000, v109
	s_waitcnt vmcnt(0)
	v_lshlrev_b32_e32 v126, 16, v110
	v_and_b32_e32 v127, 0xffff0000, v110
	v_lshlrev_b32_e32 v110, 16, v111
	v_and_b32_e32 v111, 0xffff0000, v111
	v_pk_fma_f32 v[106:107], v[106:107], v[108:109], v[110:111]
	v_pk_fma_f32 v[104:105], v[104:105], v[124:125], v[126:127]
	global_store_dwordx4 v[112:113], v[104:107], off offset:64
	global_load_dwordx2 v[104:105], v[118:119], off offset:256
	v_exp_f32_e32 v101, v101
	v_lshl_add_u64 v[106:107], v[114:115], 0, v[120:121]
	v_lshl_add_u64 v[106:107], v[106:107], 1, s[12:13]
	global_load_dwordx2 v[106:107], v[106:107], off
	v_mul_f32_e32 v102, 0x3fb8aa3b, v102
	v_mul_f32_e32 v103, 0x3fb8aa3b, v103
	v_exp_f32_e32 v102, v102
	v_exp_f32_e32 v103, v103
	v_pk_add_f32 v[100:101], v[100:101], 1.0 op_sel_hi:[1,0]
	v_mul_f32_e64 v96, v96, -v122
	v_pk_add_f32 v[102:103], v[102:103], 1.0 op_sel_hi:[1,0]
	v_rcp_f32_e32 v101, v101
	v_rcp_f32_e32 v100, v100
	v_rcp_f32_e32 v103, v103
	v_rcp_f32_e32 v102, v102
	v_mul_f32_e64 v97, v97, -v122
	v_mul_f32_e32 v96, 0x3fb8aa3b, v96
	v_mul_f32_e32 v97, 0x3fb8aa3b, v97
	v_mul_f32_e64 v98, v98, -v122
	v_mul_f32_e64 v99, v99, -v122
	v_exp_f32_e32 v96, v96
	v_exp_f32_e32 v97, v97
	v_mul_f32_e32 v98, 0x3fb8aa3b, v98
	v_mul_f32_e32 v99, 0x3fb8aa3b, v99
	v_or_b32_e32 v108, 32, v144
	v_pk_add_f32 v[96:97], v[96:97], 1.0 op_sel_hi:[1,0]
	v_ashrrev_i32_e32 v109, 31, v108
	s_waitcnt vmcnt(1)
	v_lshlrev_b32_e32 v110, 16, v104
	v_and_b32_e32 v111, 0xffff0000, v104
	v_lshlrev_b32_e32 v104, 16, v105
	v_and_b32_e32 v105, 0xffff0000, v105
	s_waitcnt vmcnt(0)
	v_lshlrev_b32_e32 v124, 16, v106
	v_and_b32_e32 v125, 0xffff0000, v106
	v_lshlrev_b32_e32 v106, 16, v107
	v_and_b32_e32 v107, 0xffff0000, v107
	v_pk_fma_f32 v[102:103], v[102:103], v[104:105], v[106:107]
	v_pk_fma_f32 v[100:101], v[100:101], v[110:111], v[124:125]
	global_store_dwordx4 v[112:113], v[100:103], off offset:512
	global_load_dwordx2 v[102:103], v[118:119], off offset:288
	v_exp_f32_e32 v110, v98
	v_lshl_add_u64 v[100:101], v[114:115], 0, v[116:117]
	v_lshl_add_u64 v[100:101], v[100:101], 1, s[12:13]
	global_load_dwordx2 v[104:105], v[100:101], off
	v_exp_f32_e32 v111, v99
	s_nop 0
	v_pk_add_f32 v[110:111], v[110:111], 1.0 op_sel_hi:[1,0]
	v_rcp_f32_e32 v97, v97
	v_rcp_f32_e32 v96, v96
	v_rcp_f32_e32 v111, v111
	v_rcp_f32_e32 v110, v110
	v_lshlrev_b64 v[100:101], 10, v[108:109]
	v_lshl_add_u64 v[106:107], v[108:109], 2, s[18:19]
	v_lshl_add_u64 v[108:109], v[100:101], 0, v[142:143]
	v_lshlrev_b64 v[114:115], 1, v[108:109]
	v_lshl_add_u64 v[98:99], s[10:11], 0, v[114:115]
	s_waitcnt vmcnt(1)
;   DI void operator()(const f32x4 (&acc)[2][2][4][2], const pg8::Unit& u, int wr, int wc, int fr, int fq) const {
;     ...
;         const int row = u.pm * 256 + ai * 128 + wr * 64 + m * 16 + fr; float rs = 0.f;
;         const float rstd = rsqrtf(ssx[row] * (1.f / DM) + EPS);
; #pragma unroll
;         for (int bj = 0; bj < 2; ++bj)
; #pragma unroll
;           for (int n = 0; n < 2; ++n) {
;             const int col = u.pn * 256 + bj * 128 + wc * 32 + n * 16 + fq * 4; const size_t off = (size_t)row * DM + col;
;             f32x4 g;
; #pragma unroll
;             for (int j = 0; j < 4; ++j) g[j] = 1.f / (1.f + __expf(-rstd * acc[ai][bj][m][n][j]));
;             const u32x2 pw = *(const u32x2*)(PT + off); f32x4 pp; pp.x = __uint_as_float(pw.x << 16); pp.y = __uint_as_float(pw.x & 0xffff0000u); pp.z = __uint_as_float(pw.y << 16); pp.w = __uint_as_float(pw.y & 0xffff0000u);
;             const u32x2 xw = *(const u32x2*)(X1B + off); f32x4 x1; x1.x = __uint_as_float(xw.x << 16); x1.y = __uint_as_float(xw.x & 0xffff0000u); x1.z = __uint_as_float(xw.y << 16); x1.w = __uint_as_float(xw.y & 0xffff0000u);
;             const f32x4 xn = x1 + pp * g;
;             if (layer != 0) *(f32x4*)(out + off) = xn;
	v_lshlrev_b32_e32 v118, 16, v102
	v_and_b32_e32 v119, 0xffff0000, v102
	v_lshlrev_b32_e32 v102, 16, v103
	v_and_b32_e32 v103, 0xffff0000, v103
	s_waitcnt vmcnt(0)
	v_lshlrev_b32_e32 v122, 16, v104
	v_and_b32_e32 v123, 0xffff0000, v104
	v_lshlrev_b32_e32 v104, 16, v105
	v_and_b32_e32 v105, 0xffff0000, v105
	v_pk_fma_f32 v[104:105], v[110:111], v[102:103], v[104:105]
	v_pk_fma_f32 v[102:103], v[96:97], v[118:119], v[122:123]
	global_store_dwordx4 v[112:113], v[102:105], off offset:576
	global_load_dword v106, v[106:107], off
	s_nop 0
	global_load_dwordx2 v[102:103], v[98:99], off
	v_lshl_add_u64 v[96:97], s[12:13], 0, v[114:115]
	global_load_dwordx2 v[104:105], v[96:97], off
	v_lshl_add_u64 v[96:97], v[108:109], 2, s[14:15]
	s_waitcnt vmcnt(2)
	v_fmamk_f32 v109, v106, 0x3a800000, v158
	s_waitcnt vmcnt(1)
	v_lshlrev_b32_e32 v106, 16, v102
	v_and_b32_e32 v107, 0xffff0000, v102
	v_mul_f32_e32 v102, 0x4b800000, v109
	v_cmp_gt_f32_e32 vcc, s44, v109
	v_lshlrev_b32_e32 v108, 16, v103
	s_waitcnt vmcnt(0)
	v_lshlrev_b32_e32 v110, 16, v104
	v_cndmask_b32_e32 v102, v109, v102, vcc
	v_rsq_f32_e32 v102, v102
	v_and_b32_e32 v109, 0xffff0000, v103
	v_and_b32_e32 v111, 0xffff0000, v104
	v_lshlrev_b32_e32 v104, 16, v105
	v_mul_f32_e32 v103, 0x45800000, v102
	v_cndmask_b32_e32 v102, v102, v103, vcc
	v_mul_f32_e64 v92, v92, -v102
	v_mul_f32_e64 v93, v93, -v102
	v_mul_f32_e32 v92, 0x3fb8aa3b, v92
	v_mul_f32_e32 v93, 0x3fb8aa3b, v93
	v_mul_f32_e64 v94, v94, -v102
	v_mul_f32_e64 v95, v95, -v102
	v_exp_f32_e32 v92, v92
	v_exp_f32_e32 v93, v93
	v_mul_f32_e32 v94, 0x3fb8aa3b, v94
	v_mul_f32_e32 v95, 0x3fb8aa3b, v95
	v_exp_f32_e32 v94, v94
	v_exp_f32_e32 v95, v95
	v_pk_add_f32 v[92:93], v[92:93], 1.0 op_sel_hi:[1,0]
	v_and_b32_e32 v105, 0xffff0000, v105
	v_pk_add_f32 v[94:95], v[94:95], 1.0 op_sel_hi:[1,0]
	v_rcp_f32_e32 v93, v93
	v_rcp_f32_e32 v92, v92
	v_rcp_f32_e32 v95, v95
	v_rcp_f32_e32 v94, v94
	v_pk_fma_f32 v[92:93], v[92:93], v[106:107], v[110:111]
	v_pk_fma_f32 v[94:95], v[94:95], v[108:109], v[104:105]
	global_store_dwordx4 v[96:97], v[92:95], off
	global_load_dwordx2 v[92:93], v[98:99], off offset:32
	v_mul_f32_e64 v88, v88, -v102
	v_lshl_add_u64 v[94:95], v[100:101], 0, v[140:141]
	v_lshl_add_u64 v[94:95], v[94:95], 1, s[12:13]
	global_load_dwordx2 v[94:95], v[94:95], off
	v_mul_f32_e64 v89, v89, -v102
	v_mul_f32_e32 v88, 0x3fb8aa3b, v88
	v_mul_f32_e32 v89, 0x3fb8aa3b, v89
	v_mul_f32_e64 v90, v90, -v102
	v_mul_f32_e64 v91, v91, -v102
	v_exp_f32_e32 v88, v88
	v_exp_f32_e32 v89, v89
	v_mul_f32_e32 v90, 0x3fb8aa3b, v90
	v_mul_f32_e32 v91, 0x3fb8aa3b, v91
	v_exp_f32_e32 v90, v90
	v_exp_f32_e32 v91, v91
	v_pk_add_f32 v[88:89], v[88:89], 1.0 op_sel_hi:[1,0]
	v_mul_f32_e64 v84, v84, -v102
	v_pk_add_f32 v[90:91], v[90:91], 1.0 op_sel_hi:[1,0]
	v_rcp_f32_e32 v89, v89
	v_rcp_f32_e32 v88, v88
	v_rcp_f32_e32 v91, v91
	v_rcp_f32_e32 v90, v90
	v_mul_f32_e64 v85, v85, -v102
	v_mul_f32_e32 v84, 0x3fb8aa3b, v84
	v_mul_f32_e32 v85, 0x3fb8aa3b, v85
	v_mul_f32_e64 v86, v86, -v102
	v_mul_f32_e64 v87, v87, -v102
	v_exp_f32_e32 v84, v84
	s_waitcnt vmcnt(1)
	v_lshlrev_b32_e32 v104, 16, v92
	v_and_b32_e32 v105, 0xffff0000, v92
	v_lshlrev_b32_e32 v92, 16, v93
	v_and_b32_e32 v93, 0xffff0000, v93
	s_waitcnt vmcnt(0)
	v_lshlrev_b32_e32 v106, 16, v94
	v_and_b32_e32 v107, 0xffff0000, v94
	v_lshlrev_b32_e32 v94, 16, v95
	v_and_b32_e32 v95, 0xffff0000, v95
	v_pk_fma_f32 v[90:91], v[90:91], v[92:93], v[94:95]
	v_pk_fma_f32 v[88:89], v[88:89], v[104:105], v[106:107]
	global_store_dwordx4 v[96:97], v[88:91], off offset:64
	global_load_dwordx2 v[88:89], v[98:99], off offset:256
	v_exp_f32_e32 v85, v85
	v_lshl_add_u64 v[90:91], v[100:101], 0, v[120:121]
	v_lshl_add_u64 v[90:91], v[90:91], 1, s[12:13]
	global_load_dwordx2 v[90:91], v[90:91], off
	v_mul_f32_e32 v86, 0x3fb8aa3b, v86
	v_mul_f32_e32 v87, 0x3fb8aa3b, v87
	v_exp_f32_e32 v86, v86
	v_exp_f32_e32 v87, v87
	v_pk_add_f32 v[84:85], v[84:85], 1.0 op_sel_hi:[1,0]
	v_mul_f32_e64 v80, v80, -v102
	v_pk_add_f32 v[86:87], v[86:87], 1.0 op_sel_hi:[1,0]
	v_rcp_f32_e32 v85, v85
	v_rcp_f32_e32 v84, v84
	v_rcp_f32_e32 v87, v87
	v_rcp_f32_e32 v86, v86
	v_mul_f32_e64 v81, v81, -v102
	v_mul_f32_e32 v80, 0x3fb8aa3b, v80
	v_mul_f32_e32 v81, 0x3fb8aa3b, v81
	v_mul_f32_e64 v82, v82, -v102
	v_mul_f32_e64 v83, v83, -v102
	v_exp_f32_e32 v80, v80
	v_exp_f32_e32 v81, v81
	v_mul_f32_e32 v82, 0x3fb8aa3b, v82
	v_mul_f32_e32 v83, 0x3fb8aa3b, v83
	v_or_b32_e32 v92, 48, v144
	v_pk_add_f32 v[80:81], v[80:81], 1.0 op_sel_hi:[1,0]
	v_ashrrev_i32_e32 v93, 31, v92
	s_waitcnt vmcnt(1)
	v_lshlrev_b32_e32 v94, 16, v88
	v_and_b32_e32 v95, 0xffff0000, v88
	v_lshlrev_b32_e32 v88, 16, v89
	v_and_b32_e32 v89, 0xffff0000, v89
	s_waitcnt vmcnt(0)
	v_lshlrev_b32_e32 v104, 16, v90
	v_and_b32_e32 v105, 0xffff0000, v90
	v_lshlrev_b32_e32 v90, 16, v91
	v_and_b32_e32 v91, 0xffff0000, v91
	v_pk_fma_f32 v[86:87], v[86:87], v[88:89], v[90:91]
	v_pk_fma_f32 v[84:85], v[84:85], v[94:95], v[104:105]
	global_store_dwordx4 v[96:97], v[84:87], off offset:512
	global_load_dwordx2 v[86:87], v[98:99], off offset:288
	v_exp_f32_e32 v94, v82
	v_lshl_add_u64 v[84:85], v[100:101], 0, v[116:117]
	v_lshl_add_u64 v[84:85], v[84:85], 1, s[12:13]
	global_load_dwordx2 v[88:89], v[84:85], off
	v_exp_f32_e32 v95, v83
	s_nop 0
	v_pk_add_f32 v[94:95], v[94:95], 1.0 op_sel_hi:[1,0]
	v_rcp_f32_e32 v81, v81
	v_rcp_f32_e32 v80, v80
	v_rcp_f32_e32 v95, v95
	v_rcp_f32_e32 v94, v94
	v_lshlrev_b64 v[84:85], 10, v[92:93]
	v_lshl_add_u64 v[90:91], v[92:93], 2, s[18:19]
	v_lshl_add_u64 v[92:93], v[84:85], 0, v[142:143]
	v_lshlrev_b64 v[98:99], 1, v[92:93]
	v_lshl_add_u64 v[82:83], s[10:11], 0, v[98:99]
	s_waitcnt vmcnt(1)
;   DI void operator()(const f32x4 (&acc)[2][2][4][2], const pg8::Unit& u, int wr, int wc, int fr, int fq) const {
;     ...
;         const int row = u.pm * 256 + ai * 128 + wr * 64 + m * 16 + fr; float rs = 0.f;
;         const float rstd = rsqrtf(ssx[row] * (1.f / DM) + EPS);
; #pragma unroll
;         for (int bj = 0; bj < 2; ++bj)
; #pragma unroll
;           for (int n = 0; n < 2; ++n) {
;             const int col = u.pn * 256 + bj * 128 + wc * 32 + n * 16 + fq * 4; const size_t off = (size_t)row * DM + col;
;             f32x4 g;
; #pragma unroll
;             for (int j = 0; j < 4; ++j) g[j] = 1.f / (1.f + __expf(-rstd * acc[ai][bj][m][n][j]));
;             const u32x2 pw = *(const u32x2*)(PT + off); f32x4 pp; pp.x = __uint_as_float(pw.x << 16); pp.y = __uint_as_float(pw.x & 0xffff0000u); pp.z = __uint_as_float(pw.y << 16); pp.w = __uint_as_float(pw.y & 0xffff0000u);
;             const u32x2 xw = *(const u32x2*)(X1B + off); f32x4 x1; x1.x = __uint_as_float(xw.x << 16); x1.y = __uint_as_float(xw.x & 0xffff0000u); x1.z = __uint_as_float(xw.y << 16); x1.w = __uint_as_float(xw.y & 0xffff0000u);
;             const f32x4 xn = x1 + pp * g;
;             if (layer != 0) *(f32x4*)(out + off) = xn;
	v_lshlrev_b32_e32 v100, 16, v86
	v_and_b32_e32 v101, 0xffff0000, v86
	v_lshlrev_b32_e32 v86, 16, v87
	v_and_b32_e32 v87, 0xffff0000, v87
	s_waitcnt vmcnt(0)
	v_lshlrev_b32_e32 v102, 16, v88
	v_and_b32_e32 v103, 0xffff0000, v88
	v_lshlrev_b32_e32 v88, 16, v89
	v_and_b32_e32 v89, 0xffff0000, v89
	v_pk_fma_f32 v[88:89], v[94:95], v[86:87], v[88:89]
	v_pk_fma_f32 v[86:87], v[80:81], v[100:101], v[102:103]
	global_store_dwordx4 v[96:97], v[86:89], off offset:576
	global_load_dword v90, v[90:91], off
	s_nop 0
	global_load_dwordx2 v[86:87], v[82:83], off
	v_lshl_add_u64 v[80:81], s[12:13], 0, v[98:99]
	global_load_dwordx2 v[88:89], v[80:81], off
	v_lshl_add_u64 v[80:81], v[92:93], 2, s[14:15]
	s_waitcnt vmcnt(2)
	v_fmamk_f32 v93, v90, 0x3a800000, v158
	s_waitcnt vmcnt(1)
	v_lshlrev_b32_e32 v90, 16, v86
	v_and_b32_e32 v91, 0xffff0000, v86
	v_mul_f32_e32 v86, 0x4b800000, v93
	v_cmp_gt_f32_e32 vcc, s44, v93
	v_lshlrev_b32_e32 v92, 16, v87
	s_waitcnt vmcnt(0)
	v_lshlrev_b32_e32 v94, 16, v88
	v_cndmask_b32_e32 v86, v93, v86, vcc
	v_rsq_f32_e32 v86, v86
	v_and_b32_e32 v93, 0xffff0000, v87
	v_and_b32_e32 v95, 0xffff0000, v88
	v_lshlrev_b32_e32 v88, 16, v89
	v_mul_f32_e32 v87, 0x45800000, v86
	v_cndmask_b32_e32 v86, v86, v87, vcc
	v_mul_f32_e64 v76, v76, -v86
	v_mul_f32_e64 v77, v77, -v86
	v_mul_f32_e32 v76, 0x3fb8aa3b, v76
	v_mul_f32_e32 v77, 0x3fb8aa3b, v77
	v_mul_f32_e64 v78, v78, -v86
	v_mul_f32_e64 v79, v79, -v86
	v_exp_f32_e32 v76, v76
	v_exp_f32_e32 v77, v77
	v_mul_f32_e32 v78, 0x3fb8aa3b, v78
	v_mul_f32_e32 v79, 0x3fb8aa3b, v79
	v_exp_f32_e32 v78, v78
	v_exp_f32_e32 v79, v79
	v_pk_add_f32 v[76:77], v[76:77], 1.0 op_sel_hi:[1,0]
	v_and_b32_e32 v89, 0xffff0000, v89
	v_pk_add_f32 v[78:79], v[78:79], 1.0 op_sel_hi:[1,0]
	v_rcp_f32_e32 v77, v77
	v_rcp_f32_e32 v76, v76
	v_rcp_f32_e32 v79, v79
	v_rcp_f32_e32 v78, v78
	v_pk_fma_f32 v[76:77], v[76:77], v[90:91], v[94:95]
	v_pk_fma_f32 v[78:79], v[78:79], v[92:93], v[88:89]
	global_store_dwordx4 v[80:81], v[76:79], off
	global_load_dwordx2 v[76:77], v[82:83], off offset:32
	v_mul_f32_e64 v72, v72, -v86
	v_lshl_add_u64 v[78:79], v[84:85], 0, v[140:141]
	v_lshl_add_u64 v[78:79], v[78:79], 1, s[12:13]
	global_load_dwordx2 v[78:79], v[78:79], off
	v_mul_f32_e64 v73, v73, -v86
	v_mul_f32_e32 v72, 0x3fb8aa3b, v72
	v_mul_f32_e32 v73, 0x3fb8aa3b, v73
	v_mul_f32_e64 v74, v74, -v86
	v_mul_f32_e64 v75, v75, -v86
	v_exp_f32_e32 v72, v72
	v_exp_f32_e32 v73, v73
	v_mul_f32_e32 v74, 0x3fb8aa3b, v74
	v_mul_f32_e32 v75, 0x3fb8aa3b, v75
	v_exp_f32_e32 v74, v74
	v_exp_f32_e32 v75, v75
	v_pk_add_f32 v[72:73], v[72:73], 1.0 op_sel_hi:[1,0]
	v_mul_f32_e64 v68, v68, -v86
	v_pk_add_f32 v[74:75], v[74:75], 1.0 op_sel_hi:[1,0]
	v_rcp_f32_e32 v73, v73
	v_rcp_f32_e32 v72, v72
	v_rcp_f32_e32 v75, v75
	v_rcp_f32_e32 v74, v74
	v_mul_f32_e64 v69, v69, -v86
	v_mul_f32_e32 v68, 0x3fb8aa3b, v68
	v_mul_f32_e32 v69, 0x3fb8aa3b, v69
	v_mul_f32_e64 v70, v70, -v86
	v_mul_f32_e64 v71, v71, -v86
	v_exp_f32_e32 v68, v68
	s_waitcnt vmcnt(1)
	v_lshlrev_b32_e32 v88, 16, v76
	v_and_b32_e32 v89, 0xffff0000, v76
	v_lshlrev_b32_e32 v76, 16, v77
	v_and_b32_e32 v77, 0xffff0000, v77
	s_waitcnt vmcnt(0)
	v_lshlrev_b32_e32 v90, 16, v78
	v_and_b32_e32 v91, 0xffff0000, v78
	v_lshlrev_b32_e32 v78, 16, v79
	v_and_b32_e32 v79, 0xffff0000, v79
	v_pk_fma_f32 v[74:75], v[74:75], v[76:77], v[78:79]
	v_pk_fma_f32 v[72:73], v[72:73], v[88:89], v[90:91]
	global_store_dwordx4 v[80:81], v[72:75], off offset:64
	global_load_dwordx2 v[72:73], v[82:83], off offset:256
	v_exp_f32_e32 v69, v69
	v_lshl_add_u64 v[74:75], v[84:85], 0, v[120:121]
	v_lshl_add_u64 v[74:75], v[74:75], 1, s[12:13]
	global_load_dwordx2 v[74:75], v[74:75], off
	v_mul_f32_e32 v70, 0x3fb8aa3b, v70
	v_mul_f32_e32 v71, 0x3fb8aa3b, v71
	v_exp_f32_e32 v70, v70
	v_exp_f32_e32 v71, v71
	v_pk_add_f32 v[68:69], v[68:69], 1.0 op_sel_hi:[1,0]
	v_mul_f32_e64 v64, v64, -v86
	v_pk_add_f32 v[70:71], v[70:71], 1.0 op_sel_hi:[1,0]
	v_rcp_f32_e32 v69, v69
	v_rcp_f32_e32 v68, v68
	v_rcp_f32_e32 v71, v71
	v_rcp_f32_e32 v70, v70
	v_mul_f32_e64 v65, v65, -v86
	v_mul_f32_e32 v64, 0x3fb8aa3b, v64
	v_mul_f32_e32 v65, 0x3fb8aa3b, v65
	v_mul_f32_e64 v66, v66, -v86
	v_mul_f32_e64 v67, v67, -v86
	v_exp_f32_e32 v64, v64
	v_exp_f32_e32 v65, v65
	v_mul_f32_e32 v66, 0x3fb8aa3b, v66
	v_mul_f32_e32 v67, 0x3fb8aa3b, v67
	v_add_u32_e32 v76, 0x80, v144
	v_pk_add_f32 v[64:65], v[64:65], 1.0 op_sel_hi:[1,0]
	v_ashrrev_i32_e32 v77, 31, v76
	s_waitcnt vmcnt(1)
	v_lshlrev_b32_e32 v78, 16, v72
	v_and_b32_e32 v79, 0xffff0000, v72
	v_lshlrev_b32_e32 v72, 16, v73
	v_and_b32_e32 v73, 0xffff0000, v73
	s_waitcnt vmcnt(0)
	v_lshlrev_b32_e32 v88, 16, v74
	v_and_b32_e32 v89, 0xffff0000, v74
	v_lshlrev_b32_e32 v74, 16, v75
	v_and_b32_e32 v75, 0xffff0000, v75
	v_pk_fma_f32 v[70:71], v[70:71], v[72:73], v[74:75]
	v_pk_fma_f32 v[68:69], v[68:69], v[78:79], v[88:89]
	global_store_dwordx4 v[80:81], v[68:71], off offset:512
	global_load_dwordx2 v[70:71], v[82:83], off offset:288
	v_exp_f32_e32 v78, v66
	v_lshl_add_u64 v[68:69], v[84:85], 0, v[116:117]
	v_lshl_add_u64 v[68:69], v[68:69], 1, s[12:13]
	global_load_dwordx2 v[72:73], v[68:69], off
	v_exp_f32_e32 v79, v67
	s_nop 0
	v_pk_add_f32 v[78:79], v[78:79], 1.0 op_sel_hi:[1,0]
	v_rcp_f32_e32 v65, v65
	v_rcp_f32_e32 v64, v64
	v_rcp_f32_e32 v79, v79
	v_rcp_f32_e32 v78, v78
	v_lshlrev_b64 v[68:69], 10, v[76:77]
	v_lshl_add_u64 v[74:75], v[76:77], 2, s[18:19]
	v_lshl_add_u64 v[76:77], v[68:69], 0, v[142:143]
	v_lshlrev_b64 v[82:83], 1, v[76:77]
	v_lshl_add_u64 v[66:67], s[10:11], 0, v[82:83]
	s_waitcnt vmcnt(1)
	v_lshlrev_b32_e32 v84, 16, v70
	v_and_b32_e32 v85, 0xffff0000, v70
	v_lshlrev_b32_e32 v70, 16, v71
	v_and_b32_e32 v71, 0xffff0000, v71
	s_waitcnt vmcnt(0)
;   DI void operator()(const f32x4 (&acc)[2][2][4][2], const pg8::Unit& u, int wr, int wc, int fr, int fq) const {
;     ...
;         const int row = u.pm * 256 + ai * 128 + wr * 64 + m * 16 + fr; float rs = 0.f;
;         const float rstd = rsqrtf(ssx[row] * (1.f / DM) + EPS);
; #pragma unroll
;         for (int bj = 0; bj < 2; ++bj)
; #pragma unroll
;           for (int n = 0; n < 2; ++n) {
;             const int col = u.pn * 256 + bj * 128 + wc * 32 + n * 16 + fq * 4; const size_t off = (size_t)row * DM + col;
;             f32x4 g;
; #pragma unroll
;             for (int j = 0; j < 4; ++j) g[j] = 1.f / (1.f + __expf(-rstd * acc[ai][bj][m][n][j]));
;             const u32x2 pw = *(const u32x2*)(PT + off); f32x4 pp; pp.x = __uint_as_float(pw.x << 16); pp.y = __uint_as_float(pw.x & 0xffff0000u); pp.z = __uint_as_float(pw.y << 16); pp.w = __uint_as_float(pw.y & 0xffff0000u);
;             const u32x2 xw = *(const u32x2*)(X1B + off); f32x4 x1; x1.x = __uint_as_float(xw.x << 16); x1.y = __uint_as_float(xw.x & 0xffff0000u); x1.z = __uint_as_float(xw.y << 16); x1.w = __uint_as_float(xw.y & 0xffff0000u);
;             const f32x4 xn = x1 + pp * g;
;             if (layer != 0) *(f32x4*)(out + off) = xn;
	v_lshlrev_b32_e32 v86, 16, v72
	v_and_b32_e32 v87, 0xffff0000, v72
	v_lshlrev_b32_e32 v72, 16, v73
	v_and_b32_e32 v73, 0xffff0000, v73
	v_pk_fma_f32 v[72:73], v[78:79], v[70:71], v[72:73]
	v_pk_fma_f32 v[70:71], v[64:65], v[84:85], v[86:87]
	global_store_dwordx4 v[80:81], v[70:73], off offset:576
	global_load_dword v74, v[74:75], off
	s_nop 0
	global_load_dwordx2 v[70:71], v[66:67], off
	v_lshl_add_u64 v[64:65], s[12:13], 0, v[82:83]
	global_load_dwordx2 v[72:73], v[64:65], off
	v_lshl_add_u64 v[64:65], v[76:77], 2, s[14:15]
	s_waitcnt vmcnt(2)
	v_fmamk_f32 v77, v74, 0x3a800000, v158
	s_waitcnt vmcnt(1)
	v_lshlrev_b32_e32 v74, 16, v70
	v_and_b32_e32 v75, 0xffff0000, v70
	v_mul_f32_e32 v70, 0x4b800000, v77
	v_cmp_gt_f32_e32 vcc, s44, v77
	v_lshlrev_b32_e32 v76, 16, v71
	s_waitcnt vmcnt(0)
	v_lshlrev_b32_e32 v78, 16, v72
	v_cndmask_b32_e32 v70, v77, v70, vcc
	v_rsq_f32_e32 v70, v70
	v_and_b32_e32 v77, 0xffff0000, v71
	v_and_b32_e32 v79, 0xffff0000, v72
	v_lshlrev_b32_e32 v72, 16, v73
	v_mul_f32_e32 v71, 0x45800000, v70
	v_cndmask_b32_e32 v70, v70, v71, vcc
	v_mul_f32_e64 v60, v60, -v70
	v_mul_f32_e64 v61, v61, -v70
	v_mul_f32_e32 v60, 0x3fb8aa3b, v60
	v_mul_f32_e32 v61, 0x3fb8aa3b, v61
	v_mul_f32_e64 v62, v62, -v70
	v_mul_f32_e64 v63, v63, -v70
	v_exp_f32_e32 v60, v60
	v_exp_f32_e32 v61, v61
	v_mul_f32_e32 v62, 0x3fb8aa3b, v62
	v_mul_f32_e32 v63, 0x3fb8aa3b, v63
	v_exp_f32_e32 v62, v62
	v_exp_f32_e32 v63, v63
	v_pk_add_f32 v[60:61], v[60:61], 1.0 op_sel_hi:[1,0]
	v_and_b32_e32 v73, 0xffff0000, v73
	v_pk_add_f32 v[62:63], v[62:63], 1.0 op_sel_hi:[1,0]
	v_rcp_f32_e32 v61, v61
	v_rcp_f32_e32 v60, v60
	v_rcp_f32_e32 v63, v63
	v_rcp_f32_e32 v62, v62
	v_pk_fma_f32 v[60:61], v[60:61], v[74:75], v[78:79]
	v_pk_fma_f32 v[62:63], v[62:63], v[76:77], v[72:73]
	global_store_dwordx4 v[64:65], v[60:63], off
	global_load_dwordx2 v[60:61], v[66:67], off offset:32
	v_mul_f32_e64 v56, v56, -v70
	v_lshl_add_u64 v[62:63], v[68:69], 0, v[140:141]
	v_lshl_add_u64 v[62:63], v[62:63], 1, s[12:13]
	global_load_dwordx2 v[62:63], v[62:63], off
	v_mul_f32_e64 v57, v57, -v70
	v_mul_f32_e32 v56, 0x3fb8aa3b, v56
	v_mul_f32_e32 v57, 0x3fb8aa3b, v57
	v_mul_f32_e64 v58, v58, -v70
	v_mul_f32_e64 v59, v59, -v70
	v_exp_f32_e32 v56, v56
	v_exp_f32_e32 v57, v57
	v_mul_f32_e32 v58, 0x3fb8aa3b, v58
	v_mul_f32_e32 v59, 0x3fb8aa3b, v59
	v_exp_f32_e32 v58, v58
	v_exp_f32_e32 v59, v59
	v_pk_add_f32 v[56:57], v[56:57], 1.0 op_sel_hi:[1,0]
	v_mul_f32_e64 v52, v52, -v70
	v_pk_add_f32 v[58:59], v[58:59], 1.0 op_sel_hi:[1,0]
	v_rcp_f32_e32 v57, v57
	v_rcp_f32_e32 v56, v56
	v_rcp_f32_e32 v59, v59
	v_rcp_f32_e32 v58, v58
	v_mul_f32_e64 v53, v53, -v70
	v_mul_f32_e32 v52, 0x3fb8aa3b, v52
	v_mul_f32_e32 v53, 0x3fb8aa3b, v53
	v_mul_f32_e64 v54, v54, -v70
	v_mul_f32_e64 v55, v55, -v70
	v_exp_f32_e32 v52, v52
	s_waitcnt vmcnt(1)
	v_lshlrev_b32_e32 v72, 16, v60
	v_and_b32_e32 v73, 0xffff0000, v60
	v_lshlrev_b32_e32 v60, 16, v61
	v_and_b32_e32 v61, 0xffff0000, v61
	s_waitcnt vmcnt(0)
	v_lshlrev_b32_e32 v74, 16, v62
	v_and_b32_e32 v75, 0xffff0000, v62
	v_lshlrev_b32_e32 v62, 16, v63
	v_and_b32_e32 v63, 0xffff0000, v63
	v_pk_fma_f32 v[58:59], v[58:59], v[60:61], v[62:63]
	v_pk_fma_f32 v[56:57], v[56:57], v[72:73], v[74:75]
	global_store_dwordx4 v[64:65], v[56:59], off offset:64
	global_load_dwordx2 v[56:57], v[66:67], off offset:256
	v_exp_f32_e32 v53, v53
	v_lshl_add_u64 v[58:59], v[68:69], 0, v[120:121]
	v_lshl_add_u64 v[58:59], v[58:59], 1, s[12:13]
	global_load_dwordx2 v[58:59], v[58:59], off
	v_mul_f32_e32 v54, 0x3fb8aa3b, v54
	v_mul_f32_e32 v55, 0x3fb8aa3b, v55
	v_exp_f32_e32 v54, v54
	v_exp_f32_e32 v55, v55
	v_pk_add_f32 v[52:53], v[52:53], 1.0 op_sel_hi:[1,0]
	v_mul_f32_e64 v48, v48, -v70
	v_pk_add_f32 v[54:55], v[54:55], 1.0 op_sel_hi:[1,0]
	v_rcp_f32_e32 v53, v53
	v_rcp_f32_e32 v52, v52
	v_rcp_f32_e32 v55, v55
	v_rcp_f32_e32 v54, v54
	v_mul_f32_e64 v49, v49, -v70
	v_mul_f32_e32 v48, 0x3fb8aa3b, v48
	v_mul_f32_e32 v49, 0x3fb8aa3b, v49
	v_mul_f32_e64 v50, v50, -v70
	v_mul_f32_e64 v51, v51, -v70
	v_exp_f32_e32 v48, v48
	v_exp_f32_e32 v49, v49
	v_mul_f32_e32 v50, 0x3fb8aa3b, v50
	v_mul_f32_e32 v51, 0x3fb8aa3b, v51
	v_add_u32_e32 v60, 0x90, v144
	v_pk_add_f32 v[48:49], v[48:49], 1.0 op_sel_hi:[1,0]
	v_ashrrev_i32_e32 v61, 31, v60
	s_waitcnt vmcnt(1)
	v_lshlrev_b32_e32 v62, 16, v56
	v_and_b32_e32 v63, 0xffff0000, v56
	v_lshlrev_b32_e32 v56, 16, v57
	v_and_b32_e32 v57, 0xffff0000, v57
	s_waitcnt vmcnt(0)
	v_lshlrev_b32_e32 v72, 16, v58
	v_and_b32_e32 v73, 0xffff0000, v58
	v_lshlrev_b32_e32 v58, 16, v59
	v_and_b32_e32 v59, 0xffff0000, v59
	v_pk_fma_f32 v[54:55], v[54:55], v[56:57], v[58:59]
	v_pk_fma_f32 v[52:53], v[52:53], v[62:63], v[72:73]
	global_store_dwordx4 v[64:65], v[52:55], off offset:512
	global_load_dwordx2 v[54:55], v[66:67], off offset:288
	v_exp_f32_e32 v62, v50
	v_lshl_add_u64 v[52:53], v[68:69], 0, v[116:117]
	v_lshl_add_u64 v[52:53], v[52:53], 1, s[12:13]
	global_load_dwordx2 v[56:57], v[52:53], off
	v_exp_f32_e32 v63, v51
	s_nop 0
	v_pk_add_f32 v[62:63], v[62:63], 1.0 op_sel_hi:[1,0]
	v_rcp_f32_e32 v49, v49
	v_rcp_f32_e32 v48, v48
	v_rcp_f32_e32 v63, v63
	v_rcp_f32_e32 v62, v62
	v_lshlrev_b64 v[52:53], 10, v[60:61]
	v_lshl_add_u64 v[58:59], v[60:61], 2, s[18:19]
	v_lshl_add_u64 v[60:61], v[52:53], 0, v[142:143]
	v_lshlrev_b64 v[66:67], 1, v[60:61]
	v_lshl_add_u64 v[50:51], s[10:11], 0, v[66:67]
	s_waitcnt vmcnt(1)
	v_lshlrev_b32_e32 v68, 16, v54
	v_and_b32_e32 v69, 0xffff0000, v54
	v_lshlrev_b32_e32 v54, 16, v55
	v_and_b32_e32 v55, 0xffff0000, v55
	s_waitcnt vmcnt(0)
;   DI void operator()(const f32x4 (&acc)[2][2][4][2], const pg8::Unit& u, int wr, int wc, int fr, int fq) const {
;     ...
;         const int row = u.pm * 256 + ai * 128 + wr * 64 + m * 16 + fr; float rs = 0.f;
;         const float rstd = rsqrtf(ssx[row] * (1.f / DM) + EPS);
; #pragma unroll
;         for (int bj = 0; bj < 2; ++bj)
; #pragma unroll
;           for (int n = 0; n < 2; ++n) {
;             const int col = u.pn * 256 + bj * 128 + wc * 32 + n * 16 + fq * 4; const size_t off = (size_t)row * DM + col;
;             f32x4 g;
; #pragma unroll
;             for (int j = 0; j < 4; ++j) g[j] = 1.f / (1.f + __expf(-rstd * acc[ai][bj][m][n][j]));
;             const u32x2 pw = *(const u32x2*)(PT + off); f32x4 pp; pp.x = __uint_as_float(pw.x << 16); pp.y = __uint_as_float(pw.x & 0xffff0000u); pp.z = __uint_as_float(pw.y << 16); pp.w = __uint_as_float(pw.y & 0xffff0000u);
;             const u32x2 xw = *(const u32x2*)(X1B + off); f32x4 x1; x1.x = __uint_as_float(xw.x << 16); x1.y = __uint_as_float(xw.x & 0xffff0000u); x1.z = __uint_as_float(xw.y << 16); x1.w = __uint_as_float(xw.y & 0xffff0000u);
;             const f32x4 xn = x1 + pp * g;
;             if (layer != 0) *(f32x4*)(out + off) = xn;
	v_lshlrev_b32_e32 v70, 16, v56
	v_and_b32_e32 v71, 0xffff0000, v56
	v_lshlrev_b32_e32 v56, 16, v57
	v_and_b32_e32 v57, 0xffff0000, v57
	v_pk_fma_f32 v[56:57], v[62:63], v[54:55], v[56:57]
	v_pk_fma_f32 v[54:55], v[48:49], v[68:69], v[70:71]
	global_store_dwordx4 v[64:65], v[54:57], off offset:576
	global_load_dword v62, v[58:59], off
	global_load_dwordx2 v[54:55], v[50:51], off
	v_lshl_add_u64 v[48:49], s[12:13], 0, v[66:67]
	global_load_dwordx2 v[56:57], v[48:49], off
	v_lshl_add_u64 v[48:49], v[60:61], 2, s[14:15]
	s_waitcnt vmcnt(2)
	v_fmamk_f32 v61, v62, 0x3a800000, v158
	s_waitcnt vmcnt(1)
	v_lshlrev_b32_e32 v58, 16, v54
	v_and_b32_e32 v59, 0xffff0000, v54
	v_mul_f32_e32 v54, 0x4b800000, v61
	v_cmp_gt_f32_e32 vcc, s44, v61
	v_lshlrev_b32_e32 v60, 16, v55
	s_waitcnt vmcnt(0)
	v_lshlrev_b32_e32 v62, 16, v56
	v_cndmask_b32_e32 v54, v61, v54, vcc
	v_rsq_f32_e32 v54, v54
	v_and_b32_e32 v61, 0xffff0000, v55
	v_and_b32_e32 v63, 0xffff0000, v56
	v_lshlrev_b32_e32 v56, 16, v57
	v_mul_f32_e32 v55, 0x45800000, v54
	v_cndmask_b32_e32 v54, v54, v55, vcc
	v_mul_f32_e64 v44, v44, -v54
	v_mul_f32_e64 v45, v45, -v54
	v_mul_f32_e32 v44, 0x3fb8aa3b, v44
	v_mul_f32_e32 v45, 0x3fb8aa3b, v45
	v_mul_f32_e64 v46, v46, -v54
	v_mul_f32_e64 v47, v47, -v54
	v_exp_f32_e32 v44, v44
	v_exp_f32_e32 v45, v45
	v_mul_f32_e32 v46, 0x3fb8aa3b, v46
	v_mul_f32_e32 v47, 0x3fb8aa3b, v47
	v_exp_f32_e32 v46, v46
	v_exp_f32_e32 v47, v47
	v_pk_add_f32 v[44:45], v[44:45], 1.0 op_sel_hi:[1,0]
	v_and_b32_e32 v57, 0xffff0000, v57
	v_pk_add_f32 v[46:47], v[46:47], 1.0 op_sel_hi:[1,0]
	v_rcp_f32_e32 v45, v45
	v_rcp_f32_e32 v44, v44
	v_rcp_f32_e32 v47, v47
	v_rcp_f32_e32 v46, v46
	v_pk_fma_f32 v[44:45], v[44:45], v[58:59], v[62:63]
	v_pk_fma_f32 v[46:47], v[46:47], v[60:61], v[56:57]
	global_store_dwordx4 v[48:49], v[44:47], off
	global_load_dwordx2 v[44:45], v[50:51], off offset:32
	v_mul_f32_e64 v40, v40, -v54
	v_lshl_add_u64 v[46:47], v[52:53], 0, v[140:141]
	v_lshl_add_u64 v[46:47], v[46:47], 1, s[12:13]
	global_load_dwordx2 v[46:47], v[46:47], off
	v_mul_f32_e64 v41, v41, -v54
	v_mul_f32_e32 v40, 0x3fb8aa3b, v40
	v_mul_f32_e32 v41, 0x3fb8aa3b, v41
	v_mul_f32_e64 v42, v42, -v54
	v_mul_f32_e64 v43, v43, -v54
	v_exp_f32_e32 v40, v40
	v_exp_f32_e32 v41, v41
	v_mul_f32_e32 v42, 0x3fb8aa3b, v42
	v_mul_f32_e32 v43, 0x3fb8aa3b, v43
	v_exp_f32_e32 v42, v42
	v_exp_f32_e32 v43, v43
	v_pk_add_f32 v[40:41], v[40:41], 1.0 op_sel_hi:[1,0]
	v_mul_f32_e64 v36, v36, -v54
	v_pk_add_f32 v[42:43], v[42:43], 1.0 op_sel_hi:[1,0]
	v_rcp_f32_e32 v41, v41
	v_rcp_f32_e32 v40, v40
	v_rcp_f32_e32 v43, v43
	v_rcp_f32_e32 v42, v42
	v_mul_f32_e64 v37, v37, -v54
	v_mul_f32_e32 v36, 0x3fb8aa3b, v36
	v_mul_f32_e32 v37, 0x3fb8aa3b, v37
	v_mul_f32_e64 v38, v38, -v54
	v_mul_f32_e64 v39, v39, -v54
	v_exp_f32_e32 v36, v36
	s_waitcnt vmcnt(1)
	v_lshlrev_b32_e32 v56, 16, v44
	v_and_b32_e32 v57, 0xffff0000, v44
	v_lshlrev_b32_e32 v44, 16, v45
	v_and_b32_e32 v45, 0xffff0000, v45
	s_waitcnt vmcnt(0)
	v_lshlrev_b32_e32 v58, 16, v46
	v_and_b32_e32 v59, 0xffff0000, v46
	v_lshlrev_b32_e32 v46, 16, v47
	v_and_b32_e32 v47, 0xffff0000, v47
	v_pk_fma_f32 v[42:43], v[42:43], v[44:45], v[46:47]
	v_pk_fma_f32 v[40:41], v[40:41], v[56:57], v[58:59]
	global_store_dwordx4 v[48:49], v[40:43], off offset:64
	global_load_dwordx2 v[40:41], v[50:51], off offset:256
	v_exp_f32_e32 v37, v37
	v_lshl_add_u64 v[42:43], v[52:53], 0, v[120:121]
	v_lshl_add_u64 v[42:43], v[42:43], 1, s[12:13]
	global_load_dwordx2 v[42:43], v[42:43], off
	v_mul_f32_e32 v38, 0x3fb8aa3b, v38
	v_mul_f32_e32 v39, 0x3fb8aa3b, v39
	v_exp_f32_e32 v38, v38
	v_exp_f32_e32 v39, v39
	v_pk_add_f32 v[36:37], v[36:37], 1.0 op_sel_hi:[1,0]
	v_mul_f32_e64 v32, v32, -v54
	v_pk_add_f32 v[38:39], v[38:39], 1.0 op_sel_hi:[1,0]
	v_rcp_f32_e32 v37, v37
	v_rcp_f32_e32 v36, v36
	v_rcp_f32_e32 v39, v39
	v_rcp_f32_e32 v38, v38
	v_mul_f32_e64 v33, v33, -v54
	v_mul_f32_e32 v32, 0x3fb8aa3b, v32
	v_mul_f32_e32 v33, 0x3fb8aa3b, v33
	v_mul_f32_e64 v34, v34, -v54
	v_mul_f32_e64 v35, v35, -v54
	v_exp_f32_e32 v32, v32
	v_exp_f32_e32 v33, v33
	v_mul_f32_e32 v34, 0x3fb8aa3b, v34
	v_mul_f32_e32 v35, 0x3fb8aa3b, v35
	v_add_u32_e32 v44, 0xa0, v144
	v_pk_add_f32 v[32:33], v[32:33], 1.0 op_sel_hi:[1,0]
	v_ashrrev_i32_e32 v45, 31, v44
	s_waitcnt vmcnt(1)
	v_lshlrev_b32_e32 v46, 16, v40
	v_and_b32_e32 v47, 0xffff0000, v40
	v_lshlrev_b32_e32 v40, 16, v41
	v_and_b32_e32 v41, 0xffff0000, v41
	s_waitcnt vmcnt(0)
	v_lshlrev_b32_e32 v56, 16, v42
	v_and_b32_e32 v57, 0xffff0000, v42
	v_lshlrev_b32_e32 v42, 16, v43
	v_and_b32_e32 v43, 0xffff0000, v43
	v_pk_fma_f32 v[38:39], v[38:39], v[40:41], v[42:43]
	v_pk_fma_f32 v[36:37], v[36:37], v[46:47], v[56:57]
	global_store_dwordx4 v[48:49], v[36:39], off offset:512
	global_load_dwordx2 v[38:39], v[50:51], off offset:288
	v_exp_f32_e32 v46, v34
	v_lshl_add_u64 v[36:37], v[52:53], 0, v[116:117]
	v_lshl_add_u64 v[36:37], v[36:37], 1, s[12:13]
	global_load_dwordx2 v[40:41], v[36:37], off
	v_exp_f32_e32 v47, v35
	s_nop 0
	v_pk_add_f32 v[46:47], v[46:47], 1.0 op_sel_hi:[1,0]
	v_rcp_f32_e32 v33, v33
	v_rcp_f32_e32 v32, v32
	v_rcp_f32_e32 v47, v47
	v_rcp_f32_e32 v46, v46
	v_lshlrev_b64 v[36:37], 10, v[44:45]
	v_lshl_add_u64 v[42:43], v[44:45], 2, s[18:19]
	v_lshl_add_u64 v[44:45], v[36:37], 0, v[142:143]
	v_lshlrev_b64 v[50:51], 1, v[44:45]
	v_lshl_add_u64 v[34:35], s[10:11], 0, v[50:51]
	s_waitcnt vmcnt(1)
	v_lshlrev_b32_e32 v52, 16, v38
	v_and_b32_e32 v53, 0xffff0000, v38
	v_lshlrev_b32_e32 v38, 16, v39
	v_and_b32_e32 v39, 0xffff0000, v39
	s_waitcnt vmcnt(0)
;   DI void operator()(const f32x4 (&acc)[2][2][4][2], const pg8::Unit& u, int wr, int wc, int fr, int fq) const {
;     ...
;         const int row = u.pm * 256 + ai * 128 + wr * 64 + m * 16 + fr; float rs = 0.f;
;         const float rstd = rsqrtf(ssx[row] * (1.f / DM) + EPS);
; #pragma unroll
;         for (int bj = 0; bj < 2; ++bj)
; #pragma unroll
;           for (int n = 0; n < 2; ++n) {
;             const int col = u.pn * 256 + bj * 128 + wc * 32 + n * 16 + fq * 4; const size_t off = (size_t)row * DM + col;
;             f32x4 g;
; #pragma unroll
;             for (int j = 0; j < 4; ++j) g[j] = 1.f / (1.f + __expf(-rstd * acc[ai][bj][m][n][j]));
;             const u32x2 pw = *(const u32x2*)(PT + off); f32x4 pp; pp.x = __uint_as_float(pw.x << 16); pp.y = __uint_as_float(pw.x & 0xffff0000u); pp.z = __uint_as_float(pw.y << 16); pp.w = __uint_as_float(pw.y & 0xffff0000u);
;             const u32x2 xw = *(const u32x2*)(X1B + off); f32x4 x1; x1.x = __uint_as_float(xw.x << 16); x1.y = __uint_as_float(xw.x & 0xffff0000u); x1.z = __uint_as_float(xw.y << 16); x1.w = __uint_as_float(xw.y & 0xffff0000u);
;             const f32x4 xn = x1 + pp * g;
;             if (layer != 0) *(f32x4*)(out + off) = xn;
	v_lshlrev_b32_e32 v54, 16, v40
	v_and_b32_e32 v55, 0xffff0000, v40
	v_lshlrev_b32_e32 v40, 16, v41
	v_and_b32_e32 v41, 0xffff0000, v41
	v_pk_fma_f32 v[40:41], v[46:47], v[38:39], v[40:41]
	v_pk_fma_f32 v[38:39], v[32:33], v[52:53], v[54:55]
	global_store_dwordx4 v[48:49], v[38:41], off offset:576
	global_load_dword v46, v[42:43], off
	global_load_dwordx2 v[38:39], v[34:35], off
	v_lshl_add_u64 v[32:33], s[12:13], 0, v[50:51]
	global_load_dwordx2 v[40:41], v[32:33], off
	v_lshl_add_u64 v[32:33], v[44:45], 2, s[14:15]
	s_waitcnt vmcnt(2)
	v_fmamk_f32 v45, v46, 0x3a800000, v158
	s_waitcnt vmcnt(1)
	v_lshlrev_b32_e32 v42, 16, v38
	v_and_b32_e32 v43, 0xffff0000, v38
	v_mul_f32_e32 v38, 0x4b800000, v45
	v_cmp_gt_f32_e32 vcc, s44, v45
	v_lshlrev_b32_e32 v44, 16, v39
	s_waitcnt vmcnt(0)
	v_lshlrev_b32_e32 v46, 16, v40
	v_cndmask_b32_e32 v38, v45, v38, vcc
	v_rsq_f32_e32 v38, v38
	v_and_b32_e32 v45, 0xffff0000, v39
	v_and_b32_e32 v47, 0xffff0000, v40
	v_lshlrev_b32_e32 v40, 16, v41
	v_mul_f32_e32 v39, 0x45800000, v38
	v_cndmask_b32_e32 v38, v38, v39, vcc
	v_mul_f32_e64 v28, v28, -v38
	v_mul_f32_e64 v29, v29, -v38
	v_mul_f32_e32 v28, 0x3fb8aa3b, v28
	v_mul_f32_e32 v29, 0x3fb8aa3b, v29
	v_mul_f32_e64 v30, v30, -v38
	v_mul_f32_e64 v31, v31, -v38
	v_exp_f32_e32 v28, v28
	v_exp_f32_e32 v29, v29
	v_mul_f32_e32 v30, 0x3fb8aa3b, v30
	v_mul_f32_e32 v31, 0x3fb8aa3b, v31
	v_exp_f32_e32 v30, v30
	v_exp_f32_e32 v31, v31
	v_pk_add_f32 v[28:29], v[28:29], 1.0 op_sel_hi:[1,0]
	v_and_b32_e32 v41, 0xffff0000, v41
	v_pk_add_f32 v[30:31], v[30:31], 1.0 op_sel_hi:[1,0]
	v_rcp_f32_e32 v29, v29
	v_rcp_f32_e32 v28, v28
	v_rcp_f32_e32 v31, v31
	v_rcp_f32_e32 v30, v30
	v_pk_fma_f32 v[28:29], v[28:29], v[42:43], v[46:47]
	v_pk_fma_f32 v[30:31], v[30:31], v[44:45], v[40:41]
	global_store_dwordx4 v[32:33], v[28:31], off
	global_load_dwordx2 v[28:29], v[34:35], off offset:32
	v_mul_f32_e64 v24, v24, -v38
	v_lshl_add_u64 v[30:31], v[36:37], 0, v[140:141]
	v_lshl_add_u64 v[30:31], v[30:31], 1, s[12:13]
	global_load_dwordx2 v[30:31], v[30:31], off
	v_mul_f32_e64 v25, v25, -v38
	v_mul_f32_e32 v24, 0x3fb8aa3b, v24
	v_mul_f32_e32 v25, 0x3fb8aa3b, v25
	v_mul_f32_e64 v26, v26, -v38
	v_mul_f32_e64 v27, v27, -v38
	v_exp_f32_e32 v24, v24
	v_exp_f32_e32 v25, v25
	v_mul_f32_e32 v26, 0x3fb8aa3b, v26
	v_mul_f32_e32 v27, 0x3fb8aa3b, v27
	v_exp_f32_e32 v26, v26
	v_exp_f32_e32 v27, v27
	v_pk_add_f32 v[24:25], v[24:25], 1.0 op_sel_hi:[1,0]
	v_mul_f32_e64 v20, v20, -v38
	v_pk_add_f32 v[26:27], v[26:27], 1.0 op_sel_hi:[1,0]
	v_rcp_f32_e32 v25, v25
	v_rcp_f32_e32 v24, v24
	v_rcp_f32_e32 v27, v27
	v_rcp_f32_e32 v26, v26
	v_mul_f32_e64 v21, v21, -v38
	v_mul_f32_e32 v20, 0x3fb8aa3b, v20
	v_mul_f32_e32 v21, 0x3fb8aa3b, v21
	v_mul_f32_e64 v22, v22, -v38
	v_mul_f32_e64 v23, v23, -v38
	v_exp_f32_e32 v20, v20
	s_waitcnt vmcnt(1)
	v_lshlrev_b32_e32 v40, 16, v28
	v_and_b32_e32 v41, 0xffff0000, v28
	v_lshlrev_b32_e32 v28, 16, v29
	v_and_b32_e32 v29, 0xffff0000, v29
	s_waitcnt vmcnt(0)
	v_lshlrev_b32_e32 v42, 16, v30
	v_and_b32_e32 v43, 0xffff0000, v30
	v_lshlrev_b32_e32 v30, 16, v31
	v_and_b32_e32 v31, 0xffff0000, v31
	v_pk_fma_f32 v[26:27], v[26:27], v[28:29], v[30:31]
	v_pk_fma_f32 v[24:25], v[24:25], v[40:41], v[42:43]
	global_store_dwordx4 v[32:33], v[24:27], off offset:64
	global_load_dwordx2 v[24:25], v[34:35], off offset:256
	v_exp_f32_e32 v21, v21
	v_lshl_add_u64 v[26:27], v[36:37], 0, v[120:121]
	v_lshl_add_u64 v[26:27], v[26:27], 1, s[12:13]
	global_load_dwordx2 v[26:27], v[26:27], off
	v_mul_f32_e32 v22, 0x3fb8aa3b, v22
	v_mul_f32_e32 v23, 0x3fb8aa3b, v23
	v_exp_f32_e32 v22, v22
	v_exp_f32_e32 v23, v23
	v_pk_add_f32 v[20:21], v[20:21], 1.0 op_sel_hi:[1,0]
	v_mul_f32_e64 v16, v16, -v38
	v_pk_add_f32 v[22:23], v[22:23], 1.0 op_sel_hi:[1,0]
	v_rcp_f32_e32 v21, v21
	v_rcp_f32_e32 v20, v20
	v_rcp_f32_e32 v23, v23
	v_rcp_f32_e32 v22, v22
	v_mul_f32_e64 v17, v17, -v38
	v_mul_f32_e32 v16, 0x3fb8aa3b, v16
	v_mul_f32_e32 v17, 0x3fb8aa3b, v17
	v_mul_f32_e64 v18, v18, -v38
	v_mul_f32_e64 v19, v19, -v38
	v_exp_f32_e32 v16, v16
	v_exp_f32_e32 v17, v17
	v_mul_f32_e32 v18, 0x3fb8aa3b, v18
	v_mul_f32_e32 v19, 0x3fb8aa3b, v19
	v_add_u32_e32 v28, 0xb0, v144
	v_pk_add_f32 v[16:17], v[16:17], 1.0 op_sel_hi:[1,0]
	v_ashrrev_i32_e32 v29, 31, v28
	s_waitcnt vmcnt(1)
	v_lshlrev_b32_e32 v30, 16, v24
	v_and_b32_e32 v31, 0xffff0000, v24
	v_lshlrev_b32_e32 v24, 16, v25
	v_and_b32_e32 v25, 0xffff0000, v25
	s_waitcnt vmcnt(0)
	v_lshlrev_b32_e32 v40, 16, v26
	v_and_b32_e32 v41, 0xffff0000, v26
	v_lshlrev_b32_e32 v26, 16, v27
	v_and_b32_e32 v27, 0xffff0000, v27
	v_pk_fma_f32 v[22:23], v[22:23], v[24:25], v[26:27]
	v_pk_fma_f32 v[20:21], v[20:21], v[30:31], v[40:41]
	global_store_dwordx4 v[32:33], v[20:23], off offset:512
	global_load_dwordx2 v[22:23], v[34:35], off offset:288
	v_exp_f32_e32 v30, v18
	v_lshl_add_u64 v[20:21], v[36:37], 0, v[116:117]
	v_lshl_add_u64 v[20:21], v[20:21], 1, s[12:13]
	global_load_dwordx2 v[24:25], v[20:21], off
	v_exp_f32_e32 v31, v19
	s_nop 0
	v_pk_add_f32 v[30:31], v[30:31], 1.0 op_sel_hi:[1,0]
	v_rcp_f32_e32 v17, v17
	v_rcp_f32_e32 v16, v16
	v_rcp_f32_e32 v31, v31
	v_rcp_f32_e32 v30, v30
	v_lshlrev_b64 v[20:21], 10, v[28:29]
	v_lshl_add_u64 v[26:27], v[28:29], 2, s[18:19]
	v_lshl_add_u64 v[28:29], v[20:21], 0, v[142:143]
	v_lshlrev_b64 v[34:35], 1, v[28:29]
	v_lshl_add_u64 v[18:19], s[10:11], 0, v[34:35]
	s_waitcnt vmcnt(1)
	v_lshlrev_b32_e32 v36, 16, v22
	v_and_b32_e32 v37, 0xffff0000, v22
	v_lshlrev_b32_e32 v22, 16, v23
	v_and_b32_e32 v23, 0xffff0000, v23
	s_waitcnt vmcnt(0)
; #define PG8_BAR __builtin_amdgcn_s_barrier()
; template <class Epi, class Sched, bool ALIGN_EPI = false, bool SP2 = false>
; __device__ __forceinline__ void gemm_phase(PG8_LAS unsigned char* lds, const Gemm g, const Sched& S, const Epi& E) {
;     ...
;         if constexpr (ALIGN_EPI) { if (wr == 0) PG8_BAR; }
;         if constexpr (!Epi::AFTER_DRAIN) { E(acc, cur, wr, wc, fr, fq); S.done(cur); }
;         if (!has_next) break;
; #pragma unroll
;         for (int a = 0; a < 2; ++a)
; #pragma unroll
;             for (int b = 0; b < 2; ++b)
; #pragma unroll
;                 for (int m = 0; m < 4; ++m)
; #pragma unroll
;                     for (int n = 0; n < 2; ++n) acc[a][b][m][n] = (f32x4){0.f, 0.f, 0.f, 0.f};
;         cur = nxt; cA = nA; cB = nB; ++ui;
;         if constexpr (ALIGN_EPI) { if (wr == 1) PG8_BAR; }
;     }
;   DI void operator()(const f32x4 (&acc)[2][2][4][2], const pg8::Unit& u, int wr, int wc, int fr, int fq) const {
;     ...
;         const int row = u.pm * 256 + ai * 128 + wr * 64 + m * 16 + fr; float rs = 0.f;
;         const float rstd = rsqrtf(ssx[row] * (1.f / DM) + EPS);
; #pragma unroll
;         for (int bj = 0; bj < 2; ++bj)
; #pragma unroll
;           for (int n = 0; n < 2; ++n) {
;             const int col = u.pn * 256 + bj * 128 + wc * 32 + n * 16 + fq * 4; const size_t off = (size_t)row * DM + col;
;             f32x4 g;
; #pragma unroll
;             for (int j = 0; j < 4; ++j) g[j] = 1.f / (1.f + __expf(-rstd * acc[ai][bj][m][n][j]));
;             const u32x2 pw = *(const u32x2*)(PT + off); f32x4 pp; pp.x = __uint_as_float(pw.x << 16); pp.y = __uint_as_float(pw.x & 0xffff0000u); pp.z = __uint_as_float(pw.y << 16); pp.w = __uint_as_float(pw.y & 0xffff0000u);
;             const u32x2 xw = *(const u32x2*)(X1B + off); f32x4 x1; x1.x = __uint_as_float(xw.x << 16); x1.y = __uint_as_float(xw.x & 0xffff0000u); x1.z = __uint_as_float(xw.y << 16); x1.w = __uint_as_float(xw.y & 0xffff0000u);
;             const f32x4 xn = x1 + pp * g;
;             if (layer != 0) *(f32x4*)(out + off) = xn;
	v_lshlrev_b32_e32 v38, 16, v24
	v_and_b32_e32 v39, 0xffff0000, v24
	v_lshlrev_b32_e32 v24, 16, v25
	v_and_b32_e32 v25, 0xffff0000, v25
	v_pk_fma_f32 v[24:25], v[30:31], v[22:23], v[24:25]
	v_pk_fma_f32 v[22:23], v[16:17], v[36:37], v[38:39]
	global_store_dwordx4 v[32:33], v[22:25], off offset:576
	global_load_dword v30, v[26:27], off
	global_load_dwordx2 v[22:23], v[18:19], off
	v_lshl_add_u64 v[16:17], s[12:13], 0, v[34:35]
	global_load_dwordx2 v[24:25], v[16:17], off
	v_lshl_add_u64 v[16:17], v[28:29], 2, s[14:15]
	s_waitcnt vmcnt(2)
	v_fmamk_f32 v28, v30, 0x3a800000, v158
	v_mul_f32_e32 v29, 0x4b800000, v28
	v_cmp_gt_f32_e32 vcc, s44, v28
	s_waitcnt vmcnt(1)
	v_lshlrev_b32_e32 v26, 16, v22
	v_and_b32_e32 v27, 0xffff0000, v22
	v_cndmask_b32_e32 v28, v28, v29, vcc
	v_rsq_f32_e32 v30, v28
	s_waitcnt vmcnt(0)
	v_lshlrev_b32_e32 v28, 16, v24
	v_and_b32_e32 v29, 0xffff0000, v24
	v_lshlrev_b32_e32 v22, 16, v23
	v_mul_f32_e32 v24, 0x45800000, v30
	v_cndmask_b32_e32 v30, v30, v24, vcc
	v_mul_f32_e64 v12, v12, -v30
	v_mul_f32_e64 v13, v13, -v30
	v_mul_f32_e32 v12, 0x3fb8aa3b, v12
	v_mul_f32_e32 v13, 0x3fb8aa3b, v13
	v_mul_f32_e64 v14, v14, -v30
	v_mul_f32_e64 v15, v15, -v30
	v_exp_f32_e32 v12, v12
	v_exp_f32_e32 v13, v13
	v_mul_f32_e32 v14, 0x3fb8aa3b, v14
	v_mul_f32_e32 v15, 0x3fb8aa3b, v15
	v_exp_f32_e32 v14, v14
	v_exp_f32_e32 v15, v15
	v_pk_add_f32 v[12:13], v[12:13], 1.0 op_sel_hi:[1,0]
	v_and_b32_e32 v23, 0xffff0000, v23
	v_pk_add_f32 v[14:15], v[14:15], 1.0 op_sel_hi:[1,0]
	v_rcp_f32_e32 v13, v13
	v_rcp_f32_e32 v12, v12
	v_rcp_f32_e32 v15, v15
	v_lshlrev_b32_e32 v24, 16, v25
	v_and_b32_e32 v25, 0xffff0000, v25
	v_rcp_f32_e32 v14, v14
	v_pk_fma_f32 v[12:13], v[12:13], v[26:27], v[28:29]
	v_pk_fma_f32 v[14:15], v[14:15], v[22:23], v[24:25]
	global_store_dwordx4 v[16:17], v[12:15], off
	global_load_dwordx2 v[12:13], v[18:19], off offset:32
	v_mul_f32_e64 v8, v8, -v30
	v_lshl_add_u64 v[14:15], v[20:21], 0, v[140:141]
	v_lshl_add_u64 v[14:15], v[14:15], 1, s[12:13]
	global_load_dwordx2 v[14:15], v[14:15], off
	v_mul_f32_e64 v9, v9, -v30
	v_mul_f32_e32 v8, 0x3fb8aa3b, v8
	v_mul_f32_e32 v9, 0x3fb8aa3b, v9
	v_mul_f32_e64 v10, v10, -v30
	v_mul_f32_e64 v11, v11, -v30
	v_exp_f32_e32 v8, v8
	v_exp_f32_e32 v9, v9
	v_mul_f32_e32 v10, 0x3fb8aa3b, v10
	v_mul_f32_e32 v11, 0x3fb8aa3b, v11
	v_exp_f32_e32 v10, v10
	v_exp_f32_e32 v11, v11
	v_pk_add_f32 v[8:9], v[8:9], 1.0 op_sel_hi:[1,0]
	v_mul_f32_e64 v4, v4, -v30
	v_pk_add_f32 v[10:11], v[10:11], 1.0 op_sel_hi:[1,0]
	v_rcp_f32_e32 v9, v9
	v_rcp_f32_e32 v8, v8
	v_rcp_f32_e32 v11, v11
	v_rcp_f32_e32 v10, v10
	v_mul_f32_e64 v5, v5, -v30
	v_mul_f32_e32 v4, 0x3fb8aa3b, v4
	v_mul_f32_e32 v5, 0x3fb8aa3b, v5
	v_mul_f32_e64 v6, v6, -v30
	v_mul_f32_e64 v7, v7, -v30
	v_exp_f32_e32 v4, v4
	s_waitcnt vmcnt(1)
	v_lshlrev_b32_e32 v22, 16, v12
	v_and_b32_e32 v23, 0xffff0000, v12
	v_lshlrev_b32_e32 v12, 16, v13
	v_and_b32_e32 v13, 0xffff0000, v13
	s_waitcnt vmcnt(0)
	v_lshlrev_b32_e32 v24, 16, v14
	v_and_b32_e32 v25, 0xffff0000, v14
	v_lshlrev_b32_e32 v14, 16, v15
	v_and_b32_e32 v15, 0xffff0000, v15
	v_pk_fma_f32 v[10:11], v[10:11], v[12:13], v[14:15]
	v_pk_fma_f32 v[8:9], v[8:9], v[22:23], v[24:25]
	global_store_dwordx4 v[16:17], v[8:11], off offset:64
	global_load_dwordx2 v[8:9], v[18:19], off offset:256
	v_exp_f32_e32 v5, v5
	v_lshl_add_u64 v[10:11], v[20:21], 0, v[120:121]
	v_lshl_add_u64 v[10:11], v[10:11], 1, s[12:13]
	global_load_dwordx2 v[10:11], v[10:11], off
	v_mul_f32_e32 v6, 0x3fb8aa3b, v6
	v_mul_f32_e32 v7, 0x3fb8aa3b, v7
	v_exp_f32_e32 v6, v6
	v_exp_f32_e32 v7, v7
	v_pk_add_f32 v[4:5], v[4:5], 1.0 op_sel_hi:[1,0]
	v_mul_f32_e64 v0, v0, -v30
	v_pk_add_f32 v[6:7], v[6:7], 1.0 op_sel_hi:[1,0]
	v_rcp_f32_e32 v5, v5
	v_rcp_f32_e32 v4, v4
	v_rcp_f32_e32 v7, v7
	v_rcp_f32_e32 v6, v6
	v_mul_f32_e64 v1, v1, -v30
	v_mul_f32_e32 v0, 0x3fb8aa3b, v0
	v_mul_f32_e32 v1, 0x3fb8aa3b, v1
	v_mul_f32_e64 v2, v2, -v30
	v_mul_f32_e64 v3, v3, -v30
	v_exp_f32_e32 v0, v0
	v_exp_f32_e32 v1, v1
	v_mul_f32_e32 v2, 0x3fb8aa3b, v2
	v_mul_f32_e32 v3, 0x3fb8aa3b, v3
	v_exp_f32_e32 v2, v2
	v_exp_f32_e32 v3, v3
	v_pk_add_f32 v[0:1], v[0:1], 1.0 op_sel_hi:[1,0]
	s_waitcnt vmcnt(1)
	v_lshlrev_b32_e32 v12, 16, v8
	v_and_b32_e32 v13, 0xffff0000, v8
	v_lshlrev_b32_e32 v8, 16, v9
	v_and_b32_e32 v9, 0xffff0000, v9
	s_waitcnt vmcnt(0)
	v_lshlrev_b32_e32 v14, 16, v10
	v_and_b32_e32 v15, 0xffff0000, v10
	v_lshlrev_b32_e32 v10, 16, v11
	v_and_b32_e32 v11, 0xffff0000, v11
	v_pk_fma_f32 v[6:7], v[6:7], v[8:9], v[10:11]
	v_pk_fma_f32 v[4:5], v[4:5], v[12:13], v[14:15]
	global_store_dwordx4 v[16:17], v[4:7], off offset:512
	global_load_dwordx2 v[4:5], v[18:19], off offset:288
	v_lshl_add_u64 v[6:7], v[20:21], 0, v[116:117]
	v_lshl_add_u64 v[6:7], v[6:7], 1, s[12:13]
	global_load_dwordx2 v[6:7], v[6:7], off
	v_pk_add_f32 v[2:3], v[2:3], 1.0 op_sel_hi:[1,0]
	v_rcp_f32_e32 v1, v1
	v_rcp_f32_e32 v0, v0
	v_rcp_f32_e32 v3, v3
	v_rcp_f32_e32 v2, v2
	s_andn2_b64 vcc, exec, s[0:1]
	s_mov_b64 s[0:1], -1
	s_waitcnt vmcnt(1)
	v_lshlrev_b32_e32 v8, 16, v4
	v_and_b32_e32 v9, 0xffff0000, v4
	v_lshlrev_b32_e32 v4, 16, v5
	v_and_b32_e32 v5, 0xffff0000, v5
	s_waitcnt vmcnt(0)
	v_lshlrev_b32_e32 v10, 16, v6
	v_and_b32_e32 v11, 0xffff0000, v6
	v_lshlrev_b32_e32 v6, 16, v7
	v_and_b32_e32 v7, 0xffff0000, v7
	v_pk_fma_f32 v[2:3], v[2:3], v[4:5], v[6:7]
	v_pk_fma_f32 v[0:1], v[0:1], v[8:9], v[10:11]
	global_store_dwordx4 v[16:17], v[0:3], off offset:576
	s_cbranch_vccnz .LBB0_2815
	s_andn2_b64 vcc, exec, s[16:17]
	s_cbranch_vccnz .LBB0_2814
	s_barrier
	s_branch .LBB0_2814
